# GEMM K-loop: closing barrier of each MFMA block issued four MFMAs early (tail at s_setprio 2); diff-attention long block first
# speedup vs baseline: 1.0107x; 1.0020x over previous
.LBB0_359:
	ds_read_b128 v[130:133], v185
	ds_read_b128 v[134:137], v185 offset:1024
	ds_read_b128 v[138:141], v185 offset:2048
	ds_read_b128 v[142:145], v185 offset:3072
	ds_read_b128 v[146:149], v187
	ds_read_b128 v[150:153], v187 offset:1024
	ds_read_b128 v[154:157], v187 offset:2048
	ds_read_b128 v[192:195], v187 offset:3072
	s_add_u32 s30, s28, 0xfff80080
	s_addc_u32 s31, s29, -1
	s_cmp_eq_u32 s76, 28
	s_cselect_b32 s35, s6, s31
	s_cselect_b32 s34, s21, s30
	s_cselect_b32 s31, s19, s75
	s_cselect_b32 s30, s73, s74
	v_lshl_add_u64 v[158:159], s[28:29], 0, v[174:175]
	s_add_i32 m0, s27, 0xc000
	ds_read_b128 v[196:199], v189
	ds_read_b128 v[200:203], v189 offset:1024
	ds_read_b128 v[204:207], v189 offset:2048
	ds_read_b128 v[208:211], v189 offset:3072
	ds_read_b128 v[212:215], v189 offset:4096
	ds_read_b128 v[216:219], v189 offset:5120
	ds_read_b128 v[220:223], v189 offset:6144
	ds_read_b128 v[224:227], v189 offset:7168
	global_load_lds_dwordx4 v[158:159], off
	v_lshl_add_u64 v[158:159], s[28:29], 0, v[172:173]
	s_add_i32 m0, s27, 0xe000
	s_nop 0
	global_load_lds_dwordx4 v[158:159], off
	s_waitcnt vmcnt(8)
	s_waitcnt lgkmcnt(0)
	s_barrier
	s_setprio 1
	s_waitcnt lgkmcnt(0)
	v_mfma_f32_16x16x32_bf16 v[124:127], v[130:133], v[196:199], v[124:127]
	v_mfma_f32_16x16x32_bf16 v[120:123], v[138:141], v[196:199], v[120:123]
	v_mfma_f32_16x16x32_bf16 v[112:115], v[130:133], v[204:207], v[112:115]
	v_mfma_f32_16x16x32_bf16 v[104:107], v[138:141], v[204:207], v[104:107]
	v_mfma_f32_16x16x32_bf16 v[96:99], v[130:133], v[212:215], v[96:99]
	v_mfma_f32_16x16x32_bf16 v[88:91], v[138:141], v[212:215], v[88:91]
	v_mfma_f32_16x16x32_bf16 v[80:83], v[130:133], v[220:223], v[80:83]
	v_mfma_f32_16x16x32_bf16 v[72:75], v[138:141], v[220:223], v[72:75]
	v_mfma_f32_16x16x32_bf16 v[124:127], v[134:137], v[200:203], v[124:127]
	v_mfma_f32_16x16x32_bf16 v[120:123], v[142:145], v[200:203], v[120:123]
	v_mfma_f32_16x16x32_bf16 v[112:115], v[134:137], v[208:211], v[112:115]
	v_mfma_f32_16x16x32_bf16 v[104:107], v[142:145], v[208:211], v[104:107]
	v_mfma_f32_16x16x32_bf16 v[96:99], v[134:137], v[216:219], v[96:99]
	v_mfma_f32_16x16x32_bf16 v[88:91], v[142:145], v[216:219], v[88:91]
	v_mfma_f32_16x16x32_bf16 v[80:83], v[134:137], v[224:227], v[80:83]
	v_mfma_f32_16x16x32_bf16 v[72:75], v[142:145], v[224:227], v[72:75]
	s_setprio 0
	s_setprio 1
	v_mfma_f32_16x16x32_bf16 v[116:119], v[146:149], v[196:199], v[116:119]
	v_mfma_f32_16x16x32_bf16 v[108:111], v[154:157], v[196:199], v[108:111]
	v_mfma_f32_16x16x32_bf16 v[100:103], v[146:149], v[204:207], v[100:103]
	v_mfma_f32_16x16x32_bf16 v[92:95], v[154:157], v[204:207], v[92:95]
	v_mfma_f32_16x16x32_bf16 v[84:87], v[146:149], v[212:215], v[84:87]
	v_mfma_f32_16x16x32_bf16 v[76:79], v[154:157], v[212:215], v[76:79]
	v_mfma_f32_16x16x32_bf16 v[68:71], v[146:149], v[220:223], v[68:71]
	v_mfma_f32_16x16x32_bf16 v[64:67], v[154:157], v[220:223], v[64:67]
	v_mfma_f32_16x16x32_bf16 v[116:119], v[150:153], v[200:203], v[116:119]
	v_mfma_f32_16x16x32_bf16 v[108:111], v[192:195], v[200:203], v[108:111]
	v_mfma_f32_16x16x32_bf16 v[100:103], v[150:153], v[208:211], v[100:103]
	v_mfma_f32_16x16x32_bf16 v[92:95], v[192:195], v[208:211], v[92:95]
	s_barrier
	s_setprio 2
	v_mfma_f32_16x16x32_bf16 v[84:87], v[150:153], v[216:219], v[84:87]
	v_mfma_f32_16x16x32_bf16 v[76:79], v[192:195], v[216:219], v[76:79]
	v_mfma_f32_16x16x32_bf16 v[68:71], v[150:153], v[224:227], v[68:71]
	v_mfma_f32_16x16x32_bf16 v[64:67], v[192:195], v[224:227], v[64:67]
	s_setprio 0
	s_add_i32 s77, s57, s67
	v_lshl_add_u64 v[158:159], s[30:31], 0, v[162:163]
	s_mov_b32 m0, s77
	ds_read_b128 v[196:199], v189 offset:16384
	ds_read_b128 v[200:203], v189 offset:17408
	ds_read_b128 v[204:207], v189 offset:18432
	ds_read_b128 v[208:211], v189 offset:19456
	ds_read_b128 v[212:215], v189 offset:20480
	ds_read_b128 v[216:219], v189 offset:21504
	ds_read_b128 v[220:223], v189 offset:22528
	ds_read_b128 v[224:227], v189 offset:23552
	global_load_lds_dwordx4 v[158:159], off
	s_add_i32 m0, s77, 0x2000
	s_add_u32 s78, s30, 0x80000
	v_lshl_add_u64 v[228:229], s[30:31], 0, v[166:167]
	s_addc_u32 s79, s31, 0
	s_add_i32 s77, s58, s67
	global_load_lds_dwordx4 v[228:229], off
	v_lshl_add_u64 v[230:231], s[78:79], 0, v[162:163]
	s_mov_b32 m0, s77
	v_lshl_add_u64 v[232:233], s[34:35], 0, v[164:165]
	global_load_lds_dwordx4 v[230:231], off
	v_lshl_add_u64 v[230:231], s[78:79], 0, v[166:167]
	s_add_i32 m0, s77, 0x2000
	s_nop 0
	global_load_lds_dwordx4 v[230:231], off
	v_lshl_add_u64 v[230:231], s[34:35], 0, v[160:161]
	s_mov_b32 m0, s27
	s_nop 0
	global_load_lds_dwordx4 v[230:231], off
	s_mov_b32 m0, s41
	s_nop 0
	global_load_lds_dwordx4 v[232:233], off
	s_waitcnt vmcnt(8)
	s_waitcnt lgkmcnt(0)
	s_barrier
	s_setprio 1
	s_waitcnt lgkmcnt(0)
	v_mfma_f32_16x16x32_bf16 v[60:63], v[130:133], v[196:199], v[60:63]
	v_mfma_f32_16x16x32_bf16 v[56:59], v[138:141], v[196:199], v[56:59]
	v_mfma_f32_16x16x32_bf16 v[48:51], v[130:133], v[204:207], v[48:51]
	v_mfma_f32_16x16x32_bf16 v[40:43], v[138:141], v[204:207], v[40:43]
	v_mfma_f32_16x16x32_bf16 v[32:35], v[130:133], v[212:215], v[32:35]
	v_mfma_f32_16x16x32_bf16 v[24:27], v[138:141], v[212:215], v[24:27]
	v_mfma_f32_16x16x32_bf16 v[16:19], v[130:133], v[220:223], v[16:19]
	v_mfma_f32_16x16x32_bf16 v[8:11], v[138:141], v[220:223], v[8:11]
	v_mfma_f32_16x16x32_bf16 v[60:63], v[134:137], v[200:203], v[60:63]
	v_mfma_f32_16x16x32_bf16 v[56:59], v[142:145], v[200:203], v[56:59]
	v_mfma_f32_16x16x32_bf16 v[48:51], v[134:137], v[208:211], v[48:51]
	v_mfma_f32_16x16x32_bf16 v[40:43], v[142:145], v[208:211], v[40:43]
	v_mfma_f32_16x16x32_bf16 v[32:35], v[134:137], v[216:219], v[32:35]
	v_mfma_f32_16x16x32_bf16 v[24:27], v[142:145], v[216:219], v[24:27]
	v_mfma_f32_16x16x32_bf16 v[16:19], v[134:137], v[224:227], v[16:19]
	v_mfma_f32_16x16x32_bf16 v[8:11], v[142:145], v[224:227], v[8:11]
	s_setprio 0
	s_setprio 1
	v_mfma_f32_16x16x32_bf16 v[52:55], v[146:149], v[196:199], v[52:55]
	v_mfma_f32_16x16x32_bf16 v[44:47], v[154:157], v[196:199], v[44:47]
	v_mfma_f32_16x16x32_bf16 v[36:39], v[146:149], v[204:207], v[36:39]
	v_mfma_f32_16x16x32_bf16 v[28:31], v[154:157], v[204:207], v[28:31]
	v_mfma_f32_16x16x32_bf16 v[20:23], v[146:149], v[212:215], v[20:23]
	v_mfma_f32_16x16x32_bf16 v[12:15], v[154:157], v[212:215], v[12:15]
	v_mfma_f32_16x16x32_bf16 v[4:7], v[146:149], v[220:223], v[4:7]
	v_mfma_f32_16x16x32_bf16 v[0:3], v[154:157], v[220:223], v[0:3]
	v_mfma_f32_16x16x32_bf16 v[52:55], v[150:153], v[200:203], v[52:55]
	v_mfma_f32_16x16x32_bf16 v[44:47], v[192:195], v[200:203], v[44:47]
	v_mfma_f32_16x16x32_bf16 v[36:39], v[150:153], v[208:211], v[36:39]
	v_mfma_f32_16x16x32_bf16 v[28:31], v[192:195], v[208:211], v[28:31]
	s_barrier
	s_setprio 2
	v_mfma_f32_16x16x32_bf16 v[20:23], v[150:153], v[216:219], v[20:23]
	v_mfma_f32_16x16x32_bf16 v[12:15], v[192:195], v[216:219], v[12:15]
	v_mfma_f32_16x16x32_bf16 v[4:7], v[150:153], v[224:227], v[4:7]
	v_mfma_f32_16x16x32_bf16 v[0:3], v[192:195], v[224:227], v[0:3]
	s_setprio 0
	s_add_i32 s77, 0, 0x18000
	v_add_u32_e32 v129, s77, v181
	s_add_i32 s78, 0, 0x1c000
	ds_read_b128 v[130:133], v129
	ds_read_b128 v[134:137], v129 offset:1024
	ds_read_b128 v[138:141], v129 offset:2048
	ds_read_b128 v[142:145], v129 offset:3072
	v_add_u32_e32 v129, s78, v181
	ds_read_b128 v[146:149], v129
	ds_read_b128 v[150:153], v129 offset:1024
	ds_read_b128 v[154:157], v129 offset:2048
	ds_read_b128 v[192:195], v129 offset:3072
	s_add_u32 s34, s34, 0x80000
	s_addc_u32 s35, s35, 0
	s_mov_b32 m0, s42
	v_lshl_add_u64 v[234:235], s[34:35], 0, v[160:161]
	ds_read_b128 v[196:199], v189 offset:32768
	ds_read_b128 v[200:203], v189 offset:33792
	ds_read_b128 v[204:207], v189 offset:34816
	ds_read_b128 v[208:211], v189 offset:35840
	ds_read_b128 v[212:215], v189 offset:36864
	ds_read_b128 v[216:219], v189 offset:37888
	ds_read_b128 v[220:223], v189 offset:38912
	ds_read_b128 v[224:227], v189 offset:39936
	global_load_lds_dwordx4 v[234:235], off
	v_lshl_add_u64 v[234:235], s[34:35], 0, v[164:165]
	s_mov_b32 m0, s43
	s_nop 0
	global_load_lds_dwordx4 v[234:235], off
	s_waitcnt vmcnt(8)
	s_waitcnt lgkmcnt(0)
	s_barrier
	s_setprio 1
	s_waitcnt lgkmcnt(0)
	v_mfma_f32_16x16x32_bf16 v[124:127], v[130:133], v[196:199], v[124:127]
	v_mfma_f32_16x16x32_bf16 v[120:123], v[138:141], v[196:199], v[120:123]
	v_mfma_f32_16x16x32_bf16 v[112:115], v[130:133], v[204:207], v[112:115]
	v_mfma_f32_16x16x32_bf16 v[104:107], v[138:141], v[204:207], v[104:107]
	v_mfma_f32_16x16x32_bf16 v[96:99], v[130:133], v[212:215], v[96:99]
	v_mfma_f32_16x16x32_bf16 v[88:91], v[138:141], v[212:215], v[88:91]
	v_mfma_f32_16x16x32_bf16 v[80:83], v[130:133], v[220:223], v[80:83]
	v_mfma_f32_16x16x32_bf16 v[72:75], v[138:141], v[220:223], v[72:75]
	v_mfma_f32_16x16x32_bf16 v[124:127], v[134:137], v[200:203], v[124:127]
	v_mfma_f32_16x16x32_bf16 v[120:123], v[142:145], v[200:203], v[120:123]
	v_mfma_f32_16x16x32_bf16 v[112:115], v[134:137], v[208:211], v[112:115]
	v_mfma_f32_16x16x32_bf16 v[104:107], v[142:145], v[208:211], v[104:107]
	v_mfma_f32_16x16x32_bf16 v[96:99], v[134:137], v[216:219], v[96:99]
	v_mfma_f32_16x16x32_bf16 v[88:91], v[142:145], v[216:219], v[88:91]
	v_mfma_f32_16x16x32_bf16 v[80:83], v[134:137], v[224:227], v[80:83]
	v_mfma_f32_16x16x32_bf16 v[72:75], v[142:145], v[224:227], v[72:75]
	s_setprio 0
	s_setprio 1
	v_mfma_f32_16x16x32_bf16 v[116:119], v[146:149], v[196:199], v[116:119]
	v_mfma_f32_16x16x32_bf16 v[108:111], v[154:157], v[196:199], v[108:111]
	v_mfma_f32_16x16x32_bf16 v[100:103], v[146:149], v[204:207], v[100:103]
	v_mfma_f32_16x16x32_bf16 v[92:95], v[154:157], v[204:207], v[92:95]
	v_mfma_f32_16x16x32_bf16 v[84:87], v[146:149], v[212:215], v[84:87]
	v_mfma_f32_16x16x32_bf16 v[76:79], v[154:157], v[212:215], v[76:79]
	v_mfma_f32_16x16x32_bf16 v[68:71], v[146:149], v[220:223], v[68:71]
	v_mfma_f32_16x16x32_bf16 v[64:67], v[154:157], v[220:223], v[64:67]
	v_mfma_f32_16x16x32_bf16 v[116:119], v[150:153], v[200:203], v[116:119]
	v_mfma_f32_16x16x32_bf16 v[108:111], v[192:195], v[200:203], v[108:111]
	v_mfma_f32_16x16x32_bf16 v[100:103], v[150:153], v[208:211], v[100:103]
	v_mfma_f32_16x16x32_bf16 v[92:95], v[192:195], v[208:211], v[92:95]
	s_barrier
	s_setprio 2
	v_mfma_f32_16x16x32_bf16 v[84:87], v[150:153], v[216:219], v[84:87]
	v_mfma_f32_16x16x32_bf16 v[76:79], v[192:195], v[216:219], v[76:79]
	v_mfma_f32_16x16x32_bf16 v[68:71], v[150:153], v[224:227], v[68:71]
	v_mfma_f32_16x16x32_bf16 v[64:67], v[192:195], v[224:227], v[64:67]
	s_setprio 0
	s_add_i32 s34, s77, s67
	v_lshl_add_u64 v[158:159], v[158:159], 0, s[12:13]
	s_mov_b32 m0, s34
	ds_read_b128 v[196:199], v189 offset:49152
	ds_read_b128 v[200:203], v189 offset:50176
	ds_read_b128 v[204:207], v189 offset:51200
	ds_read_b128 v[208:211], v189 offset:52224
	ds_read_b128 v[212:215], v189 offset:53248
	ds_read_b128 v[216:219], v189 offset:54272
	ds_read_b128 v[220:223], v189 offset:55296
	ds_read_b128 v[224:227], v189 offset:56320
	global_load_lds_dwordx4 v[158:159], off
	s_add_i32 m0, s34, 0x2000
	s_add_u32 s30, s30, 0x80080
	v_lshl_add_u64 v[158:159], v[228:229], 0, s[12:13]
	s_addc_u32 s31, s31, 0
	s_add_i32 s34, s78, s67
	global_load_lds_dwordx4 v[158:159], off
	v_lshl_add_u64 v[158:159], s[30:31], 0, v[162:163]
	s_mov_b32 m0, s34
	s_nop 0
	global_load_lds_dwordx4 v[158:159], off
	v_lshl_add_u64 v[158:159], s[30:31], 0, v[166:167]
	s_add_i32 m0, s34, 0x2000
	s_nop 0
	global_load_lds_dwordx4 v[158:159], off
	v_lshl_add_u64 v[158:159], v[230:231], 0, s[12:13]
	s_mov_b32 m0, s45
	s_nop 0
	global_load_lds_dwordx4 v[158:159], off
	v_lshl_add_u64 v[158:159], v[232:233], 0, s[12:13]
	s_mov_b32 m0, s47
	s_nop 0
	global_load_lds_dwordx4 v[158:159], off
	s_waitcnt vmcnt(8)
	s_waitcnt lgkmcnt(0)
	s_barrier
	s_setprio 1
	s_waitcnt lgkmcnt(0)
	v_mfma_f32_16x16x32_bf16 v[60:63], v[130:133], v[196:199], v[60:63]
	v_mfma_f32_16x16x32_bf16 v[56:59], v[138:141], v[196:199], v[56:59]
	v_mfma_f32_16x16x32_bf16 v[48:51], v[130:133], v[204:207], v[48:51]
	v_mfma_f32_16x16x32_bf16 v[40:43], v[138:141], v[204:207], v[40:43]
	v_mfma_f32_16x16x32_bf16 v[32:35], v[130:133], v[212:215], v[32:35]
	v_mfma_f32_16x16x32_bf16 v[24:27], v[138:141], v[212:215], v[24:27]
	v_mfma_f32_16x16x32_bf16 v[16:19], v[130:133], v[220:223], v[16:19]
	v_mfma_f32_16x16x32_bf16 v[8:11], v[138:141], v[220:223], v[8:11]
	v_mfma_f32_16x16x32_bf16 v[60:63], v[134:137], v[200:203], v[60:63]
	v_mfma_f32_16x16x32_bf16 v[56:59], v[142:145], v[200:203], v[56:59]
	v_mfma_f32_16x16x32_bf16 v[48:51], v[134:137], v[208:211], v[48:51]
	v_mfma_f32_16x16x32_bf16 v[40:43], v[142:145], v[208:211], v[40:43]
	v_mfma_f32_16x16x32_bf16 v[32:35], v[134:137], v[216:219], v[32:35]
	v_mfma_f32_16x16x32_bf16 v[24:27], v[142:145], v[216:219], v[24:27]
	v_mfma_f32_16x16x32_bf16 v[16:19], v[134:137], v[224:227], v[16:19]
	v_mfma_f32_16x16x32_bf16 v[8:11], v[142:145], v[224:227], v[8:11]
	s_setprio 0
	s_setprio 1
	v_mfma_f32_16x16x32_bf16 v[52:55], v[146:149], v[196:199], v[52:55]
	v_mfma_f32_16x16x32_bf16 v[44:47], v[154:157], v[196:199], v[44:47]
	v_mfma_f32_16x16x32_bf16 v[36:39], v[146:149], v[204:207], v[36:39]
	v_mfma_f32_16x16x32_bf16 v[28:31], v[154:157], v[204:207], v[28:31]
	v_mfma_f32_16x16x32_bf16 v[20:23], v[146:149], v[212:215], v[20:23]
	v_mfma_f32_16x16x32_bf16 v[12:15], v[154:157], v[212:215], v[12:15]
	v_mfma_f32_16x16x32_bf16 v[4:7], v[146:149], v[220:223], v[4:7]
	v_mfma_f32_16x16x32_bf16 v[0:3], v[154:157], v[220:223], v[0:3]
	v_mfma_f32_16x16x32_bf16 v[52:55], v[150:153], v[200:203], v[52:55]
	v_mfma_f32_16x16x32_bf16 v[44:47], v[192:195], v[200:203], v[44:47]
	v_mfma_f32_16x16x32_bf16 v[36:39], v[150:153], v[208:211], v[36:39]
	v_mfma_f32_16x16x32_bf16 v[28:31], v[192:195], v[208:211], v[28:31]
	s_barrier
	s_setprio 2
	v_mfma_f32_16x16x32_bf16 v[20:23], v[150:153], v[216:219], v[20:23]
	v_mfma_f32_16x16x32_bf16 v[12:15], v[192:195], v[216:219], v[12:15]
	v_mfma_f32_16x16x32_bf16 v[4:7], v[150:153], v[224:227], v[4:7]
	v_mfma_f32_16x16x32_bf16 v[0:3], v[192:195], v[224:227], v[0:3]
	s_setprio 0
	s_add_i32 s76, s76, 2
	s_add_u32 s74, s74, 0x100
	s_addc_u32 s75, s75, 0
	s_add_u32 s28, s28, 0x100
	s_addc_u32 s29, s29, 0
	s_cmp_gt_u32 s76, 29
	s_cbranch_scc0 .LBB0_359
	s_and_b64 vcc, exec, s[14:15]
	s_cbranch_vccz .LBB0_362
	s_barrier

.LBB0_1192:
	ds_read_b128 v[128:131], v215
	ds_read_b128 v[132:135], v215 offset:1024
	ds_read_b128 v[136:139], v215 offset:2048
	ds_read_b128 v[158:161], v215 offset:3072
	ds_read_b128 v[162:165], v216
	ds_read_b128 v[166:169], v216 offset:1024
	ds_read_b128 v[170:173], v216 offset:2048
	ds_read_b128 v[174:177], v216 offset:3072
	s_add_u32 s24, s22, 0xfff80080
	s_addc_u32 s25, s23, -1
	s_cmp_eq_u32 s30, 28
	s_cselect_b32 s27, s3, s25
	s_cselect_b32 s26, s15, s24
	s_cselect_b32 s25, s13, s29
	s_cselect_b32 s24, s21, s28
	v_lshl_add_u64 v[210:211], s[22:23], 0, v[152:153]
	s_add_i32 m0, s38, 0xc000
	ds_read_b128 v[178:181], v217
	ds_read_b128 v[182:185], v217 offset:1024
	ds_read_b128 v[186:189], v217 offset:2048
	ds_read_b128 v[190:193], v217 offset:3072
	ds_read_b128 v[194:197], v217 offset:4096
	ds_read_b128 v[198:201], v217 offset:5120
	ds_read_b128 v[202:205], v217 offset:6144
	ds_read_b128 v[206:209], v217 offset:7168
	global_load_lds_dwordx4 v[210:211], off
	v_lshl_add_u64 v[210:211], s[22:23], 0, v[150:151]
	s_add_i32 m0, s38, 0xe000
	s_nop 0
	global_load_lds_dwordx4 v[210:211], off
	s_waitcnt vmcnt(8)
	s_waitcnt lgkmcnt(0)
	s_barrier
	s_setprio 1
	s_waitcnt lgkmcnt(0)
	v_mfma_f32_16x16x32_bf16 v[124:127], v[128:131], v[178:181], v[124:127]
	v_mfma_f32_16x16x32_bf16 v[120:123], v[136:139], v[178:181], v[120:123]
	v_mfma_f32_16x16x32_bf16 v[116:119], v[128:131], v[186:189], v[116:119]
	v_mfma_f32_16x16x32_bf16 v[112:115], v[136:139], v[186:189], v[112:115]
	v_mfma_f32_16x16x32_bf16 v[108:111], v[128:131], v[194:197], v[108:111]
	v_mfma_f32_16x16x32_bf16 v[104:107], v[136:139], v[194:197], v[104:107]
	v_mfma_f32_16x16x32_bf16 v[100:103], v[128:131], v[202:205], v[100:103]
	v_mfma_f32_16x16x32_bf16 v[96:99], v[136:139], v[202:205], v[96:99]
	v_mfma_f32_16x16x32_bf16 v[124:127], v[132:135], v[182:185], v[124:127]
	v_mfma_f32_16x16x32_bf16 v[120:123], v[158:161], v[182:185], v[120:123]
	v_mfma_f32_16x16x32_bf16 v[116:119], v[132:135], v[190:193], v[116:119]
	v_mfma_f32_16x16x32_bf16 v[112:115], v[158:161], v[190:193], v[112:115]
	v_mfma_f32_16x16x32_bf16 v[108:111], v[132:135], v[198:201], v[108:111]
	v_mfma_f32_16x16x32_bf16 v[104:107], v[158:161], v[198:201], v[104:107]
	v_mfma_f32_16x16x32_bf16 v[100:103], v[132:135], v[206:209], v[100:103]
	v_mfma_f32_16x16x32_bf16 v[96:99], v[158:161], v[206:209], v[96:99]
	s_setprio 0
	s_setprio 1
	v_mfma_f32_16x16x32_bf16 v[60:63], v[162:165], v[178:181], v[60:63]
	v_mfma_f32_16x16x32_bf16 v[56:59], v[170:173], v[178:181], v[56:59]
	v_mfma_f32_16x16x32_bf16 v[52:55], v[162:165], v[186:189], v[52:55]
	v_mfma_f32_16x16x32_bf16 v[48:51], v[170:173], v[186:189], v[48:51]
	v_mfma_f32_16x16x32_bf16 v[44:47], v[162:165], v[194:197], v[44:47]
	v_mfma_f32_16x16x32_bf16 v[40:43], v[170:173], v[194:197], v[40:43]
	v_mfma_f32_16x16x32_bf16 v[36:39], v[162:165], v[202:205], v[36:39]
	v_mfma_f32_16x16x32_bf16 v[32:35], v[170:173], v[202:205], v[32:35]
	v_mfma_f32_16x16x32_bf16 v[60:63], v[166:169], v[182:185], v[60:63]
	v_mfma_f32_16x16x32_bf16 v[56:59], v[174:177], v[182:185], v[56:59]
	v_mfma_f32_16x16x32_bf16 v[52:55], v[166:169], v[190:193], v[52:55]
	v_mfma_f32_16x16x32_bf16 v[48:51], v[174:177], v[190:193], v[48:51]
	s_barrier
	s_setprio 2
	v_mfma_f32_16x16x32_bf16 v[44:47], v[166:169], v[198:201], v[44:47]
	v_mfma_f32_16x16x32_bf16 v[40:43], v[174:177], v[198:201], v[40:43]
	v_mfma_f32_16x16x32_bf16 v[36:39], v[166:169], v[206:209], v[36:39]
	v_mfma_f32_16x16x32_bf16 v[32:35], v[174:177], v[206:209], v[32:35]
	s_setprio 0
	s_add_i32 s31, s60, s67
	v_lshl_add_u64 v[210:211], s[24:25], 0, v[142:143]
	s_mov_b32 m0, s31
	ds_read_b128 v[178:181], v217 offset:16384
	ds_read_b128 v[182:185], v217 offset:17408
	ds_read_b128 v[186:189], v217 offset:18432
	ds_read_b128 v[190:193], v217 offset:19456
	ds_read_b128 v[194:197], v217 offset:20480
	ds_read_b128 v[198:201], v217 offset:21504
	ds_read_b128 v[202:205], v217 offset:22528
	ds_read_b128 v[206:209], v217 offset:23552
	global_load_lds_dwordx4 v[210:211], off
	s_add_i32 m0, s31, 0x2000
	s_add_u32 s74, s24, 0x80000
	v_lshl_add_u64 v[212:213], s[24:25], 0, v[146:147]
	s_addc_u32 s75, s25, 0
	s_add_i32 s31, s61, s67
	global_load_lds_dwordx4 v[212:213], off
	v_lshl_add_u64 v[220:221], s[74:75], 0, v[142:143]
	s_mov_b32 m0, s31
	v_lshl_add_u64 v[222:223], s[26:27], 0, v[144:145]
	global_load_lds_dwordx4 v[220:221], off
	v_lshl_add_u64 v[220:221], s[74:75], 0, v[146:147]
	s_add_i32 m0, s31, 0x2000
	s_nop 0
	global_load_lds_dwordx4 v[220:221], off
	v_lshl_add_u64 v[220:221], s[26:27], 0, v[140:141]
	s_mov_b32 m0, s38
	s_nop 0
	global_load_lds_dwordx4 v[220:221], off
	s_mov_b32 m0, s39
	s_nop 0
	global_load_lds_dwordx4 v[222:223], off
	s_waitcnt vmcnt(8)
	s_waitcnt lgkmcnt(0)
	s_barrier
	s_setprio 1
	s_waitcnt lgkmcnt(0)
	v_mfma_f32_16x16x32_bf16 v[92:95], v[128:131], v[178:181], v[92:95]
	v_mfma_f32_16x16x32_bf16 v[88:91], v[136:139], v[178:181], v[88:91]
	v_mfma_f32_16x16x32_bf16 v[84:87], v[128:131], v[186:189], v[84:87]
	v_mfma_f32_16x16x32_bf16 v[80:83], v[136:139], v[186:189], v[80:83]
	v_mfma_f32_16x16x32_bf16 v[76:79], v[128:131], v[194:197], v[76:79]
	v_mfma_f32_16x16x32_bf16 v[72:75], v[136:139], v[194:197], v[72:75]
	v_mfma_f32_16x16x32_bf16 v[68:71], v[128:131], v[202:205], v[68:71]
	v_mfma_f32_16x16x32_bf16 v[64:67], v[136:139], v[202:205], v[64:67]
	v_mfma_f32_16x16x32_bf16 v[92:95], v[132:135], v[182:185], v[92:95]
	v_mfma_f32_16x16x32_bf16 v[88:91], v[158:161], v[182:185], v[88:91]
	v_mfma_f32_16x16x32_bf16 v[84:87], v[132:135], v[190:193], v[84:87]
	v_mfma_f32_16x16x32_bf16 v[80:83], v[158:161], v[190:193], v[80:83]
	v_mfma_f32_16x16x32_bf16 v[76:79], v[132:135], v[198:201], v[76:79]
	v_mfma_f32_16x16x32_bf16 v[72:75], v[158:161], v[198:201], v[72:75]
	v_mfma_f32_16x16x32_bf16 v[68:71], v[132:135], v[206:209], v[68:71]
	v_mfma_f32_16x16x32_bf16 v[64:67], v[158:161], v[206:209], v[64:67]
	s_setprio 0
	s_setprio 1
	v_mfma_f32_16x16x32_bf16 v[28:31], v[162:165], v[178:181], v[28:31]
	v_mfma_f32_16x16x32_bf16 v[24:27], v[170:173], v[178:181], v[24:27]
	v_mfma_f32_16x16x32_bf16 v[20:23], v[162:165], v[186:189], v[20:23]
	v_mfma_f32_16x16x32_bf16 v[16:19], v[170:173], v[186:189], v[16:19]
	v_mfma_f32_16x16x32_bf16 v[12:15], v[162:165], v[194:197], v[12:15]
	v_mfma_f32_16x16x32_bf16 v[8:11], v[170:173], v[194:197], v[8:11]
	v_mfma_f32_16x16x32_bf16 v[4:7], v[162:165], v[202:205], v[4:7]
	v_mfma_f32_16x16x32_bf16 v[0:3], v[170:173], v[202:205], v[0:3]
	v_mfma_f32_16x16x32_bf16 v[28:31], v[166:169], v[182:185], v[28:31]
	v_mfma_f32_16x16x32_bf16 v[24:27], v[174:177], v[182:185], v[24:27]
	v_mfma_f32_16x16x32_bf16 v[20:23], v[166:169], v[190:193], v[20:23]
	v_mfma_f32_16x16x32_bf16 v[16:19], v[174:177], v[190:193], v[16:19]
	s_barrier
	s_setprio 2
	v_mfma_f32_16x16x32_bf16 v[12:15], v[166:169], v[198:201], v[12:15]
	v_mfma_f32_16x16x32_bf16 v[8:11], v[174:177], v[198:201], v[8:11]
	v_mfma_f32_16x16x32_bf16 v[4:7], v[166:169], v[206:209], v[4:7]
	v_mfma_f32_16x16x32_bf16 v[0:3], v[174:177], v[206:209], v[0:3]
	s_setprio 0
	s_add_i32 s31, 0, 0x18000
	v_add_u32_e32 v148, s31, v214
	s_add_i32 s74, 0, 0x1c000
	ds_read_b128 v[128:131], v148
	ds_read_b128 v[132:135], v148 offset:1024
	ds_read_b128 v[136:139], v148 offset:2048
	ds_read_b128 v[158:161], v148 offset:3072
	v_add_u32_e32 v148, s74, v214
	ds_read_b128 v[162:165], v148
	ds_read_b128 v[166:169], v148 offset:1024
	ds_read_b128 v[170:173], v148 offset:2048
	ds_read_b128 v[174:177], v148 offset:3072
	s_add_u32 s26, s26, 0x80000
	s_addc_u32 s27, s27, 0
	s_mov_b32 m0, s40
	v_lshl_add_u64 v[224:225], s[26:27], 0, v[140:141]
	ds_read_b128 v[178:181], v217 offset:32768
	ds_read_b128 v[182:185], v217 offset:33792
	ds_read_b128 v[186:189], v217 offset:34816
	ds_read_b128 v[190:193], v217 offset:35840
	ds_read_b128 v[194:197], v217 offset:36864
	ds_read_b128 v[198:201], v217 offset:37888
	ds_read_b128 v[202:205], v217 offset:38912
	ds_read_b128 v[206:209], v217 offset:39936
	global_load_lds_dwordx4 v[224:225], off
	v_lshl_add_u64 v[224:225], s[26:27], 0, v[144:145]
	s_mov_b32 m0, s41
	s_nop 0
	global_load_lds_dwordx4 v[224:225], off
	s_waitcnt vmcnt(8)
	s_waitcnt lgkmcnt(0)
	s_barrier
	s_setprio 1
	s_waitcnt lgkmcnt(0)
	v_mfma_f32_16x16x32_bf16 v[124:127], v[128:131], v[178:181], v[124:127]
	v_mfma_f32_16x16x32_bf16 v[120:123], v[136:139], v[178:181], v[120:123]
	v_mfma_f32_16x16x32_bf16 v[116:119], v[128:131], v[186:189], v[116:119]
	v_mfma_f32_16x16x32_bf16 v[112:115], v[136:139], v[186:189], v[112:115]
	v_mfma_f32_16x16x32_bf16 v[108:111], v[128:131], v[194:197], v[108:111]
	v_mfma_f32_16x16x32_bf16 v[104:107], v[136:139], v[194:197], v[104:107]
	v_mfma_f32_16x16x32_bf16 v[100:103], v[128:131], v[202:205], v[100:103]
	v_mfma_f32_16x16x32_bf16 v[96:99], v[136:139], v[202:205], v[96:99]
	v_mfma_f32_16x16x32_bf16 v[124:127], v[132:135], v[182:185], v[124:127]
	v_mfma_f32_16x16x32_bf16 v[120:123], v[158:161], v[182:185], v[120:123]
	v_mfma_f32_16x16x32_bf16 v[116:119], v[132:135], v[190:193], v[116:119]
	v_mfma_f32_16x16x32_bf16 v[112:115], v[158:161], v[190:193], v[112:115]
	v_mfma_f32_16x16x32_bf16 v[108:111], v[132:135], v[198:201], v[108:111]
	v_mfma_f32_16x16x32_bf16 v[104:107], v[158:161], v[198:201], v[104:107]
	v_mfma_f32_16x16x32_bf16 v[100:103], v[132:135], v[206:209], v[100:103]
	v_mfma_f32_16x16x32_bf16 v[96:99], v[158:161], v[206:209], v[96:99]
	s_setprio 0
	s_setprio 1
	v_mfma_f32_16x16x32_bf16 v[60:63], v[162:165], v[178:181], v[60:63]
	v_mfma_f32_16x16x32_bf16 v[56:59], v[170:173], v[178:181], v[56:59]
	v_mfma_f32_16x16x32_bf16 v[52:55], v[162:165], v[186:189], v[52:55]
	v_mfma_f32_16x16x32_bf16 v[48:51], v[170:173], v[186:189], v[48:51]
	v_mfma_f32_16x16x32_bf16 v[44:47], v[162:165], v[194:197], v[44:47]
	v_mfma_f32_16x16x32_bf16 v[40:43], v[170:173], v[194:197], v[40:43]
	v_mfma_f32_16x16x32_bf16 v[36:39], v[162:165], v[202:205], v[36:39]
	v_mfma_f32_16x16x32_bf16 v[32:35], v[170:173], v[202:205], v[32:35]
	v_mfma_f32_16x16x32_bf16 v[60:63], v[166:169], v[182:185], v[60:63]
	v_mfma_f32_16x16x32_bf16 v[56:59], v[174:177], v[182:185], v[56:59]
	v_mfma_f32_16x16x32_bf16 v[52:55], v[166:169], v[190:193], v[52:55]
	v_mfma_f32_16x16x32_bf16 v[48:51], v[174:177], v[190:193], v[48:51]
	s_barrier
	s_setprio 2
	v_mfma_f32_16x16x32_bf16 v[44:47], v[166:169], v[198:201], v[44:47]
	v_mfma_f32_16x16x32_bf16 v[40:43], v[174:177], v[198:201], v[40:43]
	v_mfma_f32_16x16x32_bf16 v[36:39], v[166:169], v[206:209], v[36:39]
	v_mfma_f32_16x16x32_bf16 v[32:35], v[174:177], v[206:209], v[32:35]
	s_setprio 0
	s_add_i32 s26, s31, s67
	v_lshl_add_u64 v[210:211], v[210:211], 0, s[6:7]
	s_mov_b32 m0, s26
	ds_read_b128 v[178:181], v217 offset:49152
	ds_read_b128 v[182:185], v217 offset:50176
	ds_read_b128 v[186:189], v217 offset:51200
	ds_read_b128 v[190:193], v217 offset:52224
	ds_read_b128 v[194:197], v217 offset:53248
	ds_read_b128 v[198:201], v217 offset:54272
	ds_read_b128 v[202:205], v217 offset:55296
	ds_read_b128 v[206:209], v217 offset:56320
	global_load_lds_dwordx4 v[210:211], off
	s_add_i32 m0, s26, 0x2000
	s_add_u32 s24, s24, 0x80080
	v_lshl_add_u64 v[210:211], v[212:213], 0, s[6:7]
	s_addc_u32 s25, s25, 0
	s_add_i32 s26, s74, s67
	global_load_lds_dwordx4 v[210:211], off
	v_lshl_add_u64 v[210:211], s[24:25], 0, v[142:143]
	s_mov_b32 m0, s26
	s_nop 0
	global_load_lds_dwordx4 v[210:211], off
	v_lshl_add_u64 v[210:211], s[24:25], 0, v[146:147]
	s_add_i32 m0, s26, 0x2000
	s_nop 0
	global_load_lds_dwordx4 v[210:211], off
	v_lshl_add_u64 v[210:211], v[220:221], 0, s[6:7]
	s_mov_b32 m0, s55
	s_nop 0
	global_load_lds_dwordx4 v[210:211], off
	v_lshl_add_u64 v[210:211], v[222:223], 0, s[6:7]
	s_mov_b32 m0, s56
	s_nop 0
	global_load_lds_dwordx4 v[210:211], off
	s_waitcnt vmcnt(8)
	s_waitcnt lgkmcnt(0)
	s_barrier
	s_setprio 1
	s_waitcnt lgkmcnt(0)
	v_mfma_f32_16x16x32_bf16 v[92:95], v[128:131], v[178:181], v[92:95]
	v_mfma_f32_16x16x32_bf16 v[88:91], v[136:139], v[178:181], v[88:91]
	v_mfma_f32_16x16x32_bf16 v[84:87], v[128:131], v[186:189], v[84:87]
	v_mfma_f32_16x16x32_bf16 v[80:83], v[136:139], v[186:189], v[80:83]
	v_mfma_f32_16x16x32_bf16 v[76:79], v[128:131], v[194:197], v[76:79]
	v_mfma_f32_16x16x32_bf16 v[72:75], v[136:139], v[194:197], v[72:75]
	v_mfma_f32_16x16x32_bf16 v[68:71], v[128:131], v[202:205], v[68:71]
	v_mfma_f32_16x16x32_bf16 v[64:67], v[136:139], v[202:205], v[64:67]
	v_mfma_f32_16x16x32_bf16 v[92:95], v[132:135], v[182:185], v[92:95]
	v_mfma_f32_16x16x32_bf16 v[88:91], v[158:161], v[182:185], v[88:91]
	v_mfma_f32_16x16x32_bf16 v[84:87], v[132:135], v[190:193], v[84:87]
	v_mfma_f32_16x16x32_bf16 v[80:83], v[158:161], v[190:193], v[80:83]
	v_mfma_f32_16x16x32_bf16 v[76:79], v[132:135], v[198:201], v[76:79]
	v_mfma_f32_16x16x32_bf16 v[72:75], v[158:161], v[198:201], v[72:75]
	v_mfma_f32_16x16x32_bf16 v[68:71], v[132:135], v[206:209], v[68:71]
	v_mfma_f32_16x16x32_bf16 v[64:67], v[158:161], v[206:209], v[64:67]
	s_setprio 0
	s_setprio 1
	v_mfma_f32_16x16x32_bf16 v[28:31], v[162:165], v[178:181], v[28:31]
	v_mfma_f32_16x16x32_bf16 v[24:27], v[170:173], v[178:181], v[24:27]
	v_mfma_f32_16x16x32_bf16 v[20:23], v[162:165], v[186:189], v[20:23]
	v_mfma_f32_16x16x32_bf16 v[16:19], v[170:173], v[186:189], v[16:19]
	v_mfma_f32_16x16x32_bf16 v[12:15], v[162:165], v[194:197], v[12:15]
	v_mfma_f32_16x16x32_bf16 v[8:11], v[170:173], v[194:197], v[8:11]
	v_mfma_f32_16x16x32_bf16 v[4:7], v[162:165], v[202:205], v[4:7]
	v_mfma_f32_16x16x32_bf16 v[0:3], v[170:173], v[202:205], v[0:3]
	v_mfma_f32_16x16x32_bf16 v[28:31], v[166:169], v[182:185], v[28:31]
	v_mfma_f32_16x16x32_bf16 v[24:27], v[174:177], v[182:185], v[24:27]
	v_mfma_f32_16x16x32_bf16 v[20:23], v[166:169], v[190:193], v[20:23]
	v_mfma_f32_16x16x32_bf16 v[16:19], v[174:177], v[190:193], v[16:19]
	s_barrier
	s_setprio 2
	v_mfma_f32_16x16x32_bf16 v[12:15], v[166:169], v[198:201], v[12:15]
	v_mfma_f32_16x16x32_bf16 v[8:11], v[174:177], v[198:201], v[8:11]
	v_mfma_f32_16x16x32_bf16 v[4:7], v[166:169], v[206:209], v[4:7]
	v_mfma_f32_16x16x32_bf16 v[0:3], v[174:177], v[206:209], v[0:3]
	s_setprio 0
	s_add_i32 s30, s30, 2
	s_add_u32 s28, s28, 0x100
	s_addc_u32 s29, s29, 0
	s_add_u32 s22, s22, 0x100
	s_addc_u32 s23, s23, 0
	s_cmp_gt_u32 s30, 29
	s_cbranch_scc0 .LBB0_1192
	s_and_b64 vcc, exec, s[8:9]
	s_cbranch_vccz .LBB0_1195
	s_barrier

.LBB0_1304:
	ds_read_b128 v[124:127], v163
	ds_read_b128 v[156:159], v163 offset:1024
	ds_read_b128 v[170:173], v163 offset:2048
	ds_read_b128 v[174:177], v163 offset:3072
	ds_read_b128 v[178:181], v165
	ds_read_b128 v[182:185], v165 offset:1024
	ds_read_b128 v[186:189], v165 offset:2048
	ds_read_b128 v[190:193], v165 offset:3072
	s_add_u32 s26, s24, 0xfff80080
	s_addc_u32 s27, s25, -1
	s_cmp_eq_u32 s55, 28
	s_cselect_b32 s29, s17, s27
	s_cselect_b32 s28, s51, s26
	s_cselect_b32 s27, s15, s54
	s_cselect_b32 s26, s52, s53
	v_lshl_add_u64 v[114:115], s[24:25], 0, v[148:149]
	s_add_i32 m0, s23, 0xc000
	ds_read_b128 v[194:197], v167
	ds_read_b128 v[198:201], v167 offset:1024
	ds_read_b128 v[202:205], v167 offset:2048
	ds_read_b128 v[206:209], v167 offset:3072
	ds_read_b128 v[210:213], v167 offset:4096
	ds_read_b128 v[214:217], v167 offset:5120
	ds_read_b128 v[218:221], v167 offset:6144
	ds_read_b128 v[222:225], v167 offset:7168
	global_load_lds_dwordx4 v[114:115], off
	v_lshl_add_u64 v[114:115], s[24:25], 0, v[146:147]
	s_add_i32 m0, s23, 0xe000
	s_nop 0
	global_load_lds_dwordx4 v[114:115], off
	s_waitcnt vmcnt(8)
	s_waitcnt lgkmcnt(0)
	s_barrier
	s_setprio 1
	s_waitcnt lgkmcnt(0)
	v_mfma_f32_16x16x32_bf16 v[132:135], v[124:127], v[194:197], v[132:135]
	v_mfma_f32_16x16x32_bf16 v[120:123], v[170:173], v[194:197], v[120:123]
	v_mfma_f32_16x16x32_bf16 v[108:111], v[124:127], v[202:205], v[108:111]
	v_mfma_f32_16x16x32_bf16 v[100:103], v[170:173], v[202:205], v[100:103]
	v_mfma_f32_16x16x32_bf16 v[92:95], v[124:127], v[210:213], v[92:95]
	v_mfma_f32_16x16x32_bf16 v[84:87], v[170:173], v[210:213], v[84:87]
	v_mfma_f32_16x16x32_bf16 v[76:79], v[124:127], v[218:221], v[76:79]
	v_mfma_f32_16x16x32_bf16 v[68:71], v[170:173], v[218:221], v[68:71]
	v_mfma_f32_16x16x32_bf16 v[132:135], v[156:159], v[198:201], v[132:135]
	v_mfma_f32_16x16x32_bf16 v[120:123], v[174:177], v[198:201], v[120:123]
	v_mfma_f32_16x16x32_bf16 v[108:111], v[156:159], v[206:209], v[108:111]
	v_mfma_f32_16x16x32_bf16 v[100:103], v[174:177], v[206:209], v[100:103]
	v_mfma_f32_16x16x32_bf16 v[92:95], v[156:159], v[214:217], v[92:95]
	v_mfma_f32_16x16x32_bf16 v[84:87], v[174:177], v[214:217], v[84:87]
	v_mfma_f32_16x16x32_bf16 v[76:79], v[156:159], v[222:225], v[76:79]
	v_mfma_f32_16x16x32_bf16 v[68:71], v[174:177], v[222:225], v[68:71]
	s_setprio 0
	s_setprio 1
	v_mfma_f32_16x16x32_bf16 v[128:131], v[178:181], v[194:197], v[128:131]
	v_mfma_f32_16x16x32_bf16 v[114:117], v[186:189], v[194:197], v[116:119]
	v_mfma_f32_16x16x32_bf16 v[104:107], v[178:181], v[202:205], v[104:107]
	v_mfma_f32_16x16x32_bf16 v[96:99], v[186:189], v[202:205], v[96:99]
	v_mfma_f32_16x16x32_bf16 v[88:91], v[178:181], v[210:213], v[88:91]
	v_mfma_f32_16x16x32_bf16 v[80:83], v[186:189], v[210:213], v[80:83]
	v_mfma_f32_16x16x32_bf16 v[72:75], v[178:181], v[218:221], v[72:75]
	v_mfma_f32_16x16x32_bf16 v[64:67], v[186:189], v[218:221], v[64:67]
	v_mfma_f32_16x16x32_bf16 v[128:131], v[182:185], v[198:201], v[128:131]
	v_mfma_f32_16x16x32_bf16 v[114:117], v[190:193], v[198:201], v[114:117]
	v_mfma_f32_16x16x32_bf16 v[104:107], v[182:185], v[206:209], v[104:107]
	v_mfma_f32_16x16x32_bf16 v[96:99], v[190:193], v[206:209], v[96:99]
	s_barrier
	s_setprio 2
	v_mfma_f32_16x16x32_bf16 v[88:91], v[182:185], v[214:217], v[88:91]
	v_mfma_f32_16x16x32_bf16 v[80:83], v[190:193], v[214:217], v[80:83]
	v_mfma_f32_16x16x32_bf16 v[72:75], v[182:185], v[222:225], v[72:75]
	v_mfma_f32_16x16x32_bf16 v[64:67], v[190:193], v[222:225], v[64:67]
	s_setprio 0
	s_add_i32 s56, s47, s67
	v_lshl_add_u64 v[226:227], s[26:27], 0, v[138:139]
	s_mov_b32 m0, s56
	ds_read_b128 v[194:197], v167 offset:16384
	ds_read_b128 v[198:201], v167 offset:17408
	ds_read_b128 v[202:205], v167 offset:18432
	ds_read_b128 v[206:209], v167 offset:19456
	ds_read_b128 v[210:213], v167 offset:20480
	ds_read_b128 v[214:217], v167 offset:21504
	ds_read_b128 v[218:221], v167 offset:22528
	ds_read_b128 v[222:225], v167 offset:23552
	global_load_lds_dwordx4 v[226:227], off
	s_add_i32 m0, s56, 0x2000
	s_add_u32 s56, s26, 0x80000
	v_lshl_add_u64 v[228:229], s[26:27], 0, v[142:143]
	s_addc_u32 s57, s27, 0
	s_add_i32 s58, s48, s67
	global_load_lds_dwordx4 v[228:229], off
	v_lshl_add_u64 v[118:119], s[56:57], 0, v[138:139]
	s_mov_b32 m0, s58
	v_lshl_add_u64 v[230:231], s[28:29], 0, v[136:137]
	global_load_lds_dwordx4 v[118:119], off
	v_lshl_add_u64 v[118:119], s[56:57], 0, v[142:143]
	s_add_i32 m0, s58, 0x2000
	v_lshl_add_u64 v[232:233], s[28:29], 0, v[140:141]
	global_load_lds_dwordx4 v[118:119], off
	s_mov_b32 m0, s23
	s_nop 0
	global_load_lds_dwordx4 v[230:231], off
	s_mov_b32 m0, s37
	s_nop 0
	global_load_lds_dwordx4 v[232:233], off
	s_waitcnt vmcnt(8)
	s_waitcnt lgkmcnt(0)
	s_barrier
	s_setprio 1
	s_waitcnt lgkmcnt(0)
	v_mfma_f32_16x16x32_bf16 v[60:63], v[124:127], v[194:197], v[60:63]
	v_mfma_f32_16x16x32_bf16 v[52:55], v[170:173], v[194:197], v[52:55]
	v_mfma_f32_16x16x32_bf16 v[44:47], v[124:127], v[202:205], v[44:47]
	v_mfma_f32_16x16x32_bf16 v[36:39], v[170:173], v[202:205], v[36:39]
	v_mfma_f32_16x16x32_bf16 v[28:31], v[124:127], v[210:213], v[28:31]
	v_mfma_f32_16x16x32_bf16 v[20:23], v[170:173], v[210:213], v[20:23]
	v_mfma_f32_16x16x32_bf16 v[12:15], v[124:127], v[218:221], v[12:15]
	v_mfma_f32_16x16x32_bf16 v[4:7], v[170:173], v[218:221], v[4:7]
	v_mfma_f32_16x16x32_bf16 v[60:63], v[156:159], v[198:201], v[60:63]
	v_mfma_f32_16x16x32_bf16 v[52:55], v[174:177], v[198:201], v[52:55]
	v_mfma_f32_16x16x32_bf16 v[44:47], v[156:159], v[206:209], v[44:47]
	v_mfma_f32_16x16x32_bf16 v[36:39], v[174:177], v[206:209], v[36:39]
	v_mfma_f32_16x16x32_bf16 v[28:31], v[156:159], v[214:217], v[28:31]
	v_mfma_f32_16x16x32_bf16 v[20:23], v[174:177], v[214:217], v[20:23]
	v_mfma_f32_16x16x32_bf16 v[12:15], v[156:159], v[222:225], v[12:15]
	v_mfma_f32_16x16x32_bf16 v[4:7], v[174:177], v[222:225], v[4:7]
	s_setprio 0
	s_setprio 1
	v_mfma_f32_16x16x32_bf16 v[56:59], v[178:181], v[194:197], v[56:59]
	v_mfma_f32_16x16x32_bf16 v[48:51], v[186:189], v[194:197], v[48:51]
	v_mfma_f32_16x16x32_bf16 v[40:43], v[178:181], v[202:205], v[40:43]
	v_mfma_f32_16x16x32_bf16 v[32:35], v[186:189], v[202:205], v[32:35]
	v_mfma_f32_16x16x32_bf16 v[24:27], v[178:181], v[210:213], v[24:27]
	v_mfma_f32_16x16x32_bf16 v[16:19], v[186:189], v[210:213], v[16:19]
	v_mfma_f32_16x16x32_bf16 v[8:11], v[178:181], v[218:221], v[8:11]
	v_mfma_f32_16x16x32_bf16 v[0:3], v[186:189], v[218:221], v[0:3]
	v_mfma_f32_16x16x32_bf16 v[56:59], v[182:185], v[198:201], v[56:59]
	v_mfma_f32_16x16x32_bf16 v[48:51], v[190:193], v[198:201], v[48:51]
	v_mfma_f32_16x16x32_bf16 v[40:43], v[182:185], v[206:209], v[40:43]
	v_mfma_f32_16x16x32_bf16 v[32:35], v[190:193], v[206:209], v[32:35]
	s_barrier
	s_setprio 2
	v_mfma_f32_16x16x32_bf16 v[24:27], v[182:185], v[214:217], v[24:27]
	v_mfma_f32_16x16x32_bf16 v[16:19], v[190:193], v[214:217], v[16:19]
	v_mfma_f32_16x16x32_bf16 v[8:11], v[182:185], v[222:225], v[8:11]
	v_mfma_f32_16x16x32_bf16 v[0:3], v[190:193], v[222:225], v[0:3]
	s_setprio 0
	s_add_i32 s56, 0, 0x18000
	v_add_u32_e32 v113, s56, v155
	s_add_i32 s57, 0, 0x1c000
	ds_read_b128 v[124:127], v113
	ds_read_b128 v[156:159], v113 offset:1024
	ds_read_b128 v[170:173], v113 offset:2048
	ds_read_b128 v[174:177], v113 offset:3072
	v_add_u32_e32 v113, s57, v155
	ds_read_b128 v[178:181], v113
	ds_read_b128 v[182:185], v113 offset:1024
	ds_read_b128 v[186:189], v113 offset:2048
	ds_read_b128 v[190:193], v113 offset:3072
	s_add_u32 s28, s28, 0x80000
	s_addc_u32 s29, s29, 0
	s_mov_b32 m0, s38
	v_lshl_add_u64 v[118:119], s[28:29], 0, v[136:137]
	ds_read_b128 v[194:197], v167 offset:32768
	ds_read_b128 v[198:201], v167 offset:33792
	ds_read_b128 v[202:205], v167 offset:34816
	ds_read_b128 v[206:209], v167 offset:35840
	ds_read_b128 v[210:213], v167 offset:36864
	ds_read_b128 v[214:217], v167 offset:37888
	ds_read_b128 v[218:221], v167 offset:38912
	ds_read_b128 v[222:225], v167 offset:39936
	global_load_lds_dwordx4 v[118:119], off
	v_lshl_add_u64 v[118:119], s[28:29], 0, v[140:141]
	s_mov_b32 m0, s39
	s_nop 0
	global_load_lds_dwordx4 v[118:119], off
	s_waitcnt vmcnt(8)
	s_waitcnt lgkmcnt(0)
	s_barrier
	s_setprio 1
	s_waitcnt lgkmcnt(0)
	v_mfma_f32_16x16x32_bf16 v[132:135], v[124:127], v[194:197], v[132:135]
	v_mfma_f32_16x16x32_bf16 v[118:121], v[170:173], v[194:197], v[120:123]
	v_mfma_f32_16x16x32_bf16 v[108:111], v[124:127], v[202:205], v[108:111]
	v_mfma_f32_16x16x32_bf16 v[100:103], v[170:173], v[202:205], v[100:103]
	v_mfma_f32_16x16x32_bf16 v[92:95], v[124:127], v[210:213], v[92:95]
	v_mfma_f32_16x16x32_bf16 v[84:87], v[170:173], v[210:213], v[84:87]
	v_mfma_f32_16x16x32_bf16 v[76:79], v[124:127], v[218:221], v[76:79]
	v_mfma_f32_16x16x32_bf16 v[68:71], v[170:173], v[218:221], v[68:71]
	v_mfma_f32_16x16x32_bf16 v[132:135], v[156:159], v[198:201], v[132:135]
	v_mfma_f32_16x16x32_bf16 v[120:123], v[174:177], v[198:201], v[118:121]
	v_mfma_f32_16x16x32_bf16 v[108:111], v[156:159], v[206:209], v[108:111]
	v_mfma_f32_16x16x32_bf16 v[100:103], v[174:177], v[206:209], v[100:103]
	v_mfma_f32_16x16x32_bf16 v[92:95], v[156:159], v[214:217], v[92:95]
	v_mfma_f32_16x16x32_bf16 v[84:87], v[174:177], v[214:217], v[84:87]
	v_mfma_f32_16x16x32_bf16 v[76:79], v[156:159], v[222:225], v[76:79]
	v_mfma_f32_16x16x32_bf16 v[68:71], v[174:177], v[222:225], v[68:71]
	s_setprio 0
	s_setprio 1
	v_mfma_f32_16x16x32_bf16 v[128:131], v[178:181], v[194:197], v[128:131]
	v_mfma_f32_16x16x32_bf16 v[114:117], v[186:189], v[194:197], v[114:117]
	v_mfma_f32_16x16x32_bf16 v[104:107], v[178:181], v[202:205], v[104:107]
	v_mfma_f32_16x16x32_bf16 v[96:99], v[186:189], v[202:205], v[96:99]
	v_mfma_f32_16x16x32_bf16 v[88:91], v[178:181], v[210:213], v[88:91]
	v_mfma_f32_16x16x32_bf16 v[80:83], v[186:189], v[210:213], v[80:83]
	v_mfma_f32_16x16x32_bf16 v[72:75], v[178:181], v[218:221], v[72:75]
	v_mfma_f32_16x16x32_bf16 v[64:67], v[186:189], v[218:221], v[64:67]
	v_mfma_f32_16x16x32_bf16 v[128:131], v[182:185], v[198:201], v[128:131]
	v_mfma_f32_16x16x32_bf16 v[116:119], v[190:193], v[198:201], v[114:117]
	v_mfma_f32_16x16x32_bf16 v[104:107], v[182:185], v[206:209], v[104:107]
	v_mfma_f32_16x16x32_bf16 v[96:99], v[190:193], v[206:209], v[96:99]
	s_barrier
	s_setprio 2
	v_mfma_f32_16x16x32_bf16 v[88:91], v[182:185], v[214:217], v[88:91]
	v_mfma_f32_16x16x32_bf16 v[80:83], v[190:193], v[214:217], v[80:83]
	v_mfma_f32_16x16x32_bf16 v[72:75], v[182:185], v[222:225], v[72:75]
	v_mfma_f32_16x16x32_bf16 v[64:67], v[190:193], v[222:225], v[64:67]
	s_setprio 0
	s_add_i32 s28, s56, s67
	v_lshl_add_u64 v[114:115], v[226:227], 0, s[10:11]
	s_mov_b32 m0, s28
	ds_read_b128 v[194:197], v167 offset:49152
	ds_read_b128 v[198:201], v167 offset:50176
	ds_read_b128 v[202:205], v167 offset:51200
	ds_read_b128 v[206:209], v167 offset:52224
	ds_read_b128 v[210:213], v167 offset:53248
	ds_read_b128 v[214:217], v167 offset:54272
	ds_read_b128 v[218:221], v167 offset:55296
	ds_read_b128 v[222:225], v167 offset:56320
	global_load_lds_dwordx4 v[114:115], off
	s_add_i32 m0, s28, 0x2000
	s_add_u32 s26, s26, 0x80080
	v_lshl_add_u64 v[114:115], v[228:229], 0, s[10:11]
	s_addc_u32 s27, s27, 0
	s_add_i32 s28, s57, s67
	global_load_lds_dwordx4 v[114:115], off
	v_lshl_add_u64 v[114:115], s[26:27], 0, v[138:139]
	s_mov_b32 m0, s28
	s_nop 0
	global_load_lds_dwordx4 v[114:115], off
	v_lshl_add_u64 v[114:115], s[26:27], 0, v[142:143]
	s_add_i32 m0, s28, 0x2000
	s_nop 0
	global_load_lds_dwordx4 v[114:115], off
	v_lshl_add_u64 v[114:115], v[230:231], 0, s[10:11]
	s_mov_b32 m0, s41
	s_nop 0
	global_load_lds_dwordx4 v[114:115], off
	v_lshl_add_u64 v[114:115], v[232:233], 0, s[10:11]
	s_mov_b32 m0, s42
	s_nop 0
	global_load_lds_dwordx4 v[114:115], off
	s_waitcnt vmcnt(8)
	s_waitcnt lgkmcnt(0)
	s_barrier
	s_setprio 1
	s_waitcnt lgkmcnt(0)
	v_mfma_f32_16x16x32_bf16 v[60:63], v[124:127], v[194:197], v[60:63]
	v_mfma_f32_16x16x32_bf16 v[52:55], v[170:173], v[194:197], v[52:55]
	v_mfma_f32_16x16x32_bf16 v[44:47], v[124:127], v[202:205], v[44:47]
	v_mfma_f32_16x16x32_bf16 v[36:39], v[170:173], v[202:205], v[36:39]
	v_mfma_f32_16x16x32_bf16 v[28:31], v[124:127], v[210:213], v[28:31]
	v_mfma_f32_16x16x32_bf16 v[20:23], v[170:173], v[210:213], v[20:23]
	v_mfma_f32_16x16x32_bf16 v[12:15], v[124:127], v[218:221], v[12:15]
	v_mfma_f32_16x16x32_bf16 v[4:7], v[170:173], v[218:221], v[4:7]
	v_mfma_f32_16x16x32_bf16 v[60:63], v[156:159], v[198:201], v[60:63]
	v_mfma_f32_16x16x32_bf16 v[52:55], v[174:177], v[198:201], v[52:55]
	v_mfma_f32_16x16x32_bf16 v[44:47], v[156:159], v[206:209], v[44:47]
	v_mfma_f32_16x16x32_bf16 v[36:39], v[174:177], v[206:209], v[36:39]
	v_mfma_f32_16x16x32_bf16 v[28:31], v[156:159], v[214:217], v[28:31]
	v_mfma_f32_16x16x32_bf16 v[20:23], v[174:177], v[214:217], v[20:23]
	v_mfma_f32_16x16x32_bf16 v[12:15], v[156:159], v[222:225], v[12:15]
	v_mfma_f32_16x16x32_bf16 v[4:7], v[174:177], v[222:225], v[4:7]
	s_setprio 0
	s_setprio 1
	v_mfma_f32_16x16x32_bf16 v[56:59], v[178:181], v[194:197], v[56:59]
	v_mfma_f32_16x16x32_bf16 v[48:51], v[186:189], v[194:197], v[48:51]
	v_mfma_f32_16x16x32_bf16 v[40:43], v[178:181], v[202:205], v[40:43]
	v_mfma_f32_16x16x32_bf16 v[32:35], v[186:189], v[202:205], v[32:35]
	v_mfma_f32_16x16x32_bf16 v[24:27], v[178:181], v[210:213], v[24:27]
	v_mfma_f32_16x16x32_bf16 v[16:19], v[186:189], v[210:213], v[16:19]
	v_mfma_f32_16x16x32_bf16 v[8:11], v[178:181], v[218:221], v[8:11]
	v_mfma_f32_16x16x32_bf16 v[0:3], v[186:189], v[218:221], v[0:3]
	v_mfma_f32_16x16x32_bf16 v[56:59], v[182:185], v[198:201], v[56:59]
	v_mfma_f32_16x16x32_bf16 v[48:51], v[190:193], v[198:201], v[48:51]
	v_mfma_f32_16x16x32_bf16 v[40:43], v[182:185], v[206:209], v[40:43]
	v_mfma_f32_16x16x32_bf16 v[32:35], v[190:193], v[206:209], v[32:35]
	s_barrier
	s_setprio 2
	v_mfma_f32_16x16x32_bf16 v[24:27], v[182:185], v[214:217], v[24:27]
	v_mfma_f32_16x16x32_bf16 v[16:19], v[190:193], v[214:217], v[16:19]
	v_mfma_f32_16x16x32_bf16 v[8:11], v[182:185], v[222:225], v[8:11]
	v_mfma_f32_16x16x32_bf16 v[0:3], v[190:193], v[222:225], v[0:3]
	s_setprio 0
	s_add_i32 s55, s55, 2
	s_add_u32 s53, s53, 0x100
	s_addc_u32 s54, s54, 0
	s_add_u32 s24, s24, 0x100
	s_addc_u32 s25, s25, 0
	s_cmp_gt_u32 s55, 29
	s_cbranch_scc0 .LBB0_1304
	s_and_b64 vcc, exec, s[12:13]
	s_cbranch_vccz .LBB0_1307
	s_barrier

.LBB0_1412:
	ds_read_b128 v[128:131], v215
	ds_read_b128 v[132:135], v215 offset:1024
	ds_read_b128 v[136:139], v215 offset:2048
	ds_read_b128 v[158:161], v215 offset:3072
	ds_read_b128 v[162:165], v216
	ds_read_b128 v[166:169], v216 offset:1024
	ds_read_b128 v[170:173], v216 offset:2048
	ds_read_b128 v[174:177], v216 offset:3072
	s_add_u32 s18, s16, 0x100
	s_addc_u32 s19, s17, 0
	s_cmpk_eq_i32 s26, 0x54
	s_cselect_b32 s23, s3, s19
	s_cselect_b32 s22, s2, s18
	s_cselect_b32 s21, s15, s25
	s_cselect_b32 s20, s14, s24
	v_lshl_add_u64 v[210:211], s[16:17], 0, v[152:153]
	s_add_i32 m0, s34, 0xc000
	ds_read_b128 v[178:181], v217
	ds_read_b128 v[182:185], v217 offset:1024
	ds_read_b128 v[186:189], v217 offset:2048
	ds_read_b128 v[190:193], v217 offset:3072
	ds_read_b128 v[194:197], v217 offset:4096
	ds_read_b128 v[198:201], v217 offset:5120
	ds_read_b128 v[202:205], v217 offset:6144
	ds_read_b128 v[206:209], v217 offset:7168
	global_load_lds_dwordx4 v[210:211], off
	v_lshl_add_u64 v[210:211], s[16:17], 0, v[150:151]
	s_add_i32 m0, s34, 0xe000
	s_nop 0
	global_load_lds_dwordx4 v[210:211], off
	s_waitcnt vmcnt(8)
	s_waitcnt lgkmcnt(0)
	s_barrier
	s_setprio 1
	s_waitcnt lgkmcnt(0)
	v_mfma_f32_16x16x32_bf16 v[124:127], v[128:131], v[178:181], v[124:127]
	v_mfma_f32_16x16x32_bf16 v[120:123], v[136:139], v[178:181], v[120:123]
	v_mfma_f32_16x16x32_bf16 v[116:119], v[128:131], v[186:189], v[116:119]
	v_mfma_f32_16x16x32_bf16 v[112:115], v[136:139], v[186:189], v[112:115]
	v_mfma_f32_16x16x32_bf16 v[108:111], v[128:131], v[194:197], v[108:111]
	v_mfma_f32_16x16x32_bf16 v[104:107], v[136:139], v[194:197], v[104:107]
	v_mfma_f32_16x16x32_bf16 v[100:103], v[128:131], v[202:205], v[100:103]
	v_mfma_f32_16x16x32_bf16 v[96:99], v[136:139], v[202:205], v[96:99]
	v_mfma_f32_16x16x32_bf16 v[124:127], v[132:135], v[182:185], v[124:127]
	v_mfma_f32_16x16x32_bf16 v[120:123], v[158:161], v[182:185], v[120:123]
	v_mfma_f32_16x16x32_bf16 v[116:119], v[132:135], v[190:193], v[116:119]
	v_mfma_f32_16x16x32_bf16 v[112:115], v[158:161], v[190:193], v[112:115]
	v_mfma_f32_16x16x32_bf16 v[108:111], v[132:135], v[198:201], v[108:111]
	v_mfma_f32_16x16x32_bf16 v[104:107], v[158:161], v[198:201], v[104:107]
	v_mfma_f32_16x16x32_bf16 v[100:103], v[132:135], v[206:209], v[100:103]
	v_mfma_f32_16x16x32_bf16 v[96:99], v[158:161], v[206:209], v[96:99]
	s_setprio 0
	s_setprio 1
	v_mfma_f32_16x16x32_bf16 v[60:63], v[162:165], v[178:181], v[60:63]
	v_mfma_f32_16x16x32_bf16 v[56:59], v[170:173], v[178:181], v[56:59]
	v_mfma_f32_16x16x32_bf16 v[52:55], v[162:165], v[186:189], v[52:55]
	v_mfma_f32_16x16x32_bf16 v[48:51], v[170:173], v[186:189], v[48:51]
	v_mfma_f32_16x16x32_bf16 v[44:47], v[162:165], v[194:197], v[44:47]
	v_mfma_f32_16x16x32_bf16 v[40:43], v[170:173], v[194:197], v[40:43]
	v_mfma_f32_16x16x32_bf16 v[36:39], v[162:165], v[202:205], v[36:39]
	v_mfma_f32_16x16x32_bf16 v[32:35], v[170:173], v[202:205], v[32:35]
	v_mfma_f32_16x16x32_bf16 v[60:63], v[166:169], v[182:185], v[60:63]
	v_mfma_f32_16x16x32_bf16 v[56:59], v[174:177], v[182:185], v[56:59]
	v_mfma_f32_16x16x32_bf16 v[52:55], v[166:169], v[190:193], v[52:55]
	v_mfma_f32_16x16x32_bf16 v[48:51], v[174:177], v[190:193], v[48:51]
	s_barrier
	s_setprio 2
	v_mfma_f32_16x16x32_bf16 v[44:47], v[166:169], v[198:201], v[44:47]
	v_mfma_f32_16x16x32_bf16 v[40:43], v[174:177], v[198:201], v[40:43]
	v_mfma_f32_16x16x32_bf16 v[36:39], v[166:169], v[206:209], v[36:39]
	v_mfma_f32_16x16x32_bf16 v[32:35], v[174:177], v[206:209], v[32:35]
	s_setprio 0
	s_add_i32 s16, s56, s67
	v_lshl_add_u64 v[210:211], s[20:21], 0, v[142:143]
	s_mov_b32 m0, s16
	ds_read_b128 v[178:181], v217 offset:16384
	ds_read_b128 v[182:185], v217 offset:17408
	ds_read_b128 v[186:189], v217 offset:18432
	ds_read_b128 v[190:193], v217 offset:19456
	ds_read_b128 v[194:197], v217 offset:20480
	ds_read_b128 v[198:201], v217 offset:21504
	ds_read_b128 v[202:205], v217 offset:22528
	ds_read_b128 v[206:209], v217 offset:23552
	global_load_lds_dwordx4 v[210:211], off
	s_add_i32 m0, s16, 0x2000
	s_add_u32 s16, s20, 0x160000
	v_lshl_add_u64 v[212:213], s[20:21], 0, v[146:147]
	s_addc_u32 s17, s21, 0
	s_add_i32 s27, s57, s67
	global_load_lds_dwordx4 v[212:213], off
	v_lshl_add_u64 v[220:221], s[16:17], 0, v[142:143]
	s_mov_b32 m0, s27
	v_lshl_add_u64 v[222:223], s[22:23], 0, v[144:145]
	global_load_lds_dwordx4 v[220:221], off
	v_lshl_add_u64 v[220:221], s[16:17], 0, v[146:147]
	s_add_i32 m0, s27, 0x2000
	s_nop 0
	global_load_lds_dwordx4 v[220:221], off
	v_lshl_add_u64 v[220:221], s[22:23], 0, v[140:141]
	s_mov_b32 m0, s34
	s_nop 0
	global_load_lds_dwordx4 v[220:221], off
	s_mov_b32 m0, s35
	s_nop 0
	global_load_lds_dwordx4 v[222:223], off
	s_waitcnt vmcnt(8)
	s_waitcnt lgkmcnt(0)
	s_barrier
	s_setprio 1
	s_waitcnt lgkmcnt(0)
	v_mfma_f32_16x16x32_bf16 v[92:95], v[128:131], v[178:181], v[92:95]
	v_mfma_f32_16x16x32_bf16 v[88:91], v[136:139], v[178:181], v[88:91]
	v_mfma_f32_16x16x32_bf16 v[84:87], v[128:131], v[186:189], v[84:87]
	v_mfma_f32_16x16x32_bf16 v[80:83], v[136:139], v[186:189], v[80:83]
	v_mfma_f32_16x16x32_bf16 v[76:79], v[128:131], v[194:197], v[76:79]
	v_mfma_f32_16x16x32_bf16 v[72:75], v[136:139], v[194:197], v[72:75]
	v_mfma_f32_16x16x32_bf16 v[68:71], v[128:131], v[202:205], v[68:71]
	v_mfma_f32_16x16x32_bf16 v[64:67], v[136:139], v[202:205], v[64:67]
	v_mfma_f32_16x16x32_bf16 v[92:95], v[132:135], v[182:185], v[92:95]
	v_mfma_f32_16x16x32_bf16 v[88:91], v[158:161], v[182:185], v[88:91]
	v_mfma_f32_16x16x32_bf16 v[84:87], v[132:135], v[190:193], v[84:87]
	v_mfma_f32_16x16x32_bf16 v[80:83], v[158:161], v[190:193], v[80:83]
	v_mfma_f32_16x16x32_bf16 v[76:79], v[132:135], v[198:201], v[76:79]
	v_mfma_f32_16x16x32_bf16 v[72:75], v[158:161], v[198:201], v[72:75]
	v_mfma_f32_16x16x32_bf16 v[68:71], v[132:135], v[206:209], v[68:71]
	v_mfma_f32_16x16x32_bf16 v[64:67], v[158:161], v[206:209], v[64:67]
	s_setprio 0
	s_setprio 1
	v_mfma_f32_16x16x32_bf16 v[28:31], v[162:165], v[178:181], v[28:31]
	v_mfma_f32_16x16x32_bf16 v[24:27], v[170:173], v[178:181], v[24:27]
	v_mfma_f32_16x16x32_bf16 v[20:23], v[162:165], v[186:189], v[20:23]
	v_mfma_f32_16x16x32_bf16 v[16:19], v[170:173], v[186:189], v[16:19]
	v_mfma_f32_16x16x32_bf16 v[12:15], v[162:165], v[194:197], v[12:15]
	v_mfma_f32_16x16x32_bf16 v[8:11], v[170:173], v[194:197], v[8:11]
	v_mfma_f32_16x16x32_bf16 v[4:7], v[162:165], v[202:205], v[4:7]
	v_mfma_f32_16x16x32_bf16 v[0:3], v[170:173], v[202:205], v[0:3]
	v_mfma_f32_16x16x32_bf16 v[28:31], v[166:169], v[182:185], v[28:31]
	v_mfma_f32_16x16x32_bf16 v[24:27], v[174:177], v[182:185], v[24:27]
	v_mfma_f32_16x16x32_bf16 v[20:23], v[166:169], v[190:193], v[20:23]
	v_mfma_f32_16x16x32_bf16 v[16:19], v[174:177], v[190:193], v[16:19]
	s_barrier
	s_setprio 2
	v_mfma_f32_16x16x32_bf16 v[12:15], v[166:169], v[198:201], v[12:15]
	v_mfma_f32_16x16x32_bf16 v[8:11], v[174:177], v[198:201], v[8:11]
	v_mfma_f32_16x16x32_bf16 v[4:7], v[166:169], v[206:209], v[4:7]
	v_mfma_f32_16x16x32_bf16 v[0:3], v[174:177], v[206:209], v[0:3]
	s_setprio 0
	s_add_i32 s27, 0, 0x18000
	v_add_u32_e32 v148, s27, v214
	s_add_i32 s72, 0, 0x1c000
	ds_read_b128 v[128:131], v148
	ds_read_b128 v[132:135], v148 offset:1024
	ds_read_b128 v[136:139], v148 offset:2048
	ds_read_b128 v[158:161], v148 offset:3072
	v_add_u32_e32 v148, s72, v214
	ds_read_b128 v[162:165], v148
	ds_read_b128 v[166:169], v148 offset:1024
	ds_read_b128 v[170:173], v148 offset:2048
	ds_read_b128 v[174:177], v148 offset:3072
	s_add_u32 s16, s22, 0x160000
	s_addc_u32 s17, s23, 0
	s_mov_b32 m0, s36
	v_lshl_add_u64 v[224:225], s[16:17], 0, v[140:141]
	ds_read_b128 v[178:181], v217 offset:32768
	ds_read_b128 v[182:185], v217 offset:33792
	ds_read_b128 v[186:189], v217 offset:34816
	ds_read_b128 v[190:193], v217 offset:35840
	ds_read_b128 v[194:197], v217 offset:36864
	ds_read_b128 v[198:201], v217 offset:37888
	ds_read_b128 v[202:205], v217 offset:38912
	ds_read_b128 v[206:209], v217 offset:39936
	global_load_lds_dwordx4 v[224:225], off
	v_lshl_add_u64 v[224:225], s[16:17], 0, v[144:145]
	s_mov_b32 m0, s37
	s_nop 0
	global_load_lds_dwordx4 v[224:225], off
	s_waitcnt vmcnt(8)
	s_waitcnt lgkmcnt(0)
	s_barrier
	s_setprio 1
	s_waitcnt lgkmcnt(0)
	v_mfma_f32_16x16x32_bf16 v[124:127], v[128:131], v[178:181], v[124:127]
	v_mfma_f32_16x16x32_bf16 v[120:123], v[136:139], v[178:181], v[120:123]
	v_mfma_f32_16x16x32_bf16 v[116:119], v[128:131], v[186:189], v[116:119]
	v_mfma_f32_16x16x32_bf16 v[112:115], v[136:139], v[186:189], v[112:115]
	v_mfma_f32_16x16x32_bf16 v[108:111], v[128:131], v[194:197], v[108:111]
	v_mfma_f32_16x16x32_bf16 v[104:107], v[136:139], v[194:197], v[104:107]
	v_mfma_f32_16x16x32_bf16 v[100:103], v[128:131], v[202:205], v[100:103]
	v_mfma_f32_16x16x32_bf16 v[96:99], v[136:139], v[202:205], v[96:99]
	v_mfma_f32_16x16x32_bf16 v[124:127], v[132:135], v[182:185], v[124:127]
	v_mfma_f32_16x16x32_bf16 v[120:123], v[158:161], v[182:185], v[120:123]
	v_mfma_f32_16x16x32_bf16 v[116:119], v[132:135], v[190:193], v[116:119]
	v_mfma_f32_16x16x32_bf16 v[112:115], v[158:161], v[190:193], v[112:115]
	v_mfma_f32_16x16x32_bf16 v[108:111], v[132:135], v[198:201], v[108:111]
	v_mfma_f32_16x16x32_bf16 v[104:107], v[158:161], v[198:201], v[104:107]
	v_mfma_f32_16x16x32_bf16 v[100:103], v[132:135], v[206:209], v[100:103]
	v_mfma_f32_16x16x32_bf16 v[96:99], v[158:161], v[206:209], v[96:99]
	s_setprio 0
	s_setprio 1
	v_mfma_f32_16x16x32_bf16 v[60:63], v[162:165], v[178:181], v[60:63]
	v_mfma_f32_16x16x32_bf16 v[56:59], v[170:173], v[178:181], v[56:59]
	v_mfma_f32_16x16x32_bf16 v[52:55], v[162:165], v[186:189], v[52:55]
	v_mfma_f32_16x16x32_bf16 v[48:51], v[170:173], v[186:189], v[48:51]
	v_mfma_f32_16x16x32_bf16 v[44:47], v[162:165], v[194:197], v[44:47]
	v_mfma_f32_16x16x32_bf16 v[40:43], v[170:173], v[194:197], v[40:43]
	v_mfma_f32_16x16x32_bf16 v[36:39], v[162:165], v[202:205], v[36:39]
	v_mfma_f32_16x16x32_bf16 v[32:35], v[170:173], v[202:205], v[32:35]
	v_mfma_f32_16x16x32_bf16 v[60:63], v[166:169], v[182:185], v[60:63]
	v_mfma_f32_16x16x32_bf16 v[56:59], v[174:177], v[182:185], v[56:59]
	v_mfma_f32_16x16x32_bf16 v[52:55], v[166:169], v[190:193], v[52:55]
	v_mfma_f32_16x16x32_bf16 v[48:51], v[174:177], v[190:193], v[48:51]
	s_barrier
	s_setprio 2
	v_mfma_f32_16x16x32_bf16 v[44:47], v[166:169], v[198:201], v[44:47]
	v_mfma_f32_16x16x32_bf16 v[40:43], v[174:177], v[198:201], v[40:43]
	v_mfma_f32_16x16x32_bf16 v[36:39], v[166:169], v[206:209], v[36:39]
	v_mfma_f32_16x16x32_bf16 v[32:35], v[174:177], v[206:209], v[32:35]
	s_setprio 0
	s_add_i32 s16, s27, s67
	v_lshl_add_u64 v[210:211], v[210:211], 0, s[8:9]
	s_mov_b32 m0, s16
	ds_read_b128 v[178:181], v217 offset:49152
	ds_read_b128 v[182:185], v217 offset:50176
	ds_read_b128 v[186:189], v217 offset:51200
	ds_read_b128 v[190:193], v217 offset:52224
	ds_read_b128 v[194:197], v217 offset:53248
	ds_read_b128 v[198:201], v217 offset:54272
	ds_read_b128 v[202:205], v217 offset:55296
	ds_read_b128 v[206:209], v217 offset:56320
	global_load_lds_dwordx4 v[210:211], off
	s_add_i32 m0, s16, 0x2000
	s_add_u32 s16, s20, 0x160080
	v_lshl_add_u64 v[210:211], v[212:213], 0, s[8:9]
	s_addc_u32 s17, s21, 0
	s_add_i32 s20, s72, s67
	global_load_lds_dwordx4 v[210:211], off
	v_lshl_add_u64 v[210:211], s[16:17], 0, v[142:143]
	s_mov_b32 m0, s20
	s_nop 0
	global_load_lds_dwordx4 v[210:211], off
	v_lshl_add_u64 v[210:211], s[16:17], 0, v[146:147]
	s_add_i32 m0, s20, 0x2000
	s_nop 0
	global_load_lds_dwordx4 v[210:211], off
	v_lshl_add_u64 v[210:211], v[220:221], 0, s[8:9]
	s_mov_b32 m0, s51
	s_nop 0
	global_load_lds_dwordx4 v[210:211], off
	v_lshl_add_u64 v[210:211], v[222:223], 0, s[8:9]
	s_mov_b32 m0, s52
	s_nop 0
	global_load_lds_dwordx4 v[210:211], off
	s_waitcnt vmcnt(8)
	s_waitcnt lgkmcnt(0)
	s_barrier
	s_setprio 1
	s_waitcnt lgkmcnt(0)
	v_mfma_f32_16x16x32_bf16 v[92:95], v[128:131], v[178:181], v[92:95]
	v_mfma_f32_16x16x32_bf16 v[88:91], v[136:139], v[178:181], v[88:91]
	v_mfma_f32_16x16x32_bf16 v[84:87], v[128:131], v[186:189], v[84:87]
	v_mfma_f32_16x16x32_bf16 v[80:83], v[136:139], v[186:189], v[80:83]
	v_mfma_f32_16x16x32_bf16 v[76:79], v[128:131], v[194:197], v[76:79]
	v_mfma_f32_16x16x32_bf16 v[72:75], v[136:139], v[194:197], v[72:75]
	v_mfma_f32_16x16x32_bf16 v[68:71], v[128:131], v[202:205], v[68:71]
	v_mfma_f32_16x16x32_bf16 v[64:67], v[136:139], v[202:205], v[64:67]
	v_mfma_f32_16x16x32_bf16 v[92:95], v[132:135], v[182:185], v[92:95]
	v_mfma_f32_16x16x32_bf16 v[88:91], v[158:161], v[182:185], v[88:91]
	v_mfma_f32_16x16x32_bf16 v[84:87], v[132:135], v[190:193], v[84:87]
	v_mfma_f32_16x16x32_bf16 v[80:83], v[158:161], v[190:193], v[80:83]
	v_mfma_f32_16x16x32_bf16 v[76:79], v[132:135], v[198:201], v[76:79]
	v_mfma_f32_16x16x32_bf16 v[72:75], v[158:161], v[198:201], v[72:75]
	v_mfma_f32_16x16x32_bf16 v[68:71], v[132:135], v[206:209], v[68:71]
	v_mfma_f32_16x16x32_bf16 v[64:67], v[158:161], v[206:209], v[64:67]
	s_setprio 0
	s_setprio 1
	v_mfma_f32_16x16x32_bf16 v[28:31], v[162:165], v[178:181], v[28:31]
	v_mfma_f32_16x16x32_bf16 v[24:27], v[170:173], v[178:181], v[24:27]
	v_mfma_f32_16x16x32_bf16 v[20:23], v[162:165], v[186:189], v[20:23]
	v_mfma_f32_16x16x32_bf16 v[16:19], v[170:173], v[186:189], v[16:19]
	v_mfma_f32_16x16x32_bf16 v[12:15], v[162:165], v[194:197], v[12:15]
	v_mfma_f32_16x16x32_bf16 v[8:11], v[170:173], v[194:197], v[8:11]
	v_mfma_f32_16x16x32_bf16 v[4:7], v[162:165], v[202:205], v[4:7]
	v_mfma_f32_16x16x32_bf16 v[0:3], v[170:173], v[202:205], v[0:3]
	v_mfma_f32_16x16x32_bf16 v[28:31], v[166:169], v[182:185], v[28:31]
	v_mfma_f32_16x16x32_bf16 v[24:27], v[174:177], v[182:185], v[24:27]
	v_mfma_f32_16x16x32_bf16 v[20:23], v[166:169], v[190:193], v[20:23]
	v_mfma_f32_16x16x32_bf16 v[16:19], v[174:177], v[190:193], v[16:19]
	s_barrier
	s_setprio 2
	v_mfma_f32_16x16x32_bf16 v[12:15], v[166:169], v[198:201], v[12:15]
	v_mfma_f32_16x16x32_bf16 v[8:11], v[174:177], v[198:201], v[8:11]
	v_mfma_f32_16x16x32_bf16 v[4:7], v[166:169], v[206:209], v[4:7]
	v_mfma_f32_16x16x32_bf16 v[0:3], v[174:177], v[206:209], v[0:3]
	s_setprio 0
	s_add_i32 s26, s26, 2
	s_add_u32 s24, s24, 0x100
	s_addc_u32 s25, s25, 0
	s_cmpk_gt_u32 s26, 0x55
	s_mov_b64 s[16:17], s[18:19]
	s_cbranch_scc0 .LBB0_1412
	s_and_b64 vcc, exec, s[10:11]
	s_cbranch_vccz .LBB0_1415
	s_barrier

.LBB0_1502:
	ds_read_b128 v[130:133], v177
	ds_read_b128 v[134:137], v177 offset:1024
	ds_read_b128 v[138:141], v177 offset:2048
	ds_read_b128 v[142:145], v177 offset:3072
	ds_read_b128 v[146:149], v179
	ds_read_b128 v[184:187], v179 offset:1024
	ds_read_b128 v[188:191], v179 offset:2048
	ds_read_b128 v[192:195], v179 offset:3072
	s_add_u32 s30, s28, 0xfff80080
	s_addc_u32 s31, s29, -1
	s_cmp_eq_u32 s60, 28
	s_cselect_b32 s35, s6, s31
	s_cselect_b32 s34, s21, s30
	s_cselect_b32 s31, s19, s59
	s_cselect_b32 s30, s27, s58
	v_lshl_add_u64 v[150:151], s[28:29], 0, v[166:167]
	s_add_i32 m0, s41, 0xc000
	ds_read_b128 v[196:199], v181
	ds_read_b128 v[200:203], v181 offset:1024
	ds_read_b128 v[204:207], v181 offset:2048
	ds_read_b128 v[208:211], v181 offset:3072
	ds_read_b128 v[212:215], v181 offset:4096
	ds_read_b128 v[216:219], v181 offset:5120
	ds_read_b128 v[220:223], v181 offset:6144
	ds_read_b128 v[224:227], v181 offset:7168
	global_load_lds_dwordx4 v[150:151], off
	v_lshl_add_u64 v[150:151], s[28:29], 0, v[164:165]
	s_add_i32 m0, s41, 0xe000
	s_nop 0
	global_load_lds_dwordx4 v[150:151], off
	s_waitcnt vmcnt(8)
	s_waitcnt lgkmcnt(0)
	s_barrier
	s_setprio 1
	s_waitcnt lgkmcnt(0)
	v_mfma_f32_16x16x32_bf16 v[124:127], v[130:133], v[196:199], v[124:127]
	v_mfma_f32_16x16x32_bf16 v[120:123], v[138:141], v[196:199], v[120:123]
	v_mfma_f32_16x16x32_bf16 v[108:111], v[130:133], v[204:207], v[108:111]
	v_mfma_f32_16x16x32_bf16 v[100:103], v[138:141], v[204:207], v[100:103]
	v_mfma_f32_16x16x32_bf16 v[92:95], v[130:133], v[212:215], v[92:95]
	v_mfma_f32_16x16x32_bf16 v[84:87], v[138:141], v[212:215], v[84:87]
	v_mfma_f32_16x16x32_bf16 v[76:79], v[130:133], v[220:223], v[76:79]
	v_mfma_f32_16x16x32_bf16 v[68:71], v[138:141], v[220:223], v[68:71]
	v_mfma_f32_16x16x32_bf16 v[124:127], v[134:137], v[200:203], v[124:127]
	v_mfma_f32_16x16x32_bf16 v[120:123], v[142:145], v[200:203], v[120:123]
	v_mfma_f32_16x16x32_bf16 v[108:111], v[134:137], v[208:211], v[108:111]
	v_mfma_f32_16x16x32_bf16 v[100:103], v[142:145], v[208:211], v[100:103]
	v_mfma_f32_16x16x32_bf16 v[92:95], v[134:137], v[216:219], v[92:95]
	v_mfma_f32_16x16x32_bf16 v[84:87], v[142:145], v[216:219], v[84:87]
	v_mfma_f32_16x16x32_bf16 v[76:79], v[134:137], v[224:227], v[76:79]
	v_mfma_f32_16x16x32_bf16 v[68:71], v[142:145], v[224:227], v[68:71]
	s_setprio 0
	s_setprio 1
	v_mfma_f32_16x16x32_bf16 v[116:119], v[146:149], v[196:199], v[116:119]
	v_mfma_f32_16x16x32_bf16 v[112:115], v[188:191], v[196:199], v[112:115]
	v_mfma_f32_16x16x32_bf16 v[104:107], v[146:149], v[204:207], v[104:107]
	v_mfma_f32_16x16x32_bf16 v[96:99], v[188:191], v[204:207], v[96:99]
	v_mfma_f32_16x16x32_bf16 v[88:91], v[146:149], v[212:215], v[88:91]
	v_mfma_f32_16x16x32_bf16 v[80:83], v[188:191], v[212:215], v[80:83]
	v_mfma_f32_16x16x32_bf16 v[72:75], v[146:149], v[220:223], v[72:75]
	v_mfma_f32_16x16x32_bf16 v[64:67], v[188:191], v[220:223], v[64:67]
	v_mfma_f32_16x16x32_bf16 v[116:119], v[184:187], v[200:203], v[116:119]
	v_mfma_f32_16x16x32_bf16 v[112:115], v[192:195], v[200:203], v[112:115]
	v_mfma_f32_16x16x32_bf16 v[104:107], v[184:187], v[208:211], v[104:107]
	v_mfma_f32_16x16x32_bf16 v[96:99], v[192:195], v[208:211], v[96:99]
	s_barrier
	s_setprio 2
	v_mfma_f32_16x16x32_bf16 v[88:91], v[184:187], v[216:219], v[88:91]
	v_mfma_f32_16x16x32_bf16 v[80:83], v[192:195], v[216:219], v[80:83]
	v_mfma_f32_16x16x32_bf16 v[72:75], v[184:187], v[224:227], v[72:75]
	v_mfma_f32_16x16x32_bf16 v[64:67], v[192:195], v[224:227], v[64:67]
	s_setprio 0
	s_add_i32 s61, s53, s67
	v_lshl_add_u64 v[150:151], s[30:31], 0, v[154:155]
	s_mov_b32 m0, s61
	ds_read_b128 v[196:199], v181 offset:16384
	ds_read_b128 v[200:203], v181 offset:17408
	ds_read_b128 v[204:207], v181 offset:18432
	ds_read_b128 v[208:211], v181 offset:19456
	ds_read_b128 v[212:215], v181 offset:20480
	ds_read_b128 v[216:219], v181 offset:21504
	ds_read_b128 v[220:223], v181 offset:22528
	ds_read_b128 v[224:227], v181 offset:23552
	global_load_lds_dwordx4 v[150:151], off
	s_add_i32 m0, s61, 0x2000
	s_add_u32 s62, s30, 0x80000
	v_lshl_add_u64 v[228:229], s[30:31], 0, v[158:159]
	s_addc_u32 s63, s31, 0
	s_add_i32 s61, s54, s67
	global_load_lds_dwordx4 v[228:229], off
	v_lshl_add_u64 v[230:231], s[62:63], 0, v[154:155]
	s_mov_b32 m0, s61
	v_lshl_add_u64 v[232:233], s[34:35], 0, v[156:157]
	global_load_lds_dwordx4 v[230:231], off
	v_lshl_add_u64 v[230:231], s[62:63], 0, v[158:159]
	s_add_i32 m0, s61, 0x2000
	s_nop 0
	global_load_lds_dwordx4 v[230:231], off
	v_lshl_add_u64 v[230:231], s[34:35], 0, v[152:153]
	s_mov_b32 m0, s41
	s_nop 0
	global_load_lds_dwordx4 v[230:231], off
	s_mov_b32 m0, s42
	s_nop 0
	global_load_lds_dwordx4 v[232:233], off
	s_waitcnt vmcnt(8)
	s_waitcnt lgkmcnt(0)
	s_barrier
	s_setprio 1
	s_waitcnt lgkmcnt(0)
	v_mfma_f32_16x16x32_bf16 v[60:63], v[130:133], v[196:199], v[60:63]
	v_mfma_f32_16x16x32_bf16 v[52:55], v[138:141], v[196:199], v[52:55]
	v_mfma_f32_16x16x32_bf16 v[44:47], v[130:133], v[204:207], v[44:47]
	v_mfma_f32_16x16x32_bf16 v[36:39], v[138:141], v[204:207], v[36:39]
	v_mfma_f32_16x16x32_bf16 v[28:31], v[130:133], v[212:215], v[28:31]
	v_mfma_f32_16x16x32_bf16 v[20:23], v[138:141], v[212:215], v[20:23]
	v_mfma_f32_16x16x32_bf16 v[12:15], v[130:133], v[220:223], v[12:15]
	v_mfma_f32_16x16x32_bf16 v[4:7], v[138:141], v[220:223], v[4:7]
	v_mfma_f32_16x16x32_bf16 v[60:63], v[134:137], v[200:203], v[60:63]
	v_mfma_f32_16x16x32_bf16 v[52:55], v[142:145], v[200:203], v[52:55]
	v_mfma_f32_16x16x32_bf16 v[44:47], v[134:137], v[208:211], v[44:47]
	v_mfma_f32_16x16x32_bf16 v[36:39], v[142:145], v[208:211], v[36:39]
	v_mfma_f32_16x16x32_bf16 v[28:31], v[134:137], v[216:219], v[28:31]
	v_mfma_f32_16x16x32_bf16 v[20:23], v[142:145], v[216:219], v[20:23]
	v_mfma_f32_16x16x32_bf16 v[12:15], v[134:137], v[224:227], v[12:15]
	v_mfma_f32_16x16x32_bf16 v[4:7], v[142:145], v[224:227], v[4:7]
	s_setprio 0
	s_setprio 1
	v_mfma_f32_16x16x32_bf16 v[56:59], v[146:149], v[196:199], v[56:59]
	v_mfma_f32_16x16x32_bf16 v[48:51], v[188:191], v[196:199], v[48:51]
	v_mfma_f32_16x16x32_bf16 v[40:43], v[146:149], v[204:207], v[40:43]
	v_mfma_f32_16x16x32_bf16 v[32:35], v[188:191], v[204:207], v[32:35]
	v_mfma_f32_16x16x32_bf16 v[24:27], v[146:149], v[212:215], v[24:27]
	v_mfma_f32_16x16x32_bf16 v[16:19], v[188:191], v[212:215], v[16:19]
	v_mfma_f32_16x16x32_bf16 v[8:11], v[146:149], v[220:223], v[8:11]
	v_mfma_f32_16x16x32_bf16 v[0:3], v[188:191], v[220:223], v[0:3]
	v_mfma_f32_16x16x32_bf16 v[56:59], v[184:187], v[200:203], v[56:59]
	v_mfma_f32_16x16x32_bf16 v[48:51], v[192:195], v[200:203], v[48:51]
	v_mfma_f32_16x16x32_bf16 v[40:43], v[184:187], v[208:211], v[40:43]
	v_mfma_f32_16x16x32_bf16 v[32:35], v[192:195], v[208:211], v[32:35]
	s_barrier
	s_setprio 2
	v_mfma_f32_16x16x32_bf16 v[24:27], v[184:187], v[216:219], v[24:27]
	v_mfma_f32_16x16x32_bf16 v[16:19], v[192:195], v[216:219], v[16:19]
	v_mfma_f32_16x16x32_bf16 v[8:11], v[184:187], v[224:227], v[8:11]
	v_mfma_f32_16x16x32_bf16 v[0:3], v[192:195], v[224:227], v[0:3]
	s_setprio 0
	s_add_i32 s61, 0, 0x18000
	v_add_u32_e32 v129, s61, v173
	s_add_i32 s62, 0, 0x1c000
	ds_read_b128 v[130:133], v129
	ds_read_b128 v[134:137], v129 offset:1024
	ds_read_b128 v[138:141], v129 offset:2048
	ds_read_b128 v[142:145], v129 offset:3072
	v_add_u32_e32 v129, s62, v173
	ds_read_b128 v[146:149], v129
	ds_read_b128 v[184:187], v129 offset:1024
	ds_read_b128 v[188:191], v129 offset:2048
	ds_read_b128 v[192:195], v129 offset:3072
	s_add_u32 s34, s34, 0x80000
	s_addc_u32 s35, s35, 0
	s_mov_b32 m0, s43
	v_lshl_add_u64 v[234:235], s[34:35], 0, v[152:153]
	ds_read_b128 v[196:199], v181 offset:32768
	ds_read_b128 v[200:203], v181 offset:33792
	ds_read_b128 v[204:207], v181 offset:34816
	ds_read_b128 v[208:211], v181 offset:35840
	ds_read_b128 v[212:215], v181 offset:36864
	ds_read_b128 v[216:219], v181 offset:37888
	ds_read_b128 v[220:223], v181 offset:38912
	ds_read_b128 v[224:227], v181 offset:39936
	global_load_lds_dwordx4 v[234:235], off
	v_lshl_add_u64 v[234:235], s[34:35], 0, v[156:157]
	s_mov_b32 m0, s44
	s_nop 0
	global_load_lds_dwordx4 v[234:235], off
	s_waitcnt vmcnt(8)
	s_waitcnt lgkmcnt(0)
	s_barrier
	s_setprio 1
	s_waitcnt lgkmcnt(0)
	v_mfma_f32_16x16x32_bf16 v[124:127], v[130:133], v[196:199], v[124:127]
	v_mfma_f32_16x16x32_bf16 v[120:123], v[138:141], v[196:199], v[120:123]
	v_mfma_f32_16x16x32_bf16 v[108:111], v[130:133], v[204:207], v[108:111]
	v_mfma_f32_16x16x32_bf16 v[100:103], v[138:141], v[204:207], v[100:103]
	v_mfma_f32_16x16x32_bf16 v[92:95], v[130:133], v[212:215], v[92:95]
	v_mfma_f32_16x16x32_bf16 v[84:87], v[138:141], v[212:215], v[84:87]
	v_mfma_f32_16x16x32_bf16 v[76:79], v[130:133], v[220:223], v[76:79]
	v_mfma_f32_16x16x32_bf16 v[68:71], v[138:141], v[220:223], v[68:71]
	v_mfma_f32_16x16x32_bf16 v[124:127], v[134:137], v[200:203], v[124:127]
	v_mfma_f32_16x16x32_bf16 v[120:123], v[142:145], v[200:203], v[120:123]
	v_mfma_f32_16x16x32_bf16 v[108:111], v[134:137], v[208:211], v[108:111]
	v_mfma_f32_16x16x32_bf16 v[100:103], v[142:145], v[208:211], v[100:103]
	v_mfma_f32_16x16x32_bf16 v[92:95], v[134:137], v[216:219], v[92:95]
	v_mfma_f32_16x16x32_bf16 v[84:87], v[142:145], v[216:219], v[84:87]
	v_mfma_f32_16x16x32_bf16 v[76:79], v[134:137], v[224:227], v[76:79]
	v_mfma_f32_16x16x32_bf16 v[68:71], v[142:145], v[224:227], v[68:71]
	s_setprio 0
	s_setprio 1
	v_mfma_f32_16x16x32_bf16 v[116:119], v[146:149], v[196:199], v[116:119]
	v_mfma_f32_16x16x32_bf16 v[112:115], v[188:191], v[196:199], v[112:115]
	v_mfma_f32_16x16x32_bf16 v[104:107], v[146:149], v[204:207], v[104:107]
	v_mfma_f32_16x16x32_bf16 v[96:99], v[188:191], v[204:207], v[96:99]
	v_mfma_f32_16x16x32_bf16 v[88:91], v[146:149], v[212:215], v[88:91]
	v_mfma_f32_16x16x32_bf16 v[80:83], v[188:191], v[212:215], v[80:83]
	v_mfma_f32_16x16x32_bf16 v[72:75], v[146:149], v[220:223], v[72:75]
	v_mfma_f32_16x16x32_bf16 v[64:67], v[188:191], v[220:223], v[64:67]
	v_mfma_f32_16x16x32_bf16 v[116:119], v[184:187], v[200:203], v[116:119]
	v_mfma_f32_16x16x32_bf16 v[112:115], v[192:195], v[200:203], v[112:115]
	v_mfma_f32_16x16x32_bf16 v[104:107], v[184:187], v[208:211], v[104:107]
	v_mfma_f32_16x16x32_bf16 v[96:99], v[192:195], v[208:211], v[96:99]
	s_barrier
	s_setprio 2
	v_mfma_f32_16x16x32_bf16 v[88:91], v[184:187], v[216:219], v[88:91]
	v_mfma_f32_16x16x32_bf16 v[80:83], v[192:195], v[216:219], v[80:83]
	v_mfma_f32_16x16x32_bf16 v[72:75], v[184:187], v[224:227], v[72:75]
	v_mfma_f32_16x16x32_bf16 v[64:67], v[192:195], v[224:227], v[64:67]
	s_setprio 0
	s_add_i32 s34, s61, s67
	v_lshl_add_u64 v[150:151], v[150:151], 0, s[12:13]
	s_mov_b32 m0, s34
	ds_read_b128 v[196:199], v181 offset:49152
	ds_read_b128 v[200:203], v181 offset:50176
	ds_read_b128 v[204:207], v181 offset:51200
	ds_read_b128 v[208:211], v181 offset:52224
	ds_read_b128 v[212:215], v181 offset:53248
	ds_read_b128 v[216:219], v181 offset:54272
	ds_read_b128 v[220:223], v181 offset:55296
	ds_read_b128 v[224:227], v181 offset:56320
	global_load_lds_dwordx4 v[150:151], off
	s_add_i32 m0, s34, 0x2000
	s_add_u32 s30, s30, 0x80080
	v_lshl_add_u64 v[150:151], v[228:229], 0, s[12:13]
	s_addc_u32 s31, s31, 0
	s_add_i32 s34, s62, s67
	global_load_lds_dwordx4 v[150:151], off
	v_lshl_add_u64 v[150:151], s[30:31], 0, v[154:155]
	s_mov_b32 m0, s34
	s_nop 0
	global_load_lds_dwordx4 v[150:151], off
	v_lshl_add_u64 v[150:151], s[30:31], 0, v[158:159]
	s_add_i32 m0, s34, 0x2000
	s_nop 0
	global_load_lds_dwordx4 v[150:151], off
	v_lshl_add_u64 v[150:151], v[230:231], 0, s[12:13]
	s_mov_b32 m0, s47
	s_nop 0
	global_load_lds_dwordx4 v[150:151], off
	v_lshl_add_u64 v[150:151], v[232:233], 0, s[12:13]
	s_mov_b32 m0, s48
	s_nop 0
	global_load_lds_dwordx4 v[150:151], off
	s_waitcnt vmcnt(8)
	s_waitcnt lgkmcnt(0)
	s_barrier
	s_setprio 1
	s_waitcnt lgkmcnt(0)
	v_mfma_f32_16x16x32_bf16 v[60:63], v[130:133], v[196:199], v[60:63]
	v_mfma_f32_16x16x32_bf16 v[52:55], v[138:141], v[196:199], v[52:55]
	v_mfma_f32_16x16x32_bf16 v[44:47], v[130:133], v[204:207], v[44:47]
	v_mfma_f32_16x16x32_bf16 v[36:39], v[138:141], v[204:207], v[36:39]
	v_mfma_f32_16x16x32_bf16 v[28:31], v[130:133], v[212:215], v[28:31]
	v_mfma_f32_16x16x32_bf16 v[20:23], v[138:141], v[212:215], v[20:23]
	v_mfma_f32_16x16x32_bf16 v[12:15], v[130:133], v[220:223], v[12:15]
	v_mfma_f32_16x16x32_bf16 v[4:7], v[138:141], v[220:223], v[4:7]
	v_mfma_f32_16x16x32_bf16 v[60:63], v[134:137], v[200:203], v[60:63]
	v_mfma_f32_16x16x32_bf16 v[52:55], v[142:145], v[200:203], v[52:55]
	v_mfma_f32_16x16x32_bf16 v[44:47], v[134:137], v[208:211], v[44:47]
	v_mfma_f32_16x16x32_bf16 v[36:39], v[142:145], v[208:211], v[36:39]
	v_mfma_f32_16x16x32_bf16 v[28:31], v[134:137], v[216:219], v[28:31]
	v_mfma_f32_16x16x32_bf16 v[20:23], v[142:145], v[216:219], v[20:23]
	v_mfma_f32_16x16x32_bf16 v[12:15], v[134:137], v[224:227], v[12:15]
	v_mfma_f32_16x16x32_bf16 v[4:7], v[142:145], v[224:227], v[4:7]
	s_setprio 0
	s_setprio 1
	v_mfma_f32_16x16x32_bf16 v[56:59], v[146:149], v[196:199], v[56:59]
	v_mfma_f32_16x16x32_bf16 v[48:51], v[188:191], v[196:199], v[48:51]
	v_mfma_f32_16x16x32_bf16 v[40:43], v[146:149], v[204:207], v[40:43]
	v_mfma_f32_16x16x32_bf16 v[32:35], v[188:191], v[204:207], v[32:35]
	v_mfma_f32_16x16x32_bf16 v[24:27], v[146:149], v[212:215], v[24:27]
	v_mfma_f32_16x16x32_bf16 v[16:19], v[188:191], v[212:215], v[16:19]
	v_mfma_f32_16x16x32_bf16 v[8:11], v[146:149], v[220:223], v[8:11]
	v_mfma_f32_16x16x32_bf16 v[0:3], v[188:191], v[220:223], v[0:3]
	v_mfma_f32_16x16x32_bf16 v[56:59], v[184:187], v[200:203], v[56:59]
	v_mfma_f32_16x16x32_bf16 v[48:51], v[192:195], v[200:203], v[48:51]
	v_mfma_f32_16x16x32_bf16 v[40:43], v[184:187], v[208:211], v[40:43]
	v_mfma_f32_16x16x32_bf16 v[32:35], v[192:195], v[208:211], v[32:35]
	s_barrier
	s_setprio 2
	v_mfma_f32_16x16x32_bf16 v[24:27], v[184:187], v[216:219], v[24:27]
	v_mfma_f32_16x16x32_bf16 v[16:19], v[192:195], v[216:219], v[16:19]
	v_mfma_f32_16x16x32_bf16 v[8:11], v[184:187], v[224:227], v[8:11]
	v_mfma_f32_16x16x32_bf16 v[0:3], v[192:195], v[224:227], v[0:3]
	s_setprio 0
	s_add_i32 s60, s60, 2
	s_add_u32 s58, s58, 0x100
	s_addc_u32 s59, s59, 0
	s_add_u32 s28, s28, 0x100
	s_addc_u32 s29, s29, 0
	s_cmp_gt_u32 s60, 29
	s_cbranch_scc0 .LBB0_1502
	s_and_b64 vcc, exec, s[14:15]
	s_cbranch_vccz .LBB0_1505
	s_barrier

.LBB0_1661:
	ds_read_b128 v[128:131], v243
	ds_read_b128 v[132:135], v243 offset:1024
	ds_read_b128 v[136:139], v243 offset:2048
	ds_read_b128 v[140:143], v243 offset:3072
	ds_read_b128 v[144:147], v244
	ds_read_b128 v[148:151], v244 offset:1024
	ds_read_b128 v[152:155], v244 offset:2048
	ds_read_b128 v[156:159], v244 offset:3072
	s_add_u32 s26, s24, 0xfff80080
	s_addc_u32 s27, s25, -1
	s_cmp_eq_u32 s75, 28
	s_cselect_b32 s29, s3, s27
	s_cselect_b32 s28, s5, s26
	s_cselect_b32 s27, s17, s31
	s_cselect_b32 s26, s19, s30
	v_lshl_add_u64 v[210:211], s[24:25], 0, v[180:181]
	s_add_i32 m0, s38, 0xc000
	ds_read_b128 v[160:163], v245
	ds_read_b128 v[164:167], v245 offset:1024
	ds_read_b128 v[186:189], v245 offset:2048
	ds_read_b128 v[190:193], v245 offset:3072
	ds_read_b128 v[194:197], v245 offset:4096
	ds_read_b128 v[198:201], v245 offset:5120
	ds_read_b128 v[202:205], v245 offset:6144
	ds_read_b128 v[206:209], v245 offset:7168
	global_load_lds_dwordx4 v[210:211], off
	v_lshl_add_u64 v[210:211], s[24:25], 0, v[178:179]
	s_add_i32 m0, s38, 0xe000
	s_nop 0
	global_load_lds_dwordx4 v[210:211], off
	s_waitcnt vmcnt(8)
	s_waitcnt lgkmcnt(0)
	s_barrier
	s_setprio 1
	s_waitcnt lgkmcnt(0)
	v_mfma_f32_16x16x32_bf16 v[124:127], v[128:131], v[160:163], v[124:127]
	v_mfma_f32_16x16x32_bf16 v[120:123], v[136:139], v[160:163], v[120:123]
	v_mfma_f32_16x16x32_bf16 v[116:119], v[128:131], v[186:189], v[116:119]
	v_mfma_f32_16x16x32_bf16 v[112:115], v[136:139], v[186:189], v[112:115]
	v_mfma_f32_16x16x32_bf16 v[108:111], v[128:131], v[194:197], v[108:111]
	v_mfma_f32_16x16x32_bf16 v[104:107], v[136:139], v[194:197], v[104:107]
	v_mfma_f32_16x16x32_bf16 v[100:103], v[128:131], v[202:205], v[100:103]
	v_mfma_f32_16x16x32_bf16 v[96:99], v[136:139], v[202:205], v[96:99]
	v_mfma_f32_16x16x32_bf16 v[124:127], v[132:135], v[164:167], v[124:127]
	v_mfma_f32_16x16x32_bf16 v[120:123], v[140:143], v[164:167], v[120:123]
	v_mfma_f32_16x16x32_bf16 v[116:119], v[132:135], v[190:193], v[116:119]
	v_mfma_f32_16x16x32_bf16 v[112:115], v[140:143], v[190:193], v[112:115]
	v_mfma_f32_16x16x32_bf16 v[108:111], v[132:135], v[198:201], v[108:111]
	v_mfma_f32_16x16x32_bf16 v[104:107], v[140:143], v[198:201], v[104:107]
	v_mfma_f32_16x16x32_bf16 v[100:103], v[132:135], v[206:209], v[100:103]
	v_mfma_f32_16x16x32_bf16 v[96:99], v[140:143], v[206:209], v[96:99]
	s_setprio 0
	s_setprio 1
	v_mfma_f32_16x16x32_bf16 v[60:63], v[144:147], v[160:163], v[60:63]
	v_mfma_f32_16x16x32_bf16 v[56:59], v[152:155], v[160:163], v[56:59]
	v_mfma_f32_16x16x32_bf16 v[52:55], v[144:147], v[186:189], v[52:55]
	v_mfma_f32_16x16x32_bf16 v[48:51], v[152:155], v[186:189], v[48:51]
	v_mfma_f32_16x16x32_bf16 v[44:47], v[144:147], v[194:197], v[44:47]
	v_mfma_f32_16x16x32_bf16 v[40:43], v[152:155], v[194:197], v[40:43]
	v_mfma_f32_16x16x32_bf16 v[36:39], v[144:147], v[202:205], v[36:39]
	v_mfma_f32_16x16x32_bf16 v[32:35], v[152:155], v[202:205], v[32:35]
	v_mfma_f32_16x16x32_bf16 v[60:63], v[148:151], v[164:167], v[60:63]
	v_mfma_f32_16x16x32_bf16 v[56:59], v[156:159], v[164:167], v[56:59]
	v_mfma_f32_16x16x32_bf16 v[52:55], v[148:151], v[190:193], v[52:55]
	v_mfma_f32_16x16x32_bf16 v[48:51], v[156:159], v[190:193], v[48:51]
	s_barrier
	s_setprio 2
	v_mfma_f32_16x16x32_bf16 v[44:47], v[148:151], v[198:201], v[44:47]
	v_mfma_f32_16x16x32_bf16 v[40:43], v[156:159], v[198:201], v[40:43]
	v_mfma_f32_16x16x32_bf16 v[36:39], v[148:151], v[206:209], v[36:39]
	v_mfma_f32_16x16x32_bf16 v[32:35], v[156:159], v[206:209], v[32:35]
	s_setprio 0
	s_add_i32 s76, s62, s67
	v_lshl_add_u64 v[210:211], s[26:27], 0, v[170:171]
	s_mov_b32 m0, s76
	ds_read_b128 v[160:163], v245 offset:16384
	ds_read_b128 v[164:167], v245 offset:17408
	ds_read_b128 v[186:189], v245 offset:18432
	ds_read_b128 v[190:193], v245 offset:19456
	ds_read_b128 v[194:197], v245 offset:20480
	ds_read_b128 v[198:201], v245 offset:21504
	ds_read_b128 v[202:205], v245 offset:22528
	ds_read_b128 v[206:209], v245 offset:23552
	global_load_lds_dwordx4 v[210:211], off
	s_add_i32 m0, s76, 0x2000
	s_add_u32 s76, s26, 0x80000
	v_lshl_add_u64 v[212:213], s[26:27], 0, v[174:175]
	s_addc_u32 s77, s27, 0
	s_add_i32 s78, s63, s67
	global_load_lds_dwordx4 v[212:213], off
	v_lshl_add_u64 v[214:215], s[76:77], 0, v[170:171]
	s_mov_b32 m0, s78
	v_lshl_add_u64 v[216:217], s[28:29], 0, v[172:173]
	global_load_lds_dwordx4 v[214:215], off
	v_lshl_add_u64 v[214:215], s[76:77], 0, v[174:175]
	s_add_i32 m0, s78, 0x2000
	s_nop 0
	global_load_lds_dwordx4 v[214:215], off
	v_lshl_add_u64 v[214:215], s[28:29], 0, v[168:169]
	s_mov_b32 m0, s38
	s_nop 0
	global_load_lds_dwordx4 v[214:215], off
	s_mov_b32 m0, s39
	s_nop 0
	global_load_lds_dwordx4 v[216:217], off
	s_waitcnt vmcnt(8)
	s_waitcnt lgkmcnt(0)
	s_barrier
	s_setprio 1
	s_waitcnt lgkmcnt(0)
	v_mfma_f32_16x16x32_bf16 v[92:95], v[128:131], v[160:163], v[92:95]
	v_mfma_f32_16x16x32_bf16 v[88:91], v[136:139], v[160:163], v[88:91]
	v_mfma_f32_16x16x32_bf16 v[84:87], v[128:131], v[186:189], v[84:87]
	v_mfma_f32_16x16x32_bf16 v[80:83], v[136:139], v[186:189], v[80:83]
	v_mfma_f32_16x16x32_bf16 v[76:79], v[128:131], v[194:197], v[76:79]
	v_mfma_f32_16x16x32_bf16 v[72:75], v[136:139], v[194:197], v[72:75]
	v_mfma_f32_16x16x32_bf16 v[68:71], v[128:131], v[202:205], v[68:71]
	v_mfma_f32_16x16x32_bf16 v[64:67], v[136:139], v[202:205], v[64:67]
	v_mfma_f32_16x16x32_bf16 v[92:95], v[132:135], v[164:167], v[92:95]
	v_mfma_f32_16x16x32_bf16 v[88:91], v[140:143], v[164:167], v[88:91]
	v_mfma_f32_16x16x32_bf16 v[84:87], v[132:135], v[190:193], v[84:87]
	v_mfma_f32_16x16x32_bf16 v[80:83], v[140:143], v[190:193], v[80:83]
	v_mfma_f32_16x16x32_bf16 v[76:79], v[132:135], v[198:201], v[76:79]
	v_mfma_f32_16x16x32_bf16 v[72:75], v[140:143], v[198:201], v[72:75]
	v_mfma_f32_16x16x32_bf16 v[68:71], v[132:135], v[206:209], v[68:71]
	v_mfma_f32_16x16x32_bf16 v[64:67], v[140:143], v[206:209], v[64:67]
	s_setprio 0
	s_setprio 1
	v_mfma_f32_16x16x32_bf16 v[28:31], v[144:147], v[160:163], v[28:31]
	v_mfma_f32_16x16x32_bf16 v[24:27], v[152:155], v[160:163], v[24:27]
	v_mfma_f32_16x16x32_bf16 v[20:23], v[144:147], v[186:189], v[20:23]
	v_mfma_f32_16x16x32_bf16 v[16:19], v[152:155], v[186:189], v[16:19]
	v_mfma_f32_16x16x32_bf16 v[12:15], v[144:147], v[194:197], v[12:15]
	v_mfma_f32_16x16x32_bf16 v[8:11], v[152:155], v[194:197], v[8:11]
	v_mfma_f32_16x16x32_bf16 v[4:7], v[144:147], v[202:205], v[4:7]
	v_mfma_f32_16x16x32_bf16 v[0:3], v[152:155], v[202:205], v[0:3]
	v_mfma_f32_16x16x32_bf16 v[28:31], v[148:151], v[164:167], v[28:31]
	v_mfma_f32_16x16x32_bf16 v[24:27], v[156:159], v[164:167], v[24:27]
	v_mfma_f32_16x16x32_bf16 v[20:23], v[148:151], v[190:193], v[20:23]
	v_mfma_f32_16x16x32_bf16 v[16:19], v[156:159], v[190:193], v[16:19]
	s_barrier
	s_setprio 2
	v_mfma_f32_16x16x32_bf16 v[12:15], v[148:151], v[198:201], v[12:15]
	v_mfma_f32_16x16x32_bf16 v[8:11], v[156:159], v[198:201], v[8:11]
	v_mfma_f32_16x16x32_bf16 v[4:7], v[148:151], v[206:209], v[4:7]
	v_mfma_f32_16x16x32_bf16 v[0:3], v[156:159], v[206:209], v[0:3]
	s_setprio 0
	s_add_i32 s76, 0, 0x18000
	s_add_i32 s77, 0, 0x1c000
	v_add_u32_e32 v140, s76, v242
	v_add_u32_e32 v156, s77, v242
	ds_read_b128 v[128:131], v140
	ds_read_b128 v[132:135], v140 offset:1024
	ds_read_b128 v[136:139], v140 offset:2048
	ds_read_b128 v[140:143], v140 offset:3072
	ds_read_b128 v[144:147], v156
	ds_read_b128 v[148:151], v156 offset:1024
	ds_read_b128 v[152:155], v156 offset:2048
	ds_read_b128 v[156:159], v156 offset:3072
	s_add_u32 s28, s28, 0x80000
	s_addc_u32 s29, s29, 0
	s_mov_b32 m0, s40
	v_lshl_add_u64 v[218:219], s[28:29], 0, v[168:169]
	ds_read_b128 v[160:163], v245 offset:32768
	ds_read_b128 v[164:167], v245 offset:33792
	ds_read_b128 v[186:189], v245 offset:34816
	ds_read_b128 v[190:193], v245 offset:35840
	ds_read_b128 v[194:197], v245 offset:36864
	ds_read_b128 v[198:201], v245 offset:37888
	ds_read_b128 v[202:205], v245 offset:38912
	ds_read_b128 v[206:209], v245 offset:39936
	global_load_lds_dwordx4 v[218:219], off
	v_lshl_add_u64 v[218:219], s[28:29], 0, v[172:173]
	s_mov_b32 m0, s41
	s_nop 0
	global_load_lds_dwordx4 v[218:219], off
	s_waitcnt vmcnt(8)
	s_waitcnt lgkmcnt(0)
	s_barrier
	s_setprio 1
	s_waitcnt lgkmcnt(0)
	v_mfma_f32_16x16x32_bf16 v[124:127], v[128:131], v[160:163], v[124:127]
	v_mfma_f32_16x16x32_bf16 v[120:123], v[136:139], v[160:163], v[120:123]
	v_mfma_f32_16x16x32_bf16 v[116:119], v[128:131], v[186:189], v[116:119]
	v_mfma_f32_16x16x32_bf16 v[112:115], v[136:139], v[186:189], v[112:115]
	v_mfma_f32_16x16x32_bf16 v[108:111], v[128:131], v[194:197], v[108:111]
	v_mfma_f32_16x16x32_bf16 v[104:107], v[136:139], v[194:197], v[104:107]
	v_mfma_f32_16x16x32_bf16 v[100:103], v[128:131], v[202:205], v[100:103]
	v_mfma_f32_16x16x32_bf16 v[96:99], v[136:139], v[202:205], v[96:99]
	v_mfma_f32_16x16x32_bf16 v[124:127], v[132:135], v[164:167], v[124:127]
	v_mfma_f32_16x16x32_bf16 v[120:123], v[140:143], v[164:167], v[120:123]
	v_mfma_f32_16x16x32_bf16 v[116:119], v[132:135], v[190:193], v[116:119]
	v_mfma_f32_16x16x32_bf16 v[112:115], v[140:143], v[190:193], v[112:115]
	v_mfma_f32_16x16x32_bf16 v[108:111], v[132:135], v[198:201], v[108:111]
	v_mfma_f32_16x16x32_bf16 v[104:107], v[140:143], v[198:201], v[104:107]
	v_mfma_f32_16x16x32_bf16 v[100:103], v[132:135], v[206:209], v[100:103]
	v_mfma_f32_16x16x32_bf16 v[96:99], v[140:143], v[206:209], v[96:99]
	s_setprio 0
	s_setprio 1
	v_mfma_f32_16x16x32_bf16 v[60:63], v[144:147], v[160:163], v[60:63]
	v_mfma_f32_16x16x32_bf16 v[56:59], v[152:155], v[160:163], v[56:59]
	v_mfma_f32_16x16x32_bf16 v[52:55], v[144:147], v[186:189], v[52:55]
	v_mfma_f32_16x16x32_bf16 v[48:51], v[152:155], v[186:189], v[48:51]
	v_mfma_f32_16x16x32_bf16 v[44:47], v[144:147], v[194:197], v[44:47]
	v_mfma_f32_16x16x32_bf16 v[40:43], v[152:155], v[194:197], v[40:43]
	v_mfma_f32_16x16x32_bf16 v[36:39], v[144:147], v[202:205], v[36:39]
	v_mfma_f32_16x16x32_bf16 v[32:35], v[152:155], v[202:205], v[32:35]
	v_mfma_f32_16x16x32_bf16 v[60:63], v[148:151], v[164:167], v[60:63]
	v_mfma_f32_16x16x32_bf16 v[56:59], v[156:159], v[164:167], v[56:59]
	v_mfma_f32_16x16x32_bf16 v[52:55], v[148:151], v[190:193], v[52:55]
	v_mfma_f32_16x16x32_bf16 v[48:51], v[156:159], v[190:193], v[48:51]
	s_barrier
	s_setprio 2
	v_mfma_f32_16x16x32_bf16 v[44:47], v[148:151], v[198:201], v[44:47]
	v_mfma_f32_16x16x32_bf16 v[40:43], v[156:159], v[198:201], v[40:43]
	v_mfma_f32_16x16x32_bf16 v[36:39], v[148:151], v[206:209], v[36:39]
	v_mfma_f32_16x16x32_bf16 v[32:35], v[156:159], v[206:209], v[32:35]
	s_setprio 0
	s_add_i32 s28, s76, s67
	v_lshl_add_u64 v[210:211], v[210:211], 0, s[8:9]
	s_mov_b32 m0, s28
	ds_read_b128 v[160:163], v245 offset:49152
	ds_read_b128 v[164:167], v245 offset:50176
	ds_read_b128 v[186:189], v245 offset:51200
	ds_read_b128 v[190:193], v245 offset:52224
	ds_read_b128 v[194:197], v245 offset:53248
	ds_read_b128 v[198:201], v245 offset:54272
	ds_read_b128 v[202:205], v245 offset:55296
	ds_read_b128 v[206:209], v245 offset:56320
	global_load_lds_dwordx4 v[210:211], off
	s_add_i32 m0, s28, 0x2000
	s_add_u32 s26, s26, 0x80080
	v_lshl_add_u64 v[210:211], v[212:213], 0, s[8:9]
	s_addc_u32 s27, s27, 0
	s_add_i32 s28, s77, s67
	global_load_lds_dwordx4 v[210:211], off
	v_lshl_add_u64 v[210:211], s[26:27], 0, v[170:171]
	s_mov_b32 m0, s28
	s_nop 0
	global_load_lds_dwordx4 v[210:211], off
	v_lshl_add_u64 v[210:211], s[26:27], 0, v[174:175]
	s_add_i32 m0, s28, 0x2000
	s_nop 0
	global_load_lds_dwordx4 v[210:211], off
	v_lshl_add_u64 v[210:211], v[214:215], 0, s[8:9]
	s_mov_b32 m0, s55
	s_nop 0
	global_load_lds_dwordx4 v[210:211], off
	v_lshl_add_u64 v[210:211], v[216:217], 0, s[8:9]
	s_mov_b32 m0, s56
	s_nop 0
	global_load_lds_dwordx4 v[210:211], off
	s_waitcnt vmcnt(8)
	s_waitcnt lgkmcnt(0)
	s_barrier
	s_setprio 1
	s_waitcnt lgkmcnt(0)
	v_mfma_f32_16x16x32_bf16 v[92:95], v[128:131], v[160:163], v[92:95]
	v_mfma_f32_16x16x32_bf16 v[88:91], v[136:139], v[160:163], v[88:91]
	v_mfma_f32_16x16x32_bf16 v[84:87], v[128:131], v[186:189], v[84:87]
	v_mfma_f32_16x16x32_bf16 v[80:83], v[136:139], v[186:189], v[80:83]
	v_mfma_f32_16x16x32_bf16 v[76:79], v[128:131], v[194:197], v[76:79]
	v_mfma_f32_16x16x32_bf16 v[72:75], v[136:139], v[194:197], v[72:75]
	v_mfma_f32_16x16x32_bf16 v[68:71], v[128:131], v[202:205], v[68:71]
	v_mfma_f32_16x16x32_bf16 v[64:67], v[136:139], v[202:205], v[64:67]
	v_mfma_f32_16x16x32_bf16 v[92:95], v[132:135], v[164:167], v[92:95]
	v_mfma_f32_16x16x32_bf16 v[88:91], v[140:143], v[164:167], v[88:91]
	v_mfma_f32_16x16x32_bf16 v[84:87], v[132:135], v[190:193], v[84:87]
	v_mfma_f32_16x16x32_bf16 v[80:83], v[140:143], v[190:193], v[80:83]
	v_mfma_f32_16x16x32_bf16 v[76:79], v[132:135], v[198:201], v[76:79]
	v_mfma_f32_16x16x32_bf16 v[72:75], v[140:143], v[198:201], v[72:75]
	v_mfma_f32_16x16x32_bf16 v[68:71], v[132:135], v[206:209], v[68:71]
	v_mfma_f32_16x16x32_bf16 v[64:67], v[140:143], v[206:209], v[64:67]
	s_setprio 0
	s_setprio 1
	v_mfma_f32_16x16x32_bf16 v[28:31], v[144:147], v[160:163], v[28:31]
	v_mfma_f32_16x16x32_bf16 v[24:27], v[152:155], v[160:163], v[24:27]
	v_mfma_f32_16x16x32_bf16 v[20:23], v[144:147], v[186:189], v[20:23]
	v_mfma_f32_16x16x32_bf16 v[16:19], v[152:155], v[186:189], v[16:19]
	v_mfma_f32_16x16x32_bf16 v[12:15], v[144:147], v[194:197], v[12:15]
	v_mfma_f32_16x16x32_bf16 v[8:11], v[152:155], v[194:197], v[8:11]
	v_mfma_f32_16x16x32_bf16 v[4:7], v[144:147], v[202:205], v[4:7]
	v_mfma_f32_16x16x32_bf16 v[0:3], v[152:155], v[202:205], v[0:3]
	v_mfma_f32_16x16x32_bf16 v[28:31], v[148:151], v[164:167], v[28:31]
	v_mfma_f32_16x16x32_bf16 v[24:27], v[156:159], v[164:167], v[24:27]
	v_mfma_f32_16x16x32_bf16 v[20:23], v[148:151], v[190:193], v[20:23]
	v_mfma_f32_16x16x32_bf16 v[16:19], v[156:159], v[190:193], v[16:19]
	s_barrier
	s_setprio 2
	v_mfma_f32_16x16x32_bf16 v[12:15], v[148:151], v[198:201], v[12:15]
	v_mfma_f32_16x16x32_bf16 v[8:11], v[156:159], v[198:201], v[8:11]
	v_mfma_f32_16x16x32_bf16 v[4:7], v[148:151], v[206:209], v[4:7]
	v_mfma_f32_16x16x32_bf16 v[0:3], v[156:159], v[206:209], v[0:3]
	s_setprio 0
	s_add_i32 s75, s75, 2
	s_add_u32 s30, s30, 0x100
	s_addc_u32 s31, s31, 0
	s_add_u32 s24, s24, 0x100
	s_addc_u32 s25, s25, 0
	s_cmp_gt_u32 s75, 29
	s_cbranch_scc0 .LBB0_1661
	s_and_b64 vcc, exec, s[10:11]
	s_cbranch_vccz .LBB0_1664
	s_barrier

.LBB0_1979:
	ds_read_b128 v[130:133], v185
	ds_read_b128 v[134:137], v185 offset:1024
	ds_read_b128 v[138:141], v185 offset:2048
	ds_read_b128 v[142:145], v185 offset:3072
	ds_read_b128 v[146:149], v187
	ds_read_b128 v[150:153], v187 offset:1024
	ds_read_b128 v[154:157], v187 offset:2048
	ds_read_b128 v[192:195], v187 offset:3072
	s_add_u32 s30, s28, 0xfff80080
	s_addc_u32 s31, s29, -1
	s_cmp_eq_u32 s61, 28
	s_cselect_b32 s35, s6, s31
	s_cselect_b32 s34, s21, s30
	s_cselect_b32 s31, s19, s60
	s_cselect_b32 s30, s58, s59
	v_lshl_add_u64 v[158:159], s[28:29], 0, v[174:175]
	s_add_i32 m0, s27, 0xc000
	ds_read_b128 v[196:199], v189
	ds_read_b128 v[200:203], v189 offset:1024
	ds_read_b128 v[204:207], v189 offset:2048
	ds_read_b128 v[208:211], v189 offset:3072
	ds_read_b128 v[212:215], v189 offset:4096
	ds_read_b128 v[216:219], v189 offset:5120
	ds_read_b128 v[220:223], v189 offset:6144
	ds_read_b128 v[224:227], v189 offset:7168
	global_load_lds_dwordx4 v[158:159], off
	v_lshl_add_u64 v[158:159], s[28:29], 0, v[172:173]
	s_add_i32 m0, s27, 0xe000
	s_nop 0
	global_load_lds_dwordx4 v[158:159], off
	s_waitcnt vmcnt(8)
	s_waitcnt lgkmcnt(0)
	s_barrier
	s_setprio 1
	s_waitcnt lgkmcnt(0)
	v_mfma_f32_16x16x32_bf16 v[124:127], v[130:133], v[196:199], v[124:127]
	v_mfma_f32_16x16x32_bf16 v[120:123], v[138:141], v[196:199], v[120:123]
	v_mfma_f32_16x16x32_bf16 v[112:115], v[130:133], v[204:207], v[112:115]
	v_mfma_f32_16x16x32_bf16 v[104:107], v[138:141], v[204:207], v[104:107]
	v_mfma_f32_16x16x32_bf16 v[96:99], v[130:133], v[212:215], v[96:99]
	v_mfma_f32_16x16x32_bf16 v[88:91], v[138:141], v[212:215], v[88:91]
	v_mfma_f32_16x16x32_bf16 v[80:83], v[130:133], v[220:223], v[80:83]
	v_mfma_f32_16x16x32_bf16 v[72:75], v[138:141], v[220:223], v[72:75]
	v_mfma_f32_16x16x32_bf16 v[124:127], v[134:137], v[200:203], v[124:127]
	v_mfma_f32_16x16x32_bf16 v[120:123], v[142:145], v[200:203], v[120:123]
	v_mfma_f32_16x16x32_bf16 v[112:115], v[134:137], v[208:211], v[112:115]
	v_mfma_f32_16x16x32_bf16 v[104:107], v[142:145], v[208:211], v[104:107]
	v_mfma_f32_16x16x32_bf16 v[96:99], v[134:137], v[216:219], v[96:99]
	v_mfma_f32_16x16x32_bf16 v[88:91], v[142:145], v[216:219], v[88:91]
	v_mfma_f32_16x16x32_bf16 v[80:83], v[134:137], v[224:227], v[80:83]
	v_mfma_f32_16x16x32_bf16 v[72:75], v[142:145], v[224:227], v[72:75]
	s_setprio 0
	s_setprio 1
	v_mfma_f32_16x16x32_bf16 v[116:119], v[146:149], v[196:199], v[116:119]
	v_mfma_f32_16x16x32_bf16 v[108:111], v[154:157], v[196:199], v[108:111]
	v_mfma_f32_16x16x32_bf16 v[100:103], v[146:149], v[204:207], v[100:103]
	v_mfma_f32_16x16x32_bf16 v[92:95], v[154:157], v[204:207], v[92:95]
	v_mfma_f32_16x16x32_bf16 v[84:87], v[146:149], v[212:215], v[84:87]
	v_mfma_f32_16x16x32_bf16 v[76:79], v[154:157], v[212:215], v[76:79]
	v_mfma_f32_16x16x32_bf16 v[68:71], v[146:149], v[220:223], v[68:71]
	v_mfma_f32_16x16x32_bf16 v[64:67], v[154:157], v[220:223], v[64:67]
	v_mfma_f32_16x16x32_bf16 v[116:119], v[150:153], v[200:203], v[116:119]
	v_mfma_f32_16x16x32_bf16 v[108:111], v[192:195], v[200:203], v[108:111]
	v_mfma_f32_16x16x32_bf16 v[100:103], v[150:153], v[208:211], v[100:103]
	v_mfma_f32_16x16x32_bf16 v[92:95], v[192:195], v[208:211], v[92:95]
	s_barrier
	s_setprio 2
	v_mfma_f32_16x16x32_bf16 v[84:87], v[150:153], v[216:219], v[84:87]
	v_mfma_f32_16x16x32_bf16 v[76:79], v[192:195], v[216:219], v[76:79]
	v_mfma_f32_16x16x32_bf16 v[68:71], v[150:153], v[224:227], v[68:71]
	v_mfma_f32_16x16x32_bf16 v[64:67], v[192:195], v[224:227], v[64:67]
	s_setprio 0
	s_add_i32 s62, s52, s67
	v_lshl_add_u64 v[158:159], s[30:31], 0, v[162:163]
	s_mov_b32 m0, s62
	ds_read_b128 v[196:199], v189 offset:16384
	ds_read_b128 v[200:203], v189 offset:17408
	ds_read_b128 v[204:207], v189 offset:18432
	ds_read_b128 v[208:211], v189 offset:19456
	ds_read_b128 v[212:215], v189 offset:20480
	ds_read_b128 v[216:219], v189 offset:21504
	ds_read_b128 v[220:223], v189 offset:22528
	ds_read_b128 v[224:227], v189 offset:23552
	global_load_lds_dwordx4 v[158:159], off
	s_add_i32 m0, s62, 0x2000
	s_add_u32 s62, s30, 0x80000
	v_lshl_add_u64 v[228:229], s[30:31], 0, v[166:167]
	s_addc_u32 s63, s31, 0
	s_add_i32 s64, s53, s67
	global_load_lds_dwordx4 v[228:229], off
	v_lshl_add_u64 v[230:231], s[62:63], 0, v[162:163]
	s_mov_b32 m0, s64
	v_lshl_add_u64 v[232:233], s[34:35], 0, v[164:165]
	global_load_lds_dwordx4 v[230:231], off
	v_lshl_add_u64 v[230:231], s[62:63], 0, v[166:167]
	s_add_i32 m0, s64, 0x2000
	s_nop 0
	global_load_lds_dwordx4 v[230:231], off
	v_lshl_add_u64 v[230:231], s[34:35], 0, v[160:161]
	s_mov_b32 m0, s27
	s_nop 0
	global_load_lds_dwordx4 v[230:231], off
	s_mov_b32 m0, s41
	s_nop 0
	global_load_lds_dwordx4 v[232:233], off
	s_waitcnt vmcnt(8)
	s_waitcnt lgkmcnt(0)
	s_barrier
	s_setprio 1
	s_waitcnt lgkmcnt(0)
	v_mfma_f32_16x16x32_bf16 v[60:63], v[130:133], v[196:199], v[60:63]
	v_mfma_f32_16x16x32_bf16 v[56:59], v[138:141], v[196:199], v[56:59]
	v_mfma_f32_16x16x32_bf16 v[48:51], v[130:133], v[204:207], v[48:51]
	v_mfma_f32_16x16x32_bf16 v[40:43], v[138:141], v[204:207], v[40:43]
	v_mfma_f32_16x16x32_bf16 v[32:35], v[130:133], v[212:215], v[32:35]
	v_mfma_f32_16x16x32_bf16 v[24:27], v[138:141], v[212:215], v[24:27]
	v_mfma_f32_16x16x32_bf16 v[16:19], v[130:133], v[220:223], v[16:19]
	v_mfma_f32_16x16x32_bf16 v[8:11], v[138:141], v[220:223], v[8:11]
	v_mfma_f32_16x16x32_bf16 v[60:63], v[134:137], v[200:203], v[60:63]
	v_mfma_f32_16x16x32_bf16 v[56:59], v[142:145], v[200:203], v[56:59]
	v_mfma_f32_16x16x32_bf16 v[48:51], v[134:137], v[208:211], v[48:51]
	v_mfma_f32_16x16x32_bf16 v[40:43], v[142:145], v[208:211], v[40:43]
	v_mfma_f32_16x16x32_bf16 v[32:35], v[134:137], v[216:219], v[32:35]
	v_mfma_f32_16x16x32_bf16 v[24:27], v[142:145], v[216:219], v[24:27]
	v_mfma_f32_16x16x32_bf16 v[16:19], v[134:137], v[224:227], v[16:19]
	v_mfma_f32_16x16x32_bf16 v[8:11], v[142:145], v[224:227], v[8:11]
	s_setprio 0
	s_setprio 1
	v_mfma_f32_16x16x32_bf16 v[52:55], v[146:149], v[196:199], v[52:55]
	v_mfma_f32_16x16x32_bf16 v[44:47], v[154:157], v[196:199], v[44:47]
	v_mfma_f32_16x16x32_bf16 v[36:39], v[146:149], v[204:207], v[36:39]
	v_mfma_f32_16x16x32_bf16 v[28:31], v[154:157], v[204:207], v[28:31]
	v_mfma_f32_16x16x32_bf16 v[20:23], v[146:149], v[212:215], v[20:23]
	v_mfma_f32_16x16x32_bf16 v[12:15], v[154:157], v[212:215], v[12:15]
	v_mfma_f32_16x16x32_bf16 v[4:7], v[146:149], v[220:223], v[4:7]
	v_mfma_f32_16x16x32_bf16 v[0:3], v[154:157], v[220:223], v[0:3]
	v_mfma_f32_16x16x32_bf16 v[52:55], v[150:153], v[200:203], v[52:55]
	v_mfma_f32_16x16x32_bf16 v[44:47], v[192:195], v[200:203], v[44:47]
	v_mfma_f32_16x16x32_bf16 v[36:39], v[150:153], v[208:211], v[36:39]
	v_mfma_f32_16x16x32_bf16 v[28:31], v[192:195], v[208:211], v[28:31]
	s_barrier
	s_setprio 2
	v_mfma_f32_16x16x32_bf16 v[20:23], v[150:153], v[216:219], v[20:23]
	v_mfma_f32_16x16x32_bf16 v[12:15], v[192:195], v[216:219], v[12:15]
	v_mfma_f32_16x16x32_bf16 v[4:7], v[150:153], v[224:227], v[4:7]
	v_mfma_f32_16x16x32_bf16 v[0:3], v[192:195], v[224:227], v[0:3]
	s_setprio 0
	s_add_i32 s62, 0, 0x18000
	v_add_u32_e32 v129, s62, v181
	s_add_i32 s63, 0, 0x1c000
	ds_read_b128 v[130:133], v129
	ds_read_b128 v[134:137], v129 offset:1024
	ds_read_b128 v[138:141], v129 offset:2048
	ds_read_b128 v[142:145], v129 offset:3072
	v_add_u32_e32 v129, s63, v181
	ds_read_b128 v[146:149], v129
	ds_read_b128 v[150:153], v129 offset:1024
	ds_read_b128 v[154:157], v129 offset:2048
	ds_read_b128 v[192:195], v129 offset:3072
	s_add_u32 s34, s34, 0x80000
	s_addc_u32 s35, s35, 0
	s_mov_b32 m0, s42
	v_lshl_add_u64 v[234:235], s[34:35], 0, v[160:161]
	ds_read_b128 v[196:199], v189 offset:32768
	ds_read_b128 v[200:203], v189 offset:33792
	ds_read_b128 v[204:207], v189 offset:34816
	ds_read_b128 v[208:211], v189 offset:35840
	ds_read_b128 v[212:215], v189 offset:36864
	ds_read_b128 v[216:219], v189 offset:37888
	ds_read_b128 v[220:223], v189 offset:38912
	ds_read_b128 v[224:227], v189 offset:39936
	global_load_lds_dwordx4 v[234:235], off
	v_lshl_add_u64 v[234:235], s[34:35], 0, v[164:165]
	s_mov_b32 m0, s43
	s_nop 0
	global_load_lds_dwordx4 v[234:235], off
	s_waitcnt vmcnt(8)
	s_waitcnt lgkmcnt(0)
	s_barrier
	s_setprio 1
	s_waitcnt lgkmcnt(0)
	v_mfma_f32_16x16x32_bf16 v[124:127], v[130:133], v[196:199], v[124:127]
	v_mfma_f32_16x16x32_bf16 v[120:123], v[138:141], v[196:199], v[120:123]
	v_mfma_f32_16x16x32_bf16 v[112:115], v[130:133], v[204:207], v[112:115]
	v_mfma_f32_16x16x32_bf16 v[104:107], v[138:141], v[204:207], v[104:107]
	v_mfma_f32_16x16x32_bf16 v[96:99], v[130:133], v[212:215], v[96:99]
	v_mfma_f32_16x16x32_bf16 v[88:91], v[138:141], v[212:215], v[88:91]
	v_mfma_f32_16x16x32_bf16 v[80:83], v[130:133], v[220:223], v[80:83]
	v_mfma_f32_16x16x32_bf16 v[72:75], v[138:141], v[220:223], v[72:75]
	v_mfma_f32_16x16x32_bf16 v[124:127], v[134:137], v[200:203], v[124:127]
	v_mfma_f32_16x16x32_bf16 v[120:123], v[142:145], v[200:203], v[120:123]
	v_mfma_f32_16x16x32_bf16 v[112:115], v[134:137], v[208:211], v[112:115]
	v_mfma_f32_16x16x32_bf16 v[104:107], v[142:145], v[208:211], v[104:107]
	v_mfma_f32_16x16x32_bf16 v[96:99], v[134:137], v[216:219], v[96:99]
	v_mfma_f32_16x16x32_bf16 v[88:91], v[142:145], v[216:219], v[88:91]
	v_mfma_f32_16x16x32_bf16 v[80:83], v[134:137], v[224:227], v[80:83]
	v_mfma_f32_16x16x32_bf16 v[72:75], v[142:145], v[224:227], v[72:75]
	s_setprio 0
	s_setprio 1
	v_mfma_f32_16x16x32_bf16 v[116:119], v[146:149], v[196:199], v[116:119]
	v_mfma_f32_16x16x32_bf16 v[108:111], v[154:157], v[196:199], v[108:111]
	v_mfma_f32_16x16x32_bf16 v[100:103], v[146:149], v[204:207], v[100:103]
	v_mfma_f32_16x16x32_bf16 v[92:95], v[154:157], v[204:207], v[92:95]
	v_mfma_f32_16x16x32_bf16 v[84:87], v[146:149], v[212:215], v[84:87]
	v_mfma_f32_16x16x32_bf16 v[76:79], v[154:157], v[212:215], v[76:79]
	v_mfma_f32_16x16x32_bf16 v[68:71], v[146:149], v[220:223], v[68:71]
	v_mfma_f32_16x16x32_bf16 v[64:67], v[154:157], v[220:223], v[64:67]
	v_mfma_f32_16x16x32_bf16 v[116:119], v[150:153], v[200:203], v[116:119]
	v_mfma_f32_16x16x32_bf16 v[108:111], v[192:195], v[200:203], v[108:111]
	v_mfma_f32_16x16x32_bf16 v[100:103], v[150:153], v[208:211], v[100:103]
	v_mfma_f32_16x16x32_bf16 v[92:95], v[192:195], v[208:211], v[92:95]
	s_barrier
	s_setprio 2
	v_mfma_f32_16x16x32_bf16 v[84:87], v[150:153], v[216:219], v[84:87]
	v_mfma_f32_16x16x32_bf16 v[76:79], v[192:195], v[216:219], v[76:79]
	v_mfma_f32_16x16x32_bf16 v[68:71], v[150:153], v[224:227], v[68:71]
	v_mfma_f32_16x16x32_bf16 v[64:67], v[192:195], v[224:227], v[64:67]
	s_setprio 0
	s_add_i32 s34, s62, s67
	v_lshl_add_u64 v[158:159], v[158:159], 0, s[12:13]
	s_mov_b32 m0, s34
	ds_read_b128 v[196:199], v189 offset:49152
	ds_read_b128 v[200:203], v189 offset:50176
	ds_read_b128 v[204:207], v189 offset:51200
	ds_read_b128 v[208:211], v189 offset:52224
	ds_read_b128 v[212:215], v189 offset:53248
	ds_read_b128 v[216:219], v189 offset:54272
	ds_read_b128 v[220:223], v189 offset:55296
	ds_read_b128 v[224:227], v189 offset:56320
	global_load_lds_dwordx4 v[158:159], off
	s_add_i32 m0, s34, 0x2000
	s_add_u32 s30, s30, 0x80080
	v_lshl_add_u64 v[158:159], v[228:229], 0, s[12:13]
	s_addc_u32 s31, s31, 0
	s_add_i32 s34, s63, s67
	global_load_lds_dwordx4 v[158:159], off
	v_lshl_add_u64 v[158:159], s[30:31], 0, v[162:163]
	s_mov_b32 m0, s34
	s_nop 0
	global_load_lds_dwordx4 v[158:159], off
	v_lshl_add_u64 v[158:159], s[30:31], 0, v[166:167]
	s_add_i32 m0, s34, 0x2000
	s_nop 0
	global_load_lds_dwordx4 v[158:159], off
	v_lshl_add_u64 v[158:159], v[230:231], 0, s[12:13]
	s_mov_b32 m0, s44
	s_nop 0
	global_load_lds_dwordx4 v[158:159], off
	v_lshl_add_u64 v[158:159], v[232:233], 0, s[12:13]
	s_mov_b32 m0, s45
	s_nop 0
	global_load_lds_dwordx4 v[158:159], off
	s_waitcnt vmcnt(8)
	s_waitcnt lgkmcnt(0)
	s_barrier
	s_setprio 1
	s_waitcnt lgkmcnt(0)
	v_mfma_f32_16x16x32_bf16 v[60:63], v[130:133], v[196:199], v[60:63]
	v_mfma_f32_16x16x32_bf16 v[56:59], v[138:141], v[196:199], v[56:59]
	v_mfma_f32_16x16x32_bf16 v[48:51], v[130:133], v[204:207], v[48:51]
	v_mfma_f32_16x16x32_bf16 v[40:43], v[138:141], v[204:207], v[40:43]
	v_mfma_f32_16x16x32_bf16 v[32:35], v[130:133], v[212:215], v[32:35]
	v_mfma_f32_16x16x32_bf16 v[24:27], v[138:141], v[212:215], v[24:27]
	v_mfma_f32_16x16x32_bf16 v[16:19], v[130:133], v[220:223], v[16:19]
	v_mfma_f32_16x16x32_bf16 v[8:11], v[138:141], v[220:223], v[8:11]
	v_mfma_f32_16x16x32_bf16 v[60:63], v[134:137], v[200:203], v[60:63]
	v_mfma_f32_16x16x32_bf16 v[56:59], v[142:145], v[200:203], v[56:59]
	v_mfma_f32_16x16x32_bf16 v[48:51], v[134:137], v[208:211], v[48:51]
	v_mfma_f32_16x16x32_bf16 v[40:43], v[142:145], v[208:211], v[40:43]
	v_mfma_f32_16x16x32_bf16 v[32:35], v[134:137], v[216:219], v[32:35]
	v_mfma_f32_16x16x32_bf16 v[24:27], v[142:145], v[216:219], v[24:27]
	v_mfma_f32_16x16x32_bf16 v[16:19], v[134:137], v[224:227], v[16:19]
	v_mfma_f32_16x16x32_bf16 v[8:11], v[142:145], v[224:227], v[8:11]
	s_setprio 0
	s_setprio 1
	v_mfma_f32_16x16x32_bf16 v[52:55], v[146:149], v[196:199], v[52:55]
	v_mfma_f32_16x16x32_bf16 v[44:47], v[154:157], v[196:199], v[44:47]
	v_mfma_f32_16x16x32_bf16 v[36:39], v[146:149], v[204:207], v[36:39]
	v_mfma_f32_16x16x32_bf16 v[28:31], v[154:157], v[204:207], v[28:31]
	v_mfma_f32_16x16x32_bf16 v[20:23], v[146:149], v[212:215], v[20:23]
	v_mfma_f32_16x16x32_bf16 v[12:15], v[154:157], v[212:215], v[12:15]
	v_mfma_f32_16x16x32_bf16 v[4:7], v[146:149], v[220:223], v[4:7]
	v_mfma_f32_16x16x32_bf16 v[0:3], v[154:157], v[220:223], v[0:3]
	v_mfma_f32_16x16x32_bf16 v[52:55], v[150:153], v[200:203], v[52:55]
	v_mfma_f32_16x16x32_bf16 v[44:47], v[192:195], v[200:203], v[44:47]
	v_mfma_f32_16x16x32_bf16 v[36:39], v[150:153], v[208:211], v[36:39]
	v_mfma_f32_16x16x32_bf16 v[28:31], v[192:195], v[208:211], v[28:31]
	s_barrier
	s_setprio 2
	v_mfma_f32_16x16x32_bf16 v[20:23], v[150:153], v[216:219], v[20:23]
	v_mfma_f32_16x16x32_bf16 v[12:15], v[192:195], v[216:219], v[12:15]
	v_mfma_f32_16x16x32_bf16 v[4:7], v[150:153], v[224:227], v[4:7]
	v_mfma_f32_16x16x32_bf16 v[0:3], v[192:195], v[224:227], v[0:3]
	s_setprio 0
	s_add_i32 s61, s61, 2
	s_add_u32 s59, s59, 0x100
	s_addc_u32 s60, s60, 0
	s_add_u32 s28, s28, 0x100
	s_addc_u32 s29, s29, 0
	s_cmp_gt_u32 s61, 29
	s_cbranch_scc0 .LBB0_1979
	s_and_b64 vcc, exec, s[14:15]
	s_cbranch_vccz .LBB0_1982
	s_barrier

.LBB0_2924:
	ds_read_b128 v[124:127], v163
	ds_read_b128 v[156:159], v163 offset:1024
	ds_read_b128 v[170:173], v163 offset:2048
	ds_read_b128 v[174:177], v163 offset:3072
	ds_read_b128 v[178:181], v165
	ds_read_b128 v[182:185], v165 offset:1024
	ds_read_b128 v[186:189], v165 offset:2048
	ds_read_b128 v[190:193], v165 offset:3072
	s_add_u32 s26, s24, 0xfff80080
	s_addc_u32 s27, s25, -1
	s_cmp_eq_u32 s56, 28
	s_cselect_b32 s29, s17, s27
	s_cselect_b32 s28, s52, s26
	s_cselect_b32 s27, s15, s55
	s_cselect_b32 s26, s53, s54
	v_lshl_add_u64 v[114:115], s[24:25], 0, v[148:149]
	s_add_i32 m0, s23, 0xc000
	ds_read_b128 v[194:197], v167
	ds_read_b128 v[198:201], v167 offset:1024
	ds_read_b128 v[202:205], v167 offset:2048
	ds_read_b128 v[206:209], v167 offset:3072
	ds_read_b128 v[210:213], v167 offset:4096
	ds_read_b128 v[214:217], v167 offset:5120
	ds_read_b128 v[218:221], v167 offset:6144
	ds_read_b128 v[222:225], v167 offset:7168
	global_load_lds_dwordx4 v[114:115], off
	v_lshl_add_u64 v[114:115], s[24:25], 0, v[146:147]
	s_add_i32 m0, s23, 0xe000
	s_nop 0
	global_load_lds_dwordx4 v[114:115], off
	s_waitcnt vmcnt(8)
	s_waitcnt lgkmcnt(0)
	s_barrier
	s_setprio 1
	s_waitcnt lgkmcnt(0)
	v_mfma_f32_16x16x32_bf16 v[132:135], v[124:127], v[194:197], v[132:135]
	v_mfma_f32_16x16x32_bf16 v[120:123], v[170:173], v[194:197], v[120:123]
	v_mfma_f32_16x16x32_bf16 v[108:111], v[124:127], v[202:205], v[108:111]
	v_mfma_f32_16x16x32_bf16 v[100:103], v[170:173], v[202:205], v[100:103]
	v_mfma_f32_16x16x32_bf16 v[92:95], v[124:127], v[210:213], v[92:95]
	v_mfma_f32_16x16x32_bf16 v[84:87], v[170:173], v[210:213], v[84:87]
	v_mfma_f32_16x16x32_bf16 v[76:79], v[124:127], v[218:221], v[76:79]
	v_mfma_f32_16x16x32_bf16 v[68:71], v[170:173], v[218:221], v[68:71]
	v_mfma_f32_16x16x32_bf16 v[132:135], v[156:159], v[198:201], v[132:135]
	v_mfma_f32_16x16x32_bf16 v[120:123], v[174:177], v[198:201], v[120:123]
	v_mfma_f32_16x16x32_bf16 v[108:111], v[156:159], v[206:209], v[108:111]
	v_mfma_f32_16x16x32_bf16 v[100:103], v[174:177], v[206:209], v[100:103]
	v_mfma_f32_16x16x32_bf16 v[92:95], v[156:159], v[214:217], v[92:95]
	v_mfma_f32_16x16x32_bf16 v[84:87], v[174:177], v[214:217], v[84:87]
	v_mfma_f32_16x16x32_bf16 v[76:79], v[156:159], v[222:225], v[76:79]
	v_mfma_f32_16x16x32_bf16 v[68:71], v[174:177], v[222:225], v[68:71]
	s_setprio 0
	s_setprio 1
	v_mfma_f32_16x16x32_bf16 v[128:131], v[178:181], v[194:197], v[128:131]
	v_mfma_f32_16x16x32_bf16 v[114:117], v[186:189], v[194:197], v[116:119]
	v_mfma_f32_16x16x32_bf16 v[104:107], v[178:181], v[202:205], v[104:107]
	v_mfma_f32_16x16x32_bf16 v[96:99], v[186:189], v[202:205], v[96:99]
	v_mfma_f32_16x16x32_bf16 v[88:91], v[178:181], v[210:213], v[88:91]
	v_mfma_f32_16x16x32_bf16 v[80:83], v[186:189], v[210:213], v[80:83]
	v_mfma_f32_16x16x32_bf16 v[72:75], v[178:181], v[218:221], v[72:75]
	v_mfma_f32_16x16x32_bf16 v[64:67], v[186:189], v[218:221], v[64:67]
	v_mfma_f32_16x16x32_bf16 v[128:131], v[182:185], v[198:201], v[128:131]
	v_mfma_f32_16x16x32_bf16 v[114:117], v[190:193], v[198:201], v[114:117]
	v_mfma_f32_16x16x32_bf16 v[104:107], v[182:185], v[206:209], v[104:107]
	v_mfma_f32_16x16x32_bf16 v[96:99], v[190:193], v[206:209], v[96:99]
	s_barrier
	s_setprio 2
	v_mfma_f32_16x16x32_bf16 v[88:91], v[182:185], v[214:217], v[88:91]
	v_mfma_f32_16x16x32_bf16 v[80:83], v[190:193], v[214:217], v[80:83]
	v_mfma_f32_16x16x32_bf16 v[72:75], v[182:185], v[222:225], v[72:75]
	v_mfma_f32_16x16x32_bf16 v[64:67], v[190:193], v[222:225], v[64:67]
	s_setprio 0
	s_add_i32 s57, s48, s67
	v_lshl_add_u64 v[226:227], s[26:27], 0, v[138:139]
	s_mov_b32 m0, s57
	ds_read_b128 v[194:197], v167 offset:16384
	ds_read_b128 v[198:201], v167 offset:17408
	ds_read_b128 v[202:205], v167 offset:18432
	ds_read_b128 v[206:209], v167 offset:19456
	ds_read_b128 v[210:213], v167 offset:20480
	ds_read_b128 v[214:217], v167 offset:21504
	ds_read_b128 v[218:221], v167 offset:22528
	ds_read_b128 v[222:225], v167 offset:23552
	global_load_lds_dwordx4 v[226:227], off
	s_add_i32 m0, s57, 0x2000
	s_add_u32 s58, s26, 0x80000
	v_lshl_add_u64 v[228:229], s[26:27], 0, v[142:143]
	s_addc_u32 s59, s27, 0
	s_add_i32 s57, s49, s67
	global_load_lds_dwordx4 v[228:229], off
	v_lshl_add_u64 v[118:119], s[58:59], 0, v[138:139]
	s_mov_b32 m0, s57
	v_lshl_add_u64 v[230:231], s[28:29], 0, v[136:137]
	global_load_lds_dwordx4 v[118:119], off
	v_lshl_add_u64 v[118:119], s[58:59], 0, v[142:143]
	s_add_i32 m0, s57, 0x2000
	v_lshl_add_u64 v[232:233], s[28:29], 0, v[140:141]
	global_load_lds_dwordx4 v[118:119], off
	s_mov_b32 m0, s23
	s_nop 0
	global_load_lds_dwordx4 v[230:231], off
	s_mov_b32 m0, s37
	s_nop 0
	global_load_lds_dwordx4 v[232:233], off
	s_waitcnt vmcnt(8)
	s_waitcnt lgkmcnt(0)
	s_barrier
	s_setprio 1
	s_waitcnt lgkmcnt(0)
	v_mfma_f32_16x16x32_bf16 v[60:63], v[124:127], v[194:197], v[60:63]
	v_mfma_f32_16x16x32_bf16 v[52:55], v[170:173], v[194:197], v[52:55]
	v_mfma_f32_16x16x32_bf16 v[44:47], v[124:127], v[202:205], v[44:47]
	v_mfma_f32_16x16x32_bf16 v[36:39], v[170:173], v[202:205], v[36:39]
	v_mfma_f32_16x16x32_bf16 v[28:31], v[124:127], v[210:213], v[28:31]
	v_mfma_f32_16x16x32_bf16 v[20:23], v[170:173], v[210:213], v[20:23]
	v_mfma_f32_16x16x32_bf16 v[12:15], v[124:127], v[218:221], v[12:15]
	v_mfma_f32_16x16x32_bf16 v[4:7], v[170:173], v[218:221], v[4:7]
	v_mfma_f32_16x16x32_bf16 v[60:63], v[156:159], v[198:201], v[60:63]
	v_mfma_f32_16x16x32_bf16 v[52:55], v[174:177], v[198:201], v[52:55]
	v_mfma_f32_16x16x32_bf16 v[44:47], v[156:159], v[206:209], v[44:47]
	v_mfma_f32_16x16x32_bf16 v[36:39], v[174:177], v[206:209], v[36:39]
	v_mfma_f32_16x16x32_bf16 v[28:31], v[156:159], v[214:217], v[28:31]
	v_mfma_f32_16x16x32_bf16 v[20:23], v[174:177], v[214:217], v[20:23]
	v_mfma_f32_16x16x32_bf16 v[12:15], v[156:159], v[222:225], v[12:15]
	v_mfma_f32_16x16x32_bf16 v[4:7], v[174:177], v[222:225], v[4:7]
	s_setprio 0
	s_setprio 1
	v_mfma_f32_16x16x32_bf16 v[56:59], v[178:181], v[194:197], v[56:59]
	v_mfma_f32_16x16x32_bf16 v[48:51], v[186:189], v[194:197], v[48:51]
	v_mfma_f32_16x16x32_bf16 v[40:43], v[178:181], v[202:205], v[40:43]
	v_mfma_f32_16x16x32_bf16 v[32:35], v[186:189], v[202:205], v[32:35]
	v_mfma_f32_16x16x32_bf16 v[24:27], v[178:181], v[210:213], v[24:27]
	v_mfma_f32_16x16x32_bf16 v[16:19], v[186:189], v[210:213], v[16:19]
	v_mfma_f32_16x16x32_bf16 v[8:11], v[178:181], v[218:221], v[8:11]
	v_mfma_f32_16x16x32_bf16 v[0:3], v[186:189], v[218:221], v[0:3]
	v_mfma_f32_16x16x32_bf16 v[56:59], v[182:185], v[198:201], v[56:59]
	v_mfma_f32_16x16x32_bf16 v[48:51], v[190:193], v[198:201], v[48:51]
	v_mfma_f32_16x16x32_bf16 v[40:43], v[182:185], v[206:209], v[40:43]
	v_mfma_f32_16x16x32_bf16 v[32:35], v[190:193], v[206:209], v[32:35]
	s_barrier
	s_setprio 2
	v_mfma_f32_16x16x32_bf16 v[24:27], v[182:185], v[214:217], v[24:27]
	v_mfma_f32_16x16x32_bf16 v[16:19], v[190:193], v[214:217], v[16:19]
	v_mfma_f32_16x16x32_bf16 v[8:11], v[182:185], v[222:225], v[8:11]
	v_mfma_f32_16x16x32_bf16 v[0:3], v[190:193], v[222:225], v[0:3]
	s_setprio 0
	s_add_i32 s57, 0, 0x18000
	v_add_u32_e32 v113, s57, v155
	s_add_i32 s58, 0, 0x1c000
	ds_read_b128 v[124:127], v113
	ds_read_b128 v[156:159], v113 offset:1024
	ds_read_b128 v[170:173], v113 offset:2048
	ds_read_b128 v[174:177], v113 offset:3072
	v_add_u32_e32 v113, s58, v155
	ds_read_b128 v[178:181], v113
	ds_read_b128 v[182:185], v113 offset:1024
	ds_read_b128 v[186:189], v113 offset:2048
	ds_read_b128 v[190:193], v113 offset:3072
	s_add_u32 s28, s28, 0x80000
	s_addc_u32 s29, s29, 0
	s_mov_b32 m0, s38
	v_lshl_add_u64 v[118:119], s[28:29], 0, v[136:137]
	ds_read_b128 v[194:197], v167 offset:32768
	ds_read_b128 v[198:201], v167 offset:33792
	ds_read_b128 v[202:205], v167 offset:34816
	ds_read_b128 v[206:209], v167 offset:35840
	ds_read_b128 v[210:213], v167 offset:36864
	ds_read_b128 v[214:217], v167 offset:37888
	ds_read_b128 v[218:221], v167 offset:38912
	ds_read_b128 v[222:225], v167 offset:39936
	global_load_lds_dwordx4 v[118:119], off
	v_lshl_add_u64 v[118:119], s[28:29], 0, v[140:141]
	s_mov_b32 m0, s39
	s_nop 0
	global_load_lds_dwordx4 v[118:119], off
	s_waitcnt vmcnt(8)
	s_waitcnt lgkmcnt(0)
	s_barrier
	s_setprio 1
	s_waitcnt lgkmcnt(0)
	v_mfma_f32_16x16x32_bf16 v[132:135], v[124:127], v[194:197], v[132:135]
	v_mfma_f32_16x16x32_bf16 v[118:121], v[170:173], v[194:197], v[120:123]
	v_mfma_f32_16x16x32_bf16 v[108:111], v[124:127], v[202:205], v[108:111]
	v_mfma_f32_16x16x32_bf16 v[100:103], v[170:173], v[202:205], v[100:103]
	v_mfma_f32_16x16x32_bf16 v[92:95], v[124:127], v[210:213], v[92:95]
	v_mfma_f32_16x16x32_bf16 v[84:87], v[170:173], v[210:213], v[84:87]
	v_mfma_f32_16x16x32_bf16 v[76:79], v[124:127], v[218:221], v[76:79]
	v_mfma_f32_16x16x32_bf16 v[68:71], v[170:173], v[218:221], v[68:71]
	v_mfma_f32_16x16x32_bf16 v[132:135], v[156:159], v[198:201], v[132:135]
	v_mfma_f32_16x16x32_bf16 v[120:123], v[174:177], v[198:201], v[118:121]
	v_mfma_f32_16x16x32_bf16 v[108:111], v[156:159], v[206:209], v[108:111]
	v_mfma_f32_16x16x32_bf16 v[100:103], v[174:177], v[206:209], v[100:103]
	v_mfma_f32_16x16x32_bf16 v[92:95], v[156:159], v[214:217], v[92:95]
	v_mfma_f32_16x16x32_bf16 v[84:87], v[174:177], v[214:217], v[84:87]
	v_mfma_f32_16x16x32_bf16 v[76:79], v[156:159], v[222:225], v[76:79]
	v_mfma_f32_16x16x32_bf16 v[68:71], v[174:177], v[222:225], v[68:71]
	s_setprio 0
	s_setprio 1
	v_mfma_f32_16x16x32_bf16 v[128:131], v[178:181], v[194:197], v[128:131]
	v_mfma_f32_16x16x32_bf16 v[114:117], v[186:189], v[194:197], v[114:117]
	v_mfma_f32_16x16x32_bf16 v[104:107], v[178:181], v[202:205], v[104:107]
	v_mfma_f32_16x16x32_bf16 v[96:99], v[186:189], v[202:205], v[96:99]
	v_mfma_f32_16x16x32_bf16 v[88:91], v[178:181], v[210:213], v[88:91]
	v_mfma_f32_16x16x32_bf16 v[80:83], v[186:189], v[210:213], v[80:83]
	v_mfma_f32_16x16x32_bf16 v[72:75], v[178:181], v[218:221], v[72:75]
	v_mfma_f32_16x16x32_bf16 v[64:67], v[186:189], v[218:221], v[64:67]
	v_mfma_f32_16x16x32_bf16 v[128:131], v[182:185], v[198:201], v[128:131]
	v_mfma_f32_16x16x32_bf16 v[116:119], v[190:193], v[198:201], v[114:117]
	v_mfma_f32_16x16x32_bf16 v[104:107], v[182:185], v[206:209], v[104:107]
	v_mfma_f32_16x16x32_bf16 v[96:99], v[190:193], v[206:209], v[96:99]
	s_barrier
	s_setprio 2
	v_mfma_f32_16x16x32_bf16 v[88:91], v[182:185], v[214:217], v[88:91]
	v_mfma_f32_16x16x32_bf16 v[80:83], v[190:193], v[214:217], v[80:83]
	v_mfma_f32_16x16x32_bf16 v[72:75], v[182:185], v[222:225], v[72:75]
	v_mfma_f32_16x16x32_bf16 v[64:67], v[190:193], v[222:225], v[64:67]
	s_setprio 0
	s_add_i32 s28, s57, s67
	v_lshl_add_u64 v[114:115], v[226:227], 0, s[10:11]
	s_mov_b32 m0, s28
	ds_read_b128 v[194:197], v167 offset:49152
	ds_read_b128 v[198:201], v167 offset:50176
	ds_read_b128 v[202:205], v167 offset:51200
	ds_read_b128 v[206:209], v167 offset:52224
	ds_read_b128 v[210:213], v167 offset:53248
	ds_read_b128 v[214:217], v167 offset:54272
	ds_read_b128 v[218:221], v167 offset:55296
	ds_read_b128 v[222:225], v167 offset:56320
	global_load_lds_dwordx4 v[114:115], off
	s_add_i32 m0, s28, 0x2000
	s_add_u32 s26, s26, 0x80080
	v_lshl_add_u64 v[114:115], v[228:229], 0, s[10:11]
	s_addc_u32 s27, s27, 0
	s_add_i32 s28, s58, s67
	global_load_lds_dwordx4 v[114:115], off
	v_lshl_add_u64 v[114:115], s[26:27], 0, v[138:139]
	s_mov_b32 m0, s28
	s_nop 0
	global_load_lds_dwordx4 v[114:115], off
	v_lshl_add_u64 v[114:115], s[26:27], 0, v[142:143]
	s_add_i32 m0, s28, 0x2000
	s_nop 0
	global_load_lds_dwordx4 v[114:115], off
	v_lshl_add_u64 v[114:115], v[230:231], 0, s[10:11]
	s_mov_b32 m0, s41
	s_nop 0
	global_load_lds_dwordx4 v[114:115], off
	v_lshl_add_u64 v[114:115], v[232:233], 0, s[10:11]
	s_mov_b32 m0, s42
	s_nop 0
	global_load_lds_dwordx4 v[114:115], off
	s_waitcnt vmcnt(8)
	s_waitcnt lgkmcnt(0)
	s_barrier
	s_setprio 1
	s_waitcnt lgkmcnt(0)
	v_mfma_f32_16x16x32_bf16 v[60:63], v[124:127], v[194:197], v[60:63]
	v_mfma_f32_16x16x32_bf16 v[52:55], v[170:173], v[194:197], v[52:55]
	v_mfma_f32_16x16x32_bf16 v[44:47], v[124:127], v[202:205], v[44:47]
	v_mfma_f32_16x16x32_bf16 v[36:39], v[170:173], v[202:205], v[36:39]
	v_mfma_f32_16x16x32_bf16 v[28:31], v[124:127], v[210:213], v[28:31]
	v_mfma_f32_16x16x32_bf16 v[20:23], v[170:173], v[210:213], v[20:23]
	v_mfma_f32_16x16x32_bf16 v[12:15], v[124:127], v[218:221], v[12:15]
	v_mfma_f32_16x16x32_bf16 v[4:7], v[170:173], v[218:221], v[4:7]
	v_mfma_f32_16x16x32_bf16 v[60:63], v[156:159], v[198:201], v[60:63]
	v_mfma_f32_16x16x32_bf16 v[52:55], v[174:177], v[198:201], v[52:55]
	v_mfma_f32_16x16x32_bf16 v[44:47], v[156:159], v[206:209], v[44:47]
	v_mfma_f32_16x16x32_bf16 v[36:39], v[174:177], v[206:209], v[36:39]
	v_mfma_f32_16x16x32_bf16 v[28:31], v[156:159], v[214:217], v[28:31]
	v_mfma_f32_16x16x32_bf16 v[20:23], v[174:177], v[214:217], v[20:23]
	v_mfma_f32_16x16x32_bf16 v[12:15], v[156:159], v[222:225], v[12:15]
	v_mfma_f32_16x16x32_bf16 v[4:7], v[174:177], v[222:225], v[4:7]
	s_setprio 0
	s_setprio 1
	v_mfma_f32_16x16x32_bf16 v[56:59], v[178:181], v[194:197], v[56:59]
	v_mfma_f32_16x16x32_bf16 v[48:51], v[186:189], v[194:197], v[48:51]
	v_mfma_f32_16x16x32_bf16 v[40:43], v[178:181], v[202:205], v[40:43]
	v_mfma_f32_16x16x32_bf16 v[32:35], v[186:189], v[202:205], v[32:35]
	v_mfma_f32_16x16x32_bf16 v[24:27], v[178:181], v[210:213], v[24:27]
	v_mfma_f32_16x16x32_bf16 v[16:19], v[186:189], v[210:213], v[16:19]
	v_mfma_f32_16x16x32_bf16 v[8:11], v[178:181], v[218:221], v[8:11]
	v_mfma_f32_16x16x32_bf16 v[0:3], v[186:189], v[218:221], v[0:3]
	v_mfma_f32_16x16x32_bf16 v[56:59], v[182:185], v[198:201], v[56:59]
	v_mfma_f32_16x16x32_bf16 v[48:51], v[190:193], v[198:201], v[48:51]
	v_mfma_f32_16x16x32_bf16 v[40:43], v[182:185], v[206:209], v[40:43]
	v_mfma_f32_16x16x32_bf16 v[32:35], v[190:193], v[206:209], v[32:35]
	s_barrier
	s_setprio 2
	v_mfma_f32_16x16x32_bf16 v[24:27], v[182:185], v[214:217], v[24:27]
	v_mfma_f32_16x16x32_bf16 v[16:19], v[190:193], v[214:217], v[16:19]
	v_mfma_f32_16x16x32_bf16 v[8:11], v[182:185], v[222:225], v[8:11]
	v_mfma_f32_16x16x32_bf16 v[0:3], v[190:193], v[222:225], v[0:3]
	s_setprio 0
	s_add_i32 s56, s56, 2
	s_add_u32 s54, s54, 0x100
	s_addc_u32 s55, s55, 0
	s_add_u32 s24, s24, 0x100
	s_addc_u32 s25, s25, 0
	s_cmp_gt_u32 s56, 29
	s_cbranch_scc0 .LBB0_2924
	s_and_b64 vcc, exec, s[12:13]
	s_cbranch_vccz .LBB0_2927
	s_barrier

.LBB0_3122:
	ds_read_b128 v[130:133], v177
	ds_read_b128 v[134:137], v177 offset:1024
	ds_read_b128 v[138:141], v177 offset:2048
	ds_read_b128 v[142:145], v177 offset:3072
	ds_read_b128 v[146:149], v179
	ds_read_b128 v[186:189], v179 offset:1024
	ds_read_b128 v[190:193], v179 offset:2048
	ds_read_b128 v[194:197], v179 offset:3072
	s_add_u32 s30, s28, 0xfff80080
	s_addc_u32 s31, s29, -1
	s_cmp_eq_u32 s72, 28
	s_cselect_b32 s35, s6, s31
	s_cselect_b32 s34, s21, s30
	s_cselect_b32 s31, s19, s71
	s_cselect_b32 s30, s27, s70
	v_lshl_add_u64 v[150:151], s[28:29], 0, v[166:167]
	s_add_i32 m0, s41, 0xc000
	ds_read_b128 v[198:201], v181
	ds_read_b128 v[202:205], v181 offset:1024
	ds_read_b128 v[206:209], v181 offset:2048
	ds_read_b128 v[210:213], v181 offset:3072
	ds_read_b128 v[214:217], v181 offset:4096
	ds_read_b128 v[218:221], v181 offset:5120
	ds_read_b128 v[222:225], v181 offset:6144
	ds_read_b128 v[226:229], v181 offset:7168
	global_load_lds_dwordx4 v[150:151], off
	v_lshl_add_u64 v[150:151], s[28:29], 0, v[164:165]
	s_add_i32 m0, s41, 0xe000
	s_nop 0
	global_load_lds_dwordx4 v[150:151], off
	s_waitcnt vmcnt(8)
	s_waitcnt lgkmcnt(0)
	s_barrier
	s_setprio 1
	s_waitcnt lgkmcnt(0)
	v_mfma_f32_16x16x32_bf16 v[124:127], v[130:133], v[198:201], v[124:127]
	v_mfma_f32_16x16x32_bf16 v[120:123], v[138:141], v[198:201], v[120:123]
	v_mfma_f32_16x16x32_bf16 v[108:111], v[130:133], v[206:209], v[108:111]
	v_mfma_f32_16x16x32_bf16 v[100:103], v[138:141], v[206:209], v[100:103]
	v_mfma_f32_16x16x32_bf16 v[92:95], v[130:133], v[214:217], v[92:95]
	v_mfma_f32_16x16x32_bf16 v[84:87], v[138:141], v[214:217], v[84:87]
	v_mfma_f32_16x16x32_bf16 v[76:79], v[130:133], v[222:225], v[76:79]
	v_mfma_f32_16x16x32_bf16 v[68:71], v[138:141], v[222:225], v[68:71]
	v_mfma_f32_16x16x32_bf16 v[124:127], v[134:137], v[202:205], v[124:127]
	v_mfma_f32_16x16x32_bf16 v[120:123], v[142:145], v[202:205], v[120:123]
	v_mfma_f32_16x16x32_bf16 v[108:111], v[134:137], v[210:213], v[108:111]
	v_mfma_f32_16x16x32_bf16 v[100:103], v[142:145], v[210:213], v[100:103]
	v_mfma_f32_16x16x32_bf16 v[92:95], v[134:137], v[218:221], v[92:95]
	v_mfma_f32_16x16x32_bf16 v[84:87], v[142:145], v[218:221], v[84:87]
	v_mfma_f32_16x16x32_bf16 v[76:79], v[134:137], v[226:229], v[76:79]
	v_mfma_f32_16x16x32_bf16 v[68:71], v[142:145], v[226:229], v[68:71]
	s_setprio 0
	s_setprio 1
	v_mfma_f32_16x16x32_bf16 v[116:119], v[146:149], v[198:201], v[116:119]
	v_mfma_f32_16x16x32_bf16 v[112:115], v[190:193], v[198:201], v[112:115]
	v_mfma_f32_16x16x32_bf16 v[104:107], v[146:149], v[206:209], v[104:107]
	v_mfma_f32_16x16x32_bf16 v[96:99], v[190:193], v[206:209], v[96:99]
	v_mfma_f32_16x16x32_bf16 v[88:91], v[146:149], v[214:217], v[88:91]
	v_mfma_f32_16x16x32_bf16 v[80:83], v[190:193], v[214:217], v[80:83]
	v_mfma_f32_16x16x32_bf16 v[72:75], v[146:149], v[222:225], v[72:75]
	v_mfma_f32_16x16x32_bf16 v[64:67], v[190:193], v[222:225], v[64:67]
	v_mfma_f32_16x16x32_bf16 v[116:119], v[186:189], v[202:205], v[116:119]
	v_mfma_f32_16x16x32_bf16 v[112:115], v[194:197], v[202:205], v[112:115]
	v_mfma_f32_16x16x32_bf16 v[104:107], v[186:189], v[210:213], v[104:107]
	v_mfma_f32_16x16x32_bf16 v[96:99], v[194:197], v[210:213], v[96:99]
	s_barrier
	s_setprio 2
	v_mfma_f32_16x16x32_bf16 v[88:91], v[186:189], v[218:221], v[88:91]
	v_mfma_f32_16x16x32_bf16 v[80:83], v[194:197], v[218:221], v[80:83]
	v_mfma_f32_16x16x32_bf16 v[72:75], v[186:189], v[226:229], v[72:75]
	v_mfma_f32_16x16x32_bf16 v[64:67], v[194:197], v[226:229], v[64:67]
	s_setprio 0
	s_add_i32 s73, s56, s67
	v_lshl_add_u64 v[150:151], s[30:31], 0, v[154:155]
	s_mov_b32 m0, s73
	ds_read_b128 v[198:201], v181 offset:16384
	ds_read_b128 v[202:205], v181 offset:17408
	ds_read_b128 v[206:209], v181 offset:18432
	ds_read_b128 v[210:213], v181 offset:19456
	ds_read_b128 v[214:217], v181 offset:20480
	ds_read_b128 v[218:221], v181 offset:21504
	ds_read_b128 v[222:225], v181 offset:22528
	ds_read_b128 v[226:229], v181 offset:23552
	global_load_lds_dwordx4 v[150:151], off
	s_add_i32 m0, s73, 0x2000
	s_add_u32 s74, s30, 0x80000
	v_lshl_add_u64 v[182:183], s[30:31], 0, v[158:159]
	s_addc_u32 s75, s31, 0
	s_add_i32 s73, s57, s67
	global_load_lds_dwordx4 v[182:183], off
	v_lshl_add_u64 v[230:231], s[74:75], 0, v[154:155]
	s_mov_b32 m0, s73
	v_lshl_add_u64 v[232:233], s[34:35], 0, v[156:157]
	global_load_lds_dwordx4 v[230:231], off
	v_lshl_add_u64 v[230:231], s[74:75], 0, v[158:159]
	s_add_i32 m0, s73, 0x2000
	s_nop 0
	global_load_lds_dwordx4 v[230:231], off
	v_lshl_add_u64 v[230:231], s[34:35], 0, v[152:153]
	s_mov_b32 m0, s41
	s_nop 0
	global_load_lds_dwordx4 v[230:231], off
	s_mov_b32 m0, s42
	s_nop 0
	global_load_lds_dwordx4 v[232:233], off
	s_waitcnt vmcnt(8)
	s_waitcnt lgkmcnt(0)
	s_barrier
	s_setprio 1
	s_waitcnt lgkmcnt(0)
	v_mfma_f32_16x16x32_bf16 v[60:63], v[130:133], v[198:201], v[60:63]
	v_mfma_f32_16x16x32_bf16 v[52:55], v[138:141], v[198:201], v[52:55]
	v_mfma_f32_16x16x32_bf16 v[44:47], v[130:133], v[206:209], v[44:47]
	v_mfma_f32_16x16x32_bf16 v[36:39], v[138:141], v[206:209], v[36:39]
	v_mfma_f32_16x16x32_bf16 v[28:31], v[130:133], v[214:217], v[28:31]
	v_mfma_f32_16x16x32_bf16 v[20:23], v[138:141], v[214:217], v[20:23]
	v_mfma_f32_16x16x32_bf16 v[12:15], v[130:133], v[222:225], v[12:15]
	v_mfma_f32_16x16x32_bf16 v[4:7], v[138:141], v[222:225], v[4:7]
	v_mfma_f32_16x16x32_bf16 v[60:63], v[134:137], v[202:205], v[60:63]
	v_mfma_f32_16x16x32_bf16 v[52:55], v[142:145], v[202:205], v[52:55]
	v_mfma_f32_16x16x32_bf16 v[44:47], v[134:137], v[210:213], v[44:47]
	v_mfma_f32_16x16x32_bf16 v[36:39], v[142:145], v[210:213], v[36:39]
	v_mfma_f32_16x16x32_bf16 v[28:31], v[134:137], v[218:221], v[28:31]
	v_mfma_f32_16x16x32_bf16 v[20:23], v[142:145], v[218:221], v[20:23]
	v_mfma_f32_16x16x32_bf16 v[12:15], v[134:137], v[226:229], v[12:15]
	v_mfma_f32_16x16x32_bf16 v[4:7], v[142:145], v[226:229], v[4:7]
	s_setprio 0
	s_setprio 1
	v_mfma_f32_16x16x32_bf16 v[56:59], v[146:149], v[198:201], v[56:59]
	v_mfma_f32_16x16x32_bf16 v[48:51], v[190:193], v[198:201], v[48:51]
	v_mfma_f32_16x16x32_bf16 v[40:43], v[146:149], v[206:209], v[40:43]
	v_mfma_f32_16x16x32_bf16 v[32:35], v[190:193], v[206:209], v[32:35]
	v_mfma_f32_16x16x32_bf16 v[24:27], v[146:149], v[214:217], v[24:27]
	v_mfma_f32_16x16x32_bf16 v[16:19], v[190:193], v[214:217], v[16:19]
	v_mfma_f32_16x16x32_bf16 v[8:11], v[146:149], v[222:225], v[8:11]
	v_mfma_f32_16x16x32_bf16 v[0:3], v[190:193], v[222:225], v[0:3]
	v_mfma_f32_16x16x32_bf16 v[56:59], v[186:189], v[202:205], v[56:59]
	v_mfma_f32_16x16x32_bf16 v[48:51], v[194:197], v[202:205], v[48:51]
	v_mfma_f32_16x16x32_bf16 v[40:43], v[186:189], v[210:213], v[40:43]
	v_mfma_f32_16x16x32_bf16 v[32:35], v[194:197], v[210:213], v[32:35]
	s_barrier
	s_setprio 2
	v_mfma_f32_16x16x32_bf16 v[24:27], v[186:189], v[218:221], v[24:27]
	v_mfma_f32_16x16x32_bf16 v[16:19], v[194:197], v[218:221], v[16:19]
	v_mfma_f32_16x16x32_bf16 v[8:11], v[186:189], v[226:229], v[8:11]
	v_mfma_f32_16x16x32_bf16 v[0:3], v[194:197], v[226:229], v[0:3]
	s_setprio 0
	s_add_i32 s73, 0, 0x18000
	v_add_u32_e32 v129, s73, v173
	s_add_i32 s74, 0, 0x1c000
	ds_read_b128 v[130:133], v129
	ds_read_b128 v[134:137], v129 offset:1024
	ds_read_b128 v[138:141], v129 offset:2048
	ds_read_b128 v[142:145], v129 offset:3072
	v_add_u32_e32 v129, s74, v173
	ds_read_b128 v[146:149], v129
	ds_read_b128 v[186:189], v129 offset:1024
	ds_read_b128 v[190:193], v129 offset:2048
	ds_read_b128 v[194:197], v129 offset:3072
	s_add_u32 s34, s34, 0x80000
	s_addc_u32 s35, s35, 0
	s_mov_b32 m0, s43
	v_lshl_add_u64 v[234:235], s[34:35], 0, v[152:153]
	ds_read_b128 v[198:201], v181 offset:32768
	ds_read_b128 v[202:205], v181 offset:33792
	ds_read_b128 v[206:209], v181 offset:34816
	ds_read_b128 v[210:213], v181 offset:35840
	ds_read_b128 v[214:217], v181 offset:36864
	ds_read_b128 v[218:221], v181 offset:37888
	ds_read_b128 v[222:225], v181 offset:38912
	ds_read_b128 v[226:229], v181 offset:39936
	global_load_lds_dwordx4 v[234:235], off
	v_lshl_add_u64 v[234:235], s[34:35], 0, v[156:157]
	s_mov_b32 m0, s44
	s_nop 0
	global_load_lds_dwordx4 v[234:235], off
	s_waitcnt vmcnt(8)
	s_waitcnt lgkmcnt(0)
	s_barrier
	s_setprio 1
	s_waitcnt lgkmcnt(0)
	v_mfma_f32_16x16x32_bf16 v[124:127], v[130:133], v[198:201], v[124:127]
	v_mfma_f32_16x16x32_bf16 v[120:123], v[138:141], v[198:201], v[120:123]
	v_mfma_f32_16x16x32_bf16 v[108:111], v[130:133], v[206:209], v[108:111]
	v_mfma_f32_16x16x32_bf16 v[100:103], v[138:141], v[206:209], v[100:103]
	v_mfma_f32_16x16x32_bf16 v[92:95], v[130:133], v[214:217], v[92:95]
	v_mfma_f32_16x16x32_bf16 v[84:87], v[138:141], v[214:217], v[84:87]
	v_mfma_f32_16x16x32_bf16 v[76:79], v[130:133], v[222:225], v[76:79]
	v_mfma_f32_16x16x32_bf16 v[68:71], v[138:141], v[222:225], v[68:71]
	v_mfma_f32_16x16x32_bf16 v[124:127], v[134:137], v[202:205], v[124:127]
	v_mfma_f32_16x16x32_bf16 v[120:123], v[142:145], v[202:205], v[120:123]
	v_mfma_f32_16x16x32_bf16 v[108:111], v[134:137], v[210:213], v[108:111]
	v_mfma_f32_16x16x32_bf16 v[100:103], v[142:145], v[210:213], v[100:103]
	v_mfma_f32_16x16x32_bf16 v[92:95], v[134:137], v[218:221], v[92:95]
	v_mfma_f32_16x16x32_bf16 v[84:87], v[142:145], v[218:221], v[84:87]
	v_mfma_f32_16x16x32_bf16 v[76:79], v[134:137], v[226:229], v[76:79]
	v_mfma_f32_16x16x32_bf16 v[68:71], v[142:145], v[226:229], v[68:71]
	s_setprio 0
	s_setprio 1
	v_mfma_f32_16x16x32_bf16 v[116:119], v[146:149], v[198:201], v[116:119]
	v_mfma_f32_16x16x32_bf16 v[112:115], v[190:193], v[198:201], v[112:115]
	v_mfma_f32_16x16x32_bf16 v[104:107], v[146:149], v[206:209], v[104:107]
	v_mfma_f32_16x16x32_bf16 v[96:99], v[190:193], v[206:209], v[96:99]
	v_mfma_f32_16x16x32_bf16 v[88:91], v[146:149], v[214:217], v[88:91]
	v_mfma_f32_16x16x32_bf16 v[80:83], v[190:193], v[214:217], v[80:83]
	v_mfma_f32_16x16x32_bf16 v[72:75], v[146:149], v[222:225], v[72:75]
	v_mfma_f32_16x16x32_bf16 v[64:67], v[190:193], v[222:225], v[64:67]
	v_mfma_f32_16x16x32_bf16 v[116:119], v[186:189], v[202:205], v[116:119]
	v_mfma_f32_16x16x32_bf16 v[112:115], v[194:197], v[202:205], v[112:115]
	v_mfma_f32_16x16x32_bf16 v[104:107], v[186:189], v[210:213], v[104:107]
	v_mfma_f32_16x16x32_bf16 v[96:99], v[194:197], v[210:213], v[96:99]
	s_barrier
	s_setprio 2
	v_mfma_f32_16x16x32_bf16 v[88:91], v[186:189], v[218:221], v[88:91]
	v_mfma_f32_16x16x32_bf16 v[80:83], v[194:197], v[218:221], v[80:83]
	v_mfma_f32_16x16x32_bf16 v[72:75], v[186:189], v[226:229], v[72:75]
	v_mfma_f32_16x16x32_bf16 v[64:67], v[194:197], v[226:229], v[64:67]
	s_setprio 0
	s_add_i32 s34, s73, s67
	v_lshl_add_u64 v[150:151], v[150:151], 0, s[12:13]
	s_mov_b32 m0, s34
	ds_read_b128 v[198:201], v181 offset:49152
	ds_read_b128 v[202:205], v181 offset:50176
	ds_read_b128 v[206:209], v181 offset:51200
	ds_read_b128 v[210:213], v181 offset:52224
	ds_read_b128 v[214:217], v181 offset:53248
	ds_read_b128 v[218:221], v181 offset:54272
	ds_read_b128 v[222:225], v181 offset:55296
	ds_read_b128 v[226:229], v181 offset:56320
	global_load_lds_dwordx4 v[150:151], off
	s_add_i32 m0, s34, 0x2000
	s_add_u32 s30, s30, 0x80080
	v_lshl_add_u64 v[150:151], v[182:183], 0, s[12:13]
	s_addc_u32 s31, s31, 0
	s_add_i32 s34, s74, s67
	global_load_lds_dwordx4 v[150:151], off
	v_lshl_add_u64 v[150:151], s[30:31], 0, v[154:155]
	s_mov_b32 m0, s34
	s_nop 0
	global_load_lds_dwordx4 v[150:151], off
	v_lshl_add_u64 v[150:151], s[30:31], 0, v[158:159]
	s_add_i32 m0, s34, 0x2000
	s_nop 0
	global_load_lds_dwordx4 v[150:151], off
	v_lshl_add_u64 v[150:151], v[230:231], 0, s[12:13]
	s_mov_b32 m0, s49
	s_nop 0
	global_load_lds_dwordx4 v[150:151], off
	v_lshl_add_u64 v[150:151], v[232:233], 0, s[12:13]
	s_mov_b32 m0, s50
	s_nop 0
	global_load_lds_dwordx4 v[150:151], off
	s_waitcnt vmcnt(8)
	s_waitcnt lgkmcnt(0)
	s_barrier
	s_setprio 1
	s_waitcnt lgkmcnt(0)
	v_mfma_f32_16x16x32_bf16 v[60:63], v[130:133], v[198:201], v[60:63]
	v_mfma_f32_16x16x32_bf16 v[52:55], v[138:141], v[198:201], v[52:55]
	v_mfma_f32_16x16x32_bf16 v[44:47], v[130:133], v[206:209], v[44:47]
	v_mfma_f32_16x16x32_bf16 v[36:39], v[138:141], v[206:209], v[36:39]
	v_mfma_f32_16x16x32_bf16 v[28:31], v[130:133], v[214:217], v[28:31]
	v_mfma_f32_16x16x32_bf16 v[20:23], v[138:141], v[214:217], v[20:23]
	v_mfma_f32_16x16x32_bf16 v[12:15], v[130:133], v[222:225], v[12:15]
	v_mfma_f32_16x16x32_bf16 v[4:7], v[138:141], v[222:225], v[4:7]
	v_mfma_f32_16x16x32_bf16 v[60:63], v[134:137], v[202:205], v[60:63]
	v_mfma_f32_16x16x32_bf16 v[52:55], v[142:145], v[202:205], v[52:55]
	v_mfma_f32_16x16x32_bf16 v[44:47], v[134:137], v[210:213], v[44:47]
	v_mfma_f32_16x16x32_bf16 v[36:39], v[142:145], v[210:213], v[36:39]
	v_mfma_f32_16x16x32_bf16 v[28:31], v[134:137], v[218:221], v[28:31]
	v_mfma_f32_16x16x32_bf16 v[20:23], v[142:145], v[218:221], v[20:23]
	v_mfma_f32_16x16x32_bf16 v[12:15], v[134:137], v[226:229], v[12:15]
	v_mfma_f32_16x16x32_bf16 v[4:7], v[142:145], v[226:229], v[4:7]
	s_setprio 0
	s_setprio 1
	v_mfma_f32_16x16x32_bf16 v[56:59], v[146:149], v[198:201], v[56:59]
	v_mfma_f32_16x16x32_bf16 v[48:51], v[190:193], v[198:201], v[48:51]
	v_mfma_f32_16x16x32_bf16 v[40:43], v[146:149], v[206:209], v[40:43]
	v_mfma_f32_16x16x32_bf16 v[32:35], v[190:193], v[206:209], v[32:35]
	v_mfma_f32_16x16x32_bf16 v[24:27], v[146:149], v[214:217], v[24:27]
	v_mfma_f32_16x16x32_bf16 v[16:19], v[190:193], v[214:217], v[16:19]
	v_mfma_f32_16x16x32_bf16 v[8:11], v[146:149], v[222:225], v[8:11]
	v_mfma_f32_16x16x32_bf16 v[0:3], v[190:193], v[222:225], v[0:3]
	v_mfma_f32_16x16x32_bf16 v[56:59], v[186:189], v[202:205], v[56:59]
	v_mfma_f32_16x16x32_bf16 v[48:51], v[194:197], v[202:205], v[48:51]
	v_mfma_f32_16x16x32_bf16 v[40:43], v[186:189], v[210:213], v[40:43]
	v_mfma_f32_16x16x32_bf16 v[32:35], v[194:197], v[210:213], v[32:35]
	s_barrier
	s_setprio 2
	v_mfma_f32_16x16x32_bf16 v[24:27], v[186:189], v[218:221], v[24:27]
	v_mfma_f32_16x16x32_bf16 v[16:19], v[194:197], v[218:221], v[16:19]
	v_mfma_f32_16x16x32_bf16 v[8:11], v[186:189], v[226:229], v[8:11]
	v_mfma_f32_16x16x32_bf16 v[0:3], v[194:197], v[226:229], v[0:3]
	s_setprio 0
	s_add_i32 s72, s72, 2
	s_add_u32 s70, s70, 0x100
	s_addc_u32 s71, s71, 0
	s_add_u32 s28, s28, 0x100
	s_addc_u32 s29, s29, 0
	s_cmp_gt_u32 s72, 29
	s_cbranch_scc0 .LBB0_3122
	s_and_b64 vcc, exec, s[14:15]
	s_cbranch_vccz .LBB0_3125
	s_barrier

.LBB0_3281:
	ds_read_b128 v[128:131], v231
	ds_read_b128 v[132:135], v231 offset:1024
	ds_read_b128 v[136:139], v231 offset:2048
	ds_read_b128 v[140:143], v231 offset:3072
	ds_read_b128 v[144:147], v232
	ds_read_b128 v[148:151], v232 offset:1024
	ds_read_b128 v[152:155], v232 offset:2048
	ds_read_b128 v[174:177], v232 offset:3072
	s_add_u32 s24, s22, 0xfff80080
	s_addc_u32 s25, s23, -1
	s_cmp_eq_u32 s30, 28
	s_cselect_b32 s27, s3, s25
	s_cselect_b32 s26, s15, s24
	s_cselect_b32 s25, s13, s29
	s_cselect_b32 s24, s21, s28
	v_lshl_add_u64 v[210:211], s[22:23], 0, v[168:169]
	s_add_i32 m0, s40, 0xc000
	ds_read_b128 v[178:181], v233
	ds_read_b128 v[182:185], v233 offset:1024
	ds_read_b128 v[186:189], v233 offset:2048
	ds_read_b128 v[190:193], v233 offset:3072
	ds_read_b128 v[194:197], v233 offset:4096
	ds_read_b128 v[198:201], v233 offset:5120
	ds_read_b128 v[202:205], v233 offset:6144
	ds_read_b128 v[206:209], v233 offset:7168
	global_load_lds_dwordx4 v[210:211], off
	v_lshl_add_u64 v[210:211], s[22:23], 0, v[166:167]
	s_add_i32 m0, s40, 0xe000
	s_nop 0
	global_load_lds_dwordx4 v[210:211], off
	s_waitcnt vmcnt(8)
	s_waitcnt lgkmcnt(0)
	s_barrier
	s_setprio 1
	s_waitcnt lgkmcnt(0)
	v_mfma_f32_16x16x32_bf16 v[124:127], v[128:131], v[178:181], v[124:127]
	v_mfma_f32_16x16x32_bf16 v[120:123], v[136:139], v[178:181], v[120:123]
	v_mfma_f32_16x16x32_bf16 v[116:119], v[128:131], v[186:189], v[116:119]
	v_mfma_f32_16x16x32_bf16 v[112:115], v[136:139], v[186:189], v[112:115]
	v_mfma_f32_16x16x32_bf16 v[108:111], v[128:131], v[194:197], v[108:111]
	v_mfma_f32_16x16x32_bf16 v[104:107], v[136:139], v[194:197], v[104:107]
	v_mfma_f32_16x16x32_bf16 v[100:103], v[128:131], v[202:205], v[100:103]
	v_mfma_f32_16x16x32_bf16 v[96:99], v[136:139], v[202:205], v[96:99]
	v_mfma_f32_16x16x32_bf16 v[124:127], v[132:135], v[182:185], v[124:127]
	v_mfma_f32_16x16x32_bf16 v[120:123], v[140:143], v[182:185], v[120:123]
	v_mfma_f32_16x16x32_bf16 v[116:119], v[132:135], v[190:193], v[116:119]
	v_mfma_f32_16x16x32_bf16 v[112:115], v[140:143], v[190:193], v[112:115]
	v_mfma_f32_16x16x32_bf16 v[108:111], v[132:135], v[198:201], v[108:111]
	v_mfma_f32_16x16x32_bf16 v[104:107], v[140:143], v[198:201], v[104:107]
	v_mfma_f32_16x16x32_bf16 v[100:103], v[132:135], v[206:209], v[100:103]
	v_mfma_f32_16x16x32_bf16 v[96:99], v[140:143], v[206:209], v[96:99]
	s_setprio 0
	s_setprio 1
	v_mfma_f32_16x16x32_bf16 v[60:63], v[144:147], v[178:181], v[60:63]
	v_mfma_f32_16x16x32_bf16 v[56:59], v[152:155], v[178:181], v[56:59]
	v_mfma_f32_16x16x32_bf16 v[52:55], v[144:147], v[186:189], v[52:55]
	v_mfma_f32_16x16x32_bf16 v[48:51], v[152:155], v[186:189], v[48:51]
	v_mfma_f32_16x16x32_bf16 v[44:47], v[144:147], v[194:197], v[44:47]
	v_mfma_f32_16x16x32_bf16 v[40:43], v[152:155], v[194:197], v[40:43]
	v_mfma_f32_16x16x32_bf16 v[36:39], v[144:147], v[202:205], v[36:39]
	v_mfma_f32_16x16x32_bf16 v[32:35], v[152:155], v[202:205], v[32:35]
	v_mfma_f32_16x16x32_bf16 v[60:63], v[148:151], v[182:185], v[60:63]
	v_mfma_f32_16x16x32_bf16 v[56:59], v[174:177], v[182:185], v[56:59]
	v_mfma_f32_16x16x32_bf16 v[52:55], v[148:151], v[190:193], v[52:55]
	v_mfma_f32_16x16x32_bf16 v[48:51], v[174:177], v[190:193], v[48:51]
	s_barrier
	s_setprio 2
	v_mfma_f32_16x16x32_bf16 v[44:47], v[148:151], v[198:201], v[44:47]
	v_mfma_f32_16x16x32_bf16 v[40:43], v[174:177], v[198:201], v[40:43]
	v_mfma_f32_16x16x32_bf16 v[36:39], v[148:151], v[206:209], v[36:39]
	v_mfma_f32_16x16x32_bf16 v[32:35], v[174:177], v[206:209], v[32:35]
	s_setprio 0
	s_add_i32 s31, s64, s67
	v_lshl_add_u64 v[210:211], s[24:25], 0, v[158:159]
	s_mov_b32 m0, s31
	ds_read_b128 v[178:181], v233 offset:16384
	ds_read_b128 v[182:185], v233 offset:17408
	ds_read_b128 v[186:189], v233 offset:18432
	ds_read_b128 v[190:193], v233 offset:19456
	ds_read_b128 v[194:197], v233 offset:20480
	ds_read_b128 v[198:201], v233 offset:21504
	ds_read_b128 v[202:205], v233 offset:22528
	ds_read_b128 v[206:209], v233 offset:23552
	global_load_lds_dwordx4 v[210:211], off
	s_add_i32 m0, s31, 0x2000
	s_add_u32 s34, s24, 0x80000
	v_lshl_add_u64 v[212:213], s[24:25], 0, v[162:163]
	s_addc_u32 s35, s25, 0
	s_add_i32 s31, s65, s67
	global_load_lds_dwordx4 v[212:213], off
	v_lshl_add_u64 v[214:215], s[34:35], 0, v[158:159]
	s_mov_b32 m0, s31
	v_lshl_add_u64 v[216:217], s[26:27], 0, v[160:161]
	global_load_lds_dwordx4 v[214:215], off
	v_lshl_add_u64 v[214:215], s[34:35], 0, v[162:163]
	s_add_i32 m0, s31, 0x2000
	s_nop 0
	global_load_lds_dwordx4 v[214:215], off
	v_lshl_add_u64 v[214:215], s[26:27], 0, v[156:157]
	s_mov_b32 m0, s40
	s_nop 0
	global_load_lds_dwordx4 v[214:215], off
	s_mov_b32 m0, s41
	s_nop 0
	global_load_lds_dwordx4 v[216:217], off
	s_waitcnt vmcnt(8)
	s_waitcnt lgkmcnt(0)
	s_barrier
	s_setprio 1
	s_waitcnt lgkmcnt(0)
	v_mfma_f32_16x16x32_bf16 v[92:95], v[128:131], v[178:181], v[92:95]
	v_mfma_f32_16x16x32_bf16 v[88:91], v[136:139], v[178:181], v[88:91]
	v_mfma_f32_16x16x32_bf16 v[84:87], v[128:131], v[186:189], v[84:87]
	v_mfma_f32_16x16x32_bf16 v[80:83], v[136:139], v[186:189], v[80:83]
	v_mfma_f32_16x16x32_bf16 v[76:79], v[128:131], v[194:197], v[76:79]
	v_mfma_f32_16x16x32_bf16 v[72:75], v[136:139], v[194:197], v[72:75]
	v_mfma_f32_16x16x32_bf16 v[68:71], v[128:131], v[202:205], v[68:71]
	v_mfma_f32_16x16x32_bf16 v[64:67], v[136:139], v[202:205], v[64:67]
	v_mfma_f32_16x16x32_bf16 v[92:95], v[132:135], v[182:185], v[92:95]
	v_mfma_f32_16x16x32_bf16 v[88:91], v[140:143], v[182:185], v[88:91]
	v_mfma_f32_16x16x32_bf16 v[84:87], v[132:135], v[190:193], v[84:87]
	v_mfma_f32_16x16x32_bf16 v[80:83], v[140:143], v[190:193], v[80:83]
	v_mfma_f32_16x16x32_bf16 v[76:79], v[132:135], v[198:201], v[76:79]
	v_mfma_f32_16x16x32_bf16 v[72:75], v[140:143], v[198:201], v[72:75]
	v_mfma_f32_16x16x32_bf16 v[68:71], v[132:135], v[206:209], v[68:71]
	v_mfma_f32_16x16x32_bf16 v[64:67], v[140:143], v[206:209], v[64:67]
	s_setprio 0
	s_setprio 1
	v_mfma_f32_16x16x32_bf16 v[28:31], v[144:147], v[178:181], v[28:31]
	v_mfma_f32_16x16x32_bf16 v[24:27], v[152:155], v[178:181], v[24:27]
	v_mfma_f32_16x16x32_bf16 v[20:23], v[144:147], v[186:189], v[20:23]
	v_mfma_f32_16x16x32_bf16 v[16:19], v[152:155], v[186:189], v[16:19]
	v_mfma_f32_16x16x32_bf16 v[12:15], v[144:147], v[194:197], v[12:15]
	v_mfma_f32_16x16x32_bf16 v[8:11], v[152:155], v[194:197], v[8:11]
	v_mfma_f32_16x16x32_bf16 v[4:7], v[144:147], v[202:205], v[4:7]
	v_mfma_f32_16x16x32_bf16 v[0:3], v[152:155], v[202:205], v[0:3]
	v_mfma_f32_16x16x32_bf16 v[28:31], v[148:151], v[182:185], v[28:31]
	v_mfma_f32_16x16x32_bf16 v[24:27], v[174:177], v[182:185], v[24:27]
	v_mfma_f32_16x16x32_bf16 v[20:23], v[148:151], v[190:193], v[20:23]
	v_mfma_f32_16x16x32_bf16 v[16:19], v[174:177], v[190:193], v[16:19]
	s_barrier
	s_setprio 2
	v_mfma_f32_16x16x32_bf16 v[12:15], v[148:151], v[198:201], v[12:15]
	v_mfma_f32_16x16x32_bf16 v[8:11], v[174:177], v[198:201], v[8:11]
	v_mfma_f32_16x16x32_bf16 v[4:7], v[148:151], v[206:209], v[4:7]
	v_mfma_f32_16x16x32_bf16 v[0:3], v[174:177], v[206:209], v[0:3]
	s_setprio 0
	s_add_i32 s31, 0, 0x18000
	s_add_i32 s34, 0, 0x1c000
	v_add_u32_e32 v140, s31, v230
	v_add_u32_e32 v164, s34, v230
	ds_read_b128 v[128:131], v140
	ds_read_b128 v[132:135], v140 offset:1024
	ds_read_b128 v[136:139], v140 offset:2048
	ds_read_b128 v[140:143], v140 offset:3072
	ds_read_b128 v[144:147], v164
	ds_read_b128 v[148:151], v164 offset:1024
	ds_read_b128 v[152:155], v164 offset:2048
	ds_read_b128 v[174:177], v164 offset:3072
	s_add_u32 s26, s26, 0x80000
	s_addc_u32 s27, s27, 0
	s_mov_b32 m0, s42
	v_lshl_add_u64 v[218:219], s[26:27], 0, v[156:157]
	ds_read_b128 v[178:181], v233 offset:32768
	ds_read_b128 v[182:185], v233 offset:33792
	ds_read_b128 v[186:189], v233 offset:34816
	ds_read_b128 v[190:193], v233 offset:35840
	ds_read_b128 v[194:197], v233 offset:36864
	ds_read_b128 v[198:201], v233 offset:37888
	ds_read_b128 v[202:205], v233 offset:38912
	ds_read_b128 v[206:209], v233 offset:39936
	global_load_lds_dwordx4 v[218:219], off
	v_lshl_add_u64 v[218:219], s[26:27], 0, v[160:161]
	s_mov_b32 m0, s43
	s_nop 0
	global_load_lds_dwordx4 v[218:219], off
	s_waitcnt vmcnt(8)
	s_waitcnt lgkmcnt(0)
	s_barrier
	s_setprio 1
	s_waitcnt lgkmcnt(0)
	v_mfma_f32_16x16x32_bf16 v[124:127], v[128:131], v[178:181], v[124:127]
	v_mfma_f32_16x16x32_bf16 v[120:123], v[136:139], v[178:181], v[120:123]
	v_mfma_f32_16x16x32_bf16 v[116:119], v[128:131], v[186:189], v[116:119]
	v_mfma_f32_16x16x32_bf16 v[112:115], v[136:139], v[186:189], v[112:115]
	v_mfma_f32_16x16x32_bf16 v[108:111], v[128:131], v[194:197], v[108:111]
	v_mfma_f32_16x16x32_bf16 v[104:107], v[136:139], v[194:197], v[104:107]
	v_mfma_f32_16x16x32_bf16 v[100:103], v[128:131], v[202:205], v[100:103]
	v_mfma_f32_16x16x32_bf16 v[96:99], v[136:139], v[202:205], v[96:99]
	v_mfma_f32_16x16x32_bf16 v[124:127], v[132:135], v[182:185], v[124:127]
	v_mfma_f32_16x16x32_bf16 v[120:123], v[140:143], v[182:185], v[120:123]
	v_mfma_f32_16x16x32_bf16 v[116:119], v[132:135], v[190:193], v[116:119]
	v_mfma_f32_16x16x32_bf16 v[112:115], v[140:143], v[190:193], v[112:115]
	v_mfma_f32_16x16x32_bf16 v[108:111], v[132:135], v[198:201], v[108:111]
	v_mfma_f32_16x16x32_bf16 v[104:107], v[140:143], v[198:201], v[104:107]
	v_mfma_f32_16x16x32_bf16 v[100:103], v[132:135], v[206:209], v[100:103]
	v_mfma_f32_16x16x32_bf16 v[96:99], v[140:143], v[206:209], v[96:99]
	s_setprio 0
	s_setprio 1
	v_mfma_f32_16x16x32_bf16 v[60:63], v[144:147], v[178:181], v[60:63]
	v_mfma_f32_16x16x32_bf16 v[56:59], v[152:155], v[178:181], v[56:59]
	v_mfma_f32_16x16x32_bf16 v[52:55], v[144:147], v[186:189], v[52:55]
	v_mfma_f32_16x16x32_bf16 v[48:51], v[152:155], v[186:189], v[48:51]
	v_mfma_f32_16x16x32_bf16 v[44:47], v[144:147], v[194:197], v[44:47]
	v_mfma_f32_16x16x32_bf16 v[40:43], v[152:155], v[194:197], v[40:43]
	v_mfma_f32_16x16x32_bf16 v[36:39], v[144:147], v[202:205], v[36:39]
	v_mfma_f32_16x16x32_bf16 v[32:35], v[152:155], v[202:205], v[32:35]
	v_mfma_f32_16x16x32_bf16 v[60:63], v[148:151], v[182:185], v[60:63]
	v_mfma_f32_16x16x32_bf16 v[56:59], v[174:177], v[182:185], v[56:59]
	v_mfma_f32_16x16x32_bf16 v[52:55], v[148:151], v[190:193], v[52:55]
	v_mfma_f32_16x16x32_bf16 v[48:51], v[174:177], v[190:193], v[48:51]
	s_barrier
	s_setprio 2
	v_mfma_f32_16x16x32_bf16 v[44:47], v[148:151], v[198:201], v[44:47]
	v_mfma_f32_16x16x32_bf16 v[40:43], v[174:177], v[198:201], v[40:43]
	v_mfma_f32_16x16x32_bf16 v[36:39], v[148:151], v[206:209], v[36:39]
	v_mfma_f32_16x16x32_bf16 v[32:35], v[174:177], v[206:209], v[32:35]
	s_setprio 0
	s_add_i32 s26, s31, s67
	v_lshl_add_u64 v[210:211], v[210:211], 0, s[6:7]
	s_mov_b32 m0, s26
	ds_read_b128 v[178:181], v233 offset:49152
	ds_read_b128 v[182:185], v233 offset:50176
	ds_read_b128 v[186:189], v233 offset:51200
	ds_read_b128 v[190:193], v233 offset:52224
	ds_read_b128 v[194:197], v233 offset:53248
	ds_read_b128 v[198:201], v233 offset:54272
	ds_read_b128 v[202:205], v233 offset:55296
	ds_read_b128 v[206:209], v233 offset:56320
	global_load_lds_dwordx4 v[210:211], off
	s_add_i32 m0, s26, 0x2000
	s_add_u32 s24, s24, 0x80080
	v_lshl_add_u64 v[210:211], v[212:213], 0, s[6:7]
	s_addc_u32 s25, s25, 0
	s_add_i32 s26, s34, s67
	global_load_lds_dwordx4 v[210:211], off
	v_lshl_add_u64 v[210:211], s[24:25], 0, v[158:159]
	s_mov_b32 m0, s26
	s_nop 0
	global_load_lds_dwordx4 v[210:211], off
	v_lshl_add_u64 v[210:211], s[24:25], 0, v[162:163]
	s_add_i32 m0, s26, 0x2000
	s_nop 0
	global_load_lds_dwordx4 v[210:211], off
	v_lshl_add_u64 v[210:211], v[214:215], 0, s[6:7]
	s_mov_b32 m0, s57
	s_nop 0
	global_load_lds_dwordx4 v[210:211], off
	v_lshl_add_u64 v[210:211], v[216:217], 0, s[6:7]
	s_mov_b32 m0, s58
	s_nop 0
	global_load_lds_dwordx4 v[210:211], off
	s_waitcnt vmcnt(8)
	s_waitcnt lgkmcnt(0)
	s_barrier
	s_setprio 1
	s_waitcnt lgkmcnt(0)
	v_mfma_f32_16x16x32_bf16 v[92:95], v[128:131], v[178:181], v[92:95]
	v_mfma_f32_16x16x32_bf16 v[88:91], v[136:139], v[178:181], v[88:91]
	v_mfma_f32_16x16x32_bf16 v[84:87], v[128:131], v[186:189], v[84:87]
	v_mfma_f32_16x16x32_bf16 v[80:83], v[136:139], v[186:189], v[80:83]
	v_mfma_f32_16x16x32_bf16 v[76:79], v[128:131], v[194:197], v[76:79]
	v_mfma_f32_16x16x32_bf16 v[72:75], v[136:139], v[194:197], v[72:75]
	v_mfma_f32_16x16x32_bf16 v[68:71], v[128:131], v[202:205], v[68:71]
	v_mfma_f32_16x16x32_bf16 v[64:67], v[136:139], v[202:205], v[64:67]
	v_mfma_f32_16x16x32_bf16 v[92:95], v[132:135], v[182:185], v[92:95]
	v_mfma_f32_16x16x32_bf16 v[88:91], v[140:143], v[182:185], v[88:91]
	v_mfma_f32_16x16x32_bf16 v[84:87], v[132:135], v[190:193], v[84:87]
	v_mfma_f32_16x16x32_bf16 v[80:83], v[140:143], v[190:193], v[80:83]
	v_mfma_f32_16x16x32_bf16 v[76:79], v[132:135], v[198:201], v[76:79]
	v_mfma_f32_16x16x32_bf16 v[72:75], v[140:143], v[198:201], v[72:75]
	v_mfma_f32_16x16x32_bf16 v[68:71], v[132:135], v[206:209], v[68:71]
	v_mfma_f32_16x16x32_bf16 v[64:67], v[140:143], v[206:209], v[64:67]
	s_setprio 0
	s_setprio 1
	v_mfma_f32_16x16x32_bf16 v[28:31], v[144:147], v[178:181], v[28:31]
	v_mfma_f32_16x16x32_bf16 v[24:27], v[152:155], v[178:181], v[24:27]
	v_mfma_f32_16x16x32_bf16 v[20:23], v[144:147], v[186:189], v[20:23]
	v_mfma_f32_16x16x32_bf16 v[16:19], v[152:155], v[186:189], v[16:19]
	v_mfma_f32_16x16x32_bf16 v[12:15], v[144:147], v[194:197], v[12:15]
	v_mfma_f32_16x16x32_bf16 v[8:11], v[152:155], v[194:197], v[8:11]
	v_mfma_f32_16x16x32_bf16 v[4:7], v[144:147], v[202:205], v[4:7]
	v_mfma_f32_16x16x32_bf16 v[0:3], v[152:155], v[202:205], v[0:3]
	v_mfma_f32_16x16x32_bf16 v[28:31], v[148:151], v[182:185], v[28:31]
	v_mfma_f32_16x16x32_bf16 v[24:27], v[174:177], v[182:185], v[24:27]
	v_mfma_f32_16x16x32_bf16 v[20:23], v[148:151], v[190:193], v[20:23]
	v_mfma_f32_16x16x32_bf16 v[16:19], v[174:177], v[190:193], v[16:19]
	s_barrier
	s_setprio 2
	v_mfma_f32_16x16x32_bf16 v[12:15], v[148:151], v[198:201], v[12:15]
	v_mfma_f32_16x16x32_bf16 v[8:11], v[174:177], v[198:201], v[8:11]
	v_mfma_f32_16x16x32_bf16 v[4:7], v[148:151], v[206:209], v[4:7]
	v_mfma_f32_16x16x32_bf16 v[0:3], v[174:177], v[206:209], v[0:3]
	s_setprio 0
	s_add_i32 s30, s30, 2
	s_add_u32 s28, s28, 0x100
	s_addc_u32 s29, s29, 0
	s_add_u32 s22, s22, 0x100
	s_addc_u32 s23, s23, 0
	s_cmp_gt_u32 s30, 29
	s_cbranch_scc0 .LBB0_3281
	s_and_b64 vcc, exec, s[8:9]
	s_cbranch_vccz .LBB0_3284
	s_barrier

.LBB0_3501:
	ds_read_b128 v[128:131], v201
	ds_read_b128 v[132:135], v201 offset:1024
	ds_read_b128 v[136:139], v201 offset:2048
	ds_read_b128 v[140:143], v201 offset:3072
	ds_read_b128 v[144:147], v202
	ds_read_b128 v[148:151], v202 offset:1024
	ds_read_b128 v[170:173], v202 offset:2048
	ds_read_b128 v[174:177], v202 offset:3072
	s_add_u32 s18, s16, 0x100
	s_addc_u32 s19, s17, 0
	s_cmpk_eq_i32 s68, 0x54
	s_cselect_b32 s23, s3, s19
	s_cselect_b32 s22, s2, s18
	s_cselect_b32 s21, s15, s25
	s_cselect_b32 s20, s14, s24
	v_lshl_add_u64 v[198:199], s[16:17], 0, v[164:165]
	s_add_i32 m0, s30, 0xc000
	ds_read_b128 v[178:181], v203
	ds_read_b128 v[182:185], v203 offset:1024
	ds_read_b128 v[186:189], v203 offset:2048
	ds_read_b128 v[190:193], v203 offset:3072
	ds_read_b128 v[194:197], v203 offset:4096
	ds_read_b128 v[206:209], v203 offset:5120
	ds_read_b128 v[210:213], v203 offset:6144
	ds_read_b128 v[214:217], v203 offset:7168
	global_load_lds_dwordx4 v[198:199], off
	v_lshl_add_u64 v[198:199], s[16:17], 0, v[162:163]
	s_add_i32 m0, s30, 0xe000
	s_nop 0
	global_load_lds_dwordx4 v[198:199], off
	s_waitcnt vmcnt(8)
	s_waitcnt lgkmcnt(0)
	s_barrier
	s_setprio 1
	s_waitcnt lgkmcnt(0)
	v_mfma_f32_16x16x32_bf16 v[124:127], v[128:131], v[178:181], v[124:127]
	v_mfma_f32_16x16x32_bf16 v[120:123], v[136:139], v[178:181], v[120:123]
	v_mfma_f32_16x16x32_bf16 v[116:119], v[128:131], v[186:189], v[116:119]
	v_mfma_f32_16x16x32_bf16 v[112:115], v[136:139], v[186:189], v[112:115]
	v_mfma_f32_16x16x32_bf16 v[108:111], v[128:131], v[194:197], v[108:111]
	v_mfma_f32_16x16x32_bf16 v[104:107], v[136:139], v[194:197], v[104:107]
	v_mfma_f32_16x16x32_bf16 v[100:103], v[128:131], v[210:213], v[100:103]
	v_mfma_f32_16x16x32_bf16 v[96:99], v[136:139], v[210:213], v[96:99]
	v_mfma_f32_16x16x32_bf16 v[124:127], v[132:135], v[182:185], v[124:127]
	v_mfma_f32_16x16x32_bf16 v[120:123], v[140:143], v[182:185], v[120:123]
	v_mfma_f32_16x16x32_bf16 v[116:119], v[132:135], v[190:193], v[116:119]
	v_mfma_f32_16x16x32_bf16 v[112:115], v[140:143], v[190:193], v[112:115]
	v_mfma_f32_16x16x32_bf16 v[108:111], v[132:135], v[206:209], v[108:111]
	v_mfma_f32_16x16x32_bf16 v[104:107], v[140:143], v[206:209], v[104:107]
	v_mfma_f32_16x16x32_bf16 v[100:103], v[132:135], v[214:217], v[100:103]
	v_mfma_f32_16x16x32_bf16 v[96:99], v[140:143], v[214:217], v[96:99]
	s_setprio 0
	s_setprio 1
	v_mfma_f32_16x16x32_bf16 v[60:63], v[144:147], v[178:181], v[60:63]
	v_mfma_f32_16x16x32_bf16 v[56:59], v[170:173], v[178:181], v[56:59]
	v_mfma_f32_16x16x32_bf16 v[52:55], v[144:147], v[186:189], v[52:55]
	v_mfma_f32_16x16x32_bf16 v[48:51], v[170:173], v[186:189], v[48:51]
	v_mfma_f32_16x16x32_bf16 v[44:47], v[144:147], v[194:197], v[44:47]
	v_mfma_f32_16x16x32_bf16 v[40:43], v[170:173], v[194:197], v[40:43]
	v_mfma_f32_16x16x32_bf16 v[36:39], v[144:147], v[210:213], v[36:39]
	v_mfma_f32_16x16x32_bf16 v[32:35], v[170:173], v[210:213], v[32:35]
	v_mfma_f32_16x16x32_bf16 v[60:63], v[148:151], v[182:185], v[60:63]
	v_mfma_f32_16x16x32_bf16 v[56:59], v[174:177], v[182:185], v[56:59]
	v_mfma_f32_16x16x32_bf16 v[52:55], v[148:151], v[190:193], v[52:55]
	v_mfma_f32_16x16x32_bf16 v[48:51], v[174:177], v[190:193], v[48:51]
	s_barrier
	s_setprio 2
	v_mfma_f32_16x16x32_bf16 v[44:47], v[148:151], v[206:209], v[44:47]
	v_mfma_f32_16x16x32_bf16 v[40:43], v[174:177], v[206:209], v[40:43]
	v_mfma_f32_16x16x32_bf16 v[36:39], v[148:151], v[214:217], v[36:39]
	v_mfma_f32_16x16x32_bf16 v[32:35], v[174:177], v[214:217], v[32:35]
	s_setprio 0
	s_add_i32 s16, s52, s67
	v_lshl_add_u64 v[198:199], s[20:21], 0, v[154:155]
	s_mov_b32 m0, s16
	ds_read_b128 v[178:181], v203 offset:16384
	ds_read_b128 v[182:185], v203 offset:17408
	ds_read_b128 v[186:189], v203 offset:18432
	ds_read_b128 v[190:193], v203 offset:19456
	ds_read_b128 v[194:197], v203 offset:20480
	ds_read_b128 v[206:209], v203 offset:21504
	ds_read_b128 v[210:213], v203 offset:22528
	ds_read_b128 v[214:217], v203 offset:23552
	global_load_lds_dwordx4 v[198:199], off
	s_add_i32 m0, s16, 0x2000
	s_add_u32 s16, s20, 0x160000
	v_lshl_add_u64 v[218:219], s[20:21], 0, v[158:159]
	s_addc_u32 s17, s21, 0
	s_add_i32 s69, s53, s67
	global_load_lds_dwordx4 v[218:219], off
	v_lshl_add_u64 v[220:221], s[16:17], 0, v[154:155]
	s_mov_b32 m0, s69
	v_lshl_add_u64 v[222:223], s[22:23], 0, v[156:157]
	global_load_lds_dwordx4 v[220:221], off
	v_lshl_add_u64 v[220:221], s[16:17], 0, v[158:159]
	s_add_i32 m0, s69, 0x2000
	s_nop 0
	global_load_lds_dwordx4 v[220:221], off
	v_lshl_add_u64 v[220:221], s[22:23], 0, v[152:153]
	s_mov_b32 m0, s30
	s_nop 0
	global_load_lds_dwordx4 v[220:221], off
	s_mov_b32 m0, s31
	s_nop 0
	global_load_lds_dwordx4 v[222:223], off
	s_waitcnt vmcnt(8)
	s_waitcnt lgkmcnt(0)
	s_barrier
	s_setprio 1
	s_waitcnt lgkmcnt(0)
	v_mfma_f32_16x16x32_bf16 v[92:95], v[128:131], v[178:181], v[92:95]
	v_mfma_f32_16x16x32_bf16 v[88:91], v[136:139], v[178:181], v[88:91]
	v_mfma_f32_16x16x32_bf16 v[84:87], v[128:131], v[186:189], v[84:87]
	v_mfma_f32_16x16x32_bf16 v[80:83], v[136:139], v[186:189], v[80:83]
	v_mfma_f32_16x16x32_bf16 v[76:79], v[128:131], v[194:197], v[76:79]
	v_mfma_f32_16x16x32_bf16 v[72:75], v[136:139], v[194:197], v[72:75]
	v_mfma_f32_16x16x32_bf16 v[68:71], v[128:131], v[210:213], v[68:71]
	v_mfma_f32_16x16x32_bf16 v[64:67], v[136:139], v[210:213], v[64:67]
	v_mfma_f32_16x16x32_bf16 v[92:95], v[132:135], v[182:185], v[92:95]
	v_mfma_f32_16x16x32_bf16 v[88:91], v[140:143], v[182:185], v[88:91]
	v_mfma_f32_16x16x32_bf16 v[84:87], v[132:135], v[190:193], v[84:87]
	v_mfma_f32_16x16x32_bf16 v[80:83], v[140:143], v[190:193], v[80:83]
	v_mfma_f32_16x16x32_bf16 v[76:79], v[132:135], v[206:209], v[76:79]
	v_mfma_f32_16x16x32_bf16 v[72:75], v[140:143], v[206:209], v[72:75]
	v_mfma_f32_16x16x32_bf16 v[68:71], v[132:135], v[214:217], v[68:71]
	v_mfma_f32_16x16x32_bf16 v[64:67], v[140:143], v[214:217], v[64:67]
	s_setprio 0
	s_setprio 1
	v_mfma_f32_16x16x32_bf16 v[28:31], v[144:147], v[178:181], v[28:31]
	v_mfma_f32_16x16x32_bf16 v[24:27], v[170:173], v[178:181], v[24:27]
	v_mfma_f32_16x16x32_bf16 v[20:23], v[144:147], v[186:189], v[20:23]
	v_mfma_f32_16x16x32_bf16 v[16:19], v[170:173], v[186:189], v[16:19]
	v_mfma_f32_16x16x32_bf16 v[12:15], v[144:147], v[194:197], v[12:15]
	v_mfma_f32_16x16x32_bf16 v[8:11], v[170:173], v[194:197], v[8:11]
	v_mfma_f32_16x16x32_bf16 v[4:7], v[144:147], v[210:213], v[4:7]
	v_mfma_f32_16x16x32_bf16 v[0:3], v[170:173], v[210:213], v[0:3]
	v_mfma_f32_16x16x32_bf16 v[28:31], v[148:151], v[182:185], v[28:31]
	v_mfma_f32_16x16x32_bf16 v[24:27], v[174:177], v[182:185], v[24:27]
	v_mfma_f32_16x16x32_bf16 v[20:23], v[148:151], v[190:193], v[20:23]
	v_mfma_f32_16x16x32_bf16 v[16:19], v[174:177], v[190:193], v[16:19]
	s_barrier
	s_setprio 2
	v_mfma_f32_16x16x32_bf16 v[12:15], v[148:151], v[206:209], v[12:15]
	v_mfma_f32_16x16x32_bf16 v[8:11], v[174:177], v[206:209], v[8:11]
	v_mfma_f32_16x16x32_bf16 v[4:7], v[148:151], v[214:217], v[4:7]
	v_mfma_f32_16x16x32_bf16 v[0:3], v[174:177], v[214:217], v[0:3]
	s_setprio 0
	s_add_i32 s69, 0, 0x18000
	s_add_i32 s70, 0, 0x1c000
	v_add_u32_e32 v140, s69, v200
	v_add_u32_e32 v160, s70, v200
	ds_read_b128 v[128:131], v140
	ds_read_b128 v[132:135], v140 offset:1024
	ds_read_b128 v[136:139], v140 offset:2048
	ds_read_b128 v[140:143], v140 offset:3072
	ds_read_b128 v[144:147], v160
	ds_read_b128 v[148:151], v160 offset:1024
	ds_read_b128 v[170:173], v160 offset:2048
	ds_read_b128 v[174:177], v160 offset:3072
	s_add_u32 s16, s22, 0x160000
	s_addc_u32 s17, s23, 0
	s_mov_b32 m0, s34
	v_lshl_add_u64 v[224:225], s[16:17], 0, v[152:153]
	ds_read_b128 v[178:181], v203 offset:32768
	ds_read_b128 v[182:185], v203 offset:33792
	ds_read_b128 v[186:189], v203 offset:34816
	ds_read_b128 v[190:193], v203 offset:35840
	ds_read_b128 v[194:197], v203 offset:36864
	ds_read_b128 v[206:209], v203 offset:37888
	ds_read_b128 v[210:213], v203 offset:38912
	ds_read_b128 v[214:217], v203 offset:39936
	global_load_lds_dwordx4 v[224:225], off
	v_lshl_add_u64 v[224:225], s[16:17], 0, v[156:157]
	s_mov_b32 m0, s35
	s_nop 0
	global_load_lds_dwordx4 v[224:225], off
	s_waitcnt vmcnt(8)
	s_waitcnt lgkmcnt(0)
	s_barrier
	s_setprio 1
	s_waitcnt lgkmcnt(0)
	v_mfma_f32_16x16x32_bf16 v[124:127], v[128:131], v[178:181], v[124:127]
	v_mfma_f32_16x16x32_bf16 v[120:123], v[136:139], v[178:181], v[120:123]
	v_mfma_f32_16x16x32_bf16 v[116:119], v[128:131], v[186:189], v[116:119]
	v_mfma_f32_16x16x32_bf16 v[112:115], v[136:139], v[186:189], v[112:115]
	v_mfma_f32_16x16x32_bf16 v[108:111], v[128:131], v[194:197], v[108:111]
	v_mfma_f32_16x16x32_bf16 v[104:107], v[136:139], v[194:197], v[104:107]
	v_mfma_f32_16x16x32_bf16 v[100:103], v[128:131], v[210:213], v[100:103]
	v_mfma_f32_16x16x32_bf16 v[96:99], v[136:139], v[210:213], v[96:99]
	v_mfma_f32_16x16x32_bf16 v[124:127], v[132:135], v[182:185], v[124:127]
	v_mfma_f32_16x16x32_bf16 v[120:123], v[140:143], v[182:185], v[120:123]
	v_mfma_f32_16x16x32_bf16 v[116:119], v[132:135], v[190:193], v[116:119]
	v_mfma_f32_16x16x32_bf16 v[112:115], v[140:143], v[190:193], v[112:115]
	v_mfma_f32_16x16x32_bf16 v[108:111], v[132:135], v[206:209], v[108:111]
	v_mfma_f32_16x16x32_bf16 v[104:107], v[140:143], v[206:209], v[104:107]
	v_mfma_f32_16x16x32_bf16 v[100:103], v[132:135], v[214:217], v[100:103]
	v_mfma_f32_16x16x32_bf16 v[96:99], v[140:143], v[214:217], v[96:99]
	s_setprio 0
	s_setprio 1
	v_mfma_f32_16x16x32_bf16 v[60:63], v[144:147], v[178:181], v[60:63]
	v_mfma_f32_16x16x32_bf16 v[56:59], v[170:173], v[178:181], v[56:59]
	v_mfma_f32_16x16x32_bf16 v[52:55], v[144:147], v[186:189], v[52:55]
	v_mfma_f32_16x16x32_bf16 v[48:51], v[170:173], v[186:189], v[48:51]
	v_mfma_f32_16x16x32_bf16 v[44:47], v[144:147], v[194:197], v[44:47]
	v_mfma_f32_16x16x32_bf16 v[40:43], v[170:173], v[194:197], v[40:43]
	v_mfma_f32_16x16x32_bf16 v[36:39], v[144:147], v[210:213], v[36:39]
	v_mfma_f32_16x16x32_bf16 v[32:35], v[170:173], v[210:213], v[32:35]
	v_mfma_f32_16x16x32_bf16 v[60:63], v[148:151], v[182:185], v[60:63]
	v_mfma_f32_16x16x32_bf16 v[56:59], v[174:177], v[182:185], v[56:59]
	v_mfma_f32_16x16x32_bf16 v[52:55], v[148:151], v[190:193], v[52:55]
	v_mfma_f32_16x16x32_bf16 v[48:51], v[174:177], v[190:193], v[48:51]
	s_barrier
	s_setprio 2
	v_mfma_f32_16x16x32_bf16 v[44:47], v[148:151], v[206:209], v[44:47]
	v_mfma_f32_16x16x32_bf16 v[40:43], v[174:177], v[206:209], v[40:43]
	v_mfma_f32_16x16x32_bf16 v[36:39], v[148:151], v[214:217], v[36:39]
	v_mfma_f32_16x16x32_bf16 v[32:35], v[174:177], v[214:217], v[32:35]
	s_setprio 0
	s_add_i32 s16, s69, s67
	v_lshl_add_u64 v[198:199], v[198:199], 0, s[8:9]
	s_mov_b32 m0, s16
	ds_read_b128 v[178:181], v203 offset:49152
	ds_read_b128 v[182:185], v203 offset:50176
	ds_read_b128 v[186:189], v203 offset:51200
	ds_read_b128 v[190:193], v203 offset:52224
	ds_read_b128 v[194:197], v203 offset:53248
	ds_read_b128 v[206:209], v203 offset:54272
	ds_read_b128 v[210:213], v203 offset:55296
	ds_read_b128 v[214:217], v203 offset:56320
	global_load_lds_dwordx4 v[198:199], off
	s_add_i32 m0, s16, 0x2000
	s_add_u32 s16, s20, 0x160080
	v_lshl_add_u64 v[198:199], v[218:219], 0, s[8:9]
	s_addc_u32 s17, s21, 0
	s_add_i32 s20, s70, s67
	global_load_lds_dwordx4 v[198:199], off
	v_lshl_add_u64 v[198:199], s[16:17], 0, v[154:155]
	s_mov_b32 m0, s20
	s_nop 0
	global_load_lds_dwordx4 v[198:199], off
	v_lshl_add_u64 v[198:199], s[16:17], 0, v[158:159]
	s_add_i32 m0, s20, 0x2000
	s_nop 0
	global_load_lds_dwordx4 v[198:199], off
	v_lshl_add_u64 v[198:199], v[220:221], 0, s[8:9]
	s_mov_b32 m0, s47
	s_nop 0
	global_load_lds_dwordx4 v[198:199], off
	v_lshl_add_u64 v[198:199], v[222:223], 0, s[8:9]
	s_mov_b32 m0, s48
	s_nop 0
	global_load_lds_dwordx4 v[198:199], off
	s_waitcnt vmcnt(8)
	s_waitcnt lgkmcnt(0)
	s_barrier
	s_setprio 1
	s_waitcnt lgkmcnt(0)
	v_mfma_f32_16x16x32_bf16 v[92:95], v[128:131], v[178:181], v[92:95]
	v_mfma_f32_16x16x32_bf16 v[88:91], v[136:139], v[178:181], v[88:91]
	v_mfma_f32_16x16x32_bf16 v[84:87], v[128:131], v[186:189], v[84:87]
	v_mfma_f32_16x16x32_bf16 v[80:83], v[136:139], v[186:189], v[80:83]
	v_mfma_f32_16x16x32_bf16 v[76:79], v[128:131], v[194:197], v[76:79]
	v_mfma_f32_16x16x32_bf16 v[72:75], v[136:139], v[194:197], v[72:75]
	v_mfma_f32_16x16x32_bf16 v[68:71], v[128:131], v[210:213], v[68:71]
	v_mfma_f32_16x16x32_bf16 v[64:67], v[136:139], v[210:213], v[64:67]
	v_mfma_f32_16x16x32_bf16 v[92:95], v[132:135], v[182:185], v[92:95]
	v_mfma_f32_16x16x32_bf16 v[88:91], v[140:143], v[182:185], v[88:91]
	v_mfma_f32_16x16x32_bf16 v[84:87], v[132:135], v[190:193], v[84:87]
	v_mfma_f32_16x16x32_bf16 v[80:83], v[140:143], v[190:193], v[80:83]
	v_mfma_f32_16x16x32_bf16 v[76:79], v[132:135], v[206:209], v[76:79]
	v_mfma_f32_16x16x32_bf16 v[72:75], v[140:143], v[206:209], v[72:75]
	v_mfma_f32_16x16x32_bf16 v[68:71], v[132:135], v[214:217], v[68:71]
	v_mfma_f32_16x16x32_bf16 v[64:67], v[140:143], v[214:217], v[64:67]
	s_setprio 0
	s_setprio 1
	v_mfma_f32_16x16x32_bf16 v[28:31], v[144:147], v[178:181], v[28:31]
	v_mfma_f32_16x16x32_bf16 v[24:27], v[170:173], v[178:181], v[24:27]
	v_mfma_f32_16x16x32_bf16 v[20:23], v[144:147], v[186:189], v[20:23]
	v_mfma_f32_16x16x32_bf16 v[16:19], v[170:173], v[186:189], v[16:19]
	v_mfma_f32_16x16x32_bf16 v[12:15], v[144:147], v[194:197], v[12:15]
	v_mfma_f32_16x16x32_bf16 v[8:11], v[170:173], v[194:197], v[8:11]
	v_mfma_f32_16x16x32_bf16 v[4:7], v[144:147], v[210:213], v[4:7]
	v_mfma_f32_16x16x32_bf16 v[0:3], v[170:173], v[210:213], v[0:3]
	v_mfma_f32_16x16x32_bf16 v[28:31], v[148:151], v[182:185], v[28:31]
	v_mfma_f32_16x16x32_bf16 v[24:27], v[174:177], v[182:185], v[24:27]
	v_mfma_f32_16x16x32_bf16 v[20:23], v[148:151], v[190:193], v[20:23]
	v_mfma_f32_16x16x32_bf16 v[16:19], v[174:177], v[190:193], v[16:19]
	s_barrier
	s_setprio 2
	v_mfma_f32_16x16x32_bf16 v[12:15], v[148:151], v[206:209], v[12:15]
	v_mfma_f32_16x16x32_bf16 v[8:11], v[174:177], v[206:209], v[8:11]
	v_mfma_f32_16x16x32_bf16 v[4:7], v[148:151], v[214:217], v[4:7]
	v_mfma_f32_16x16x32_bf16 v[0:3], v[174:177], v[214:217], v[0:3]
	s_setprio 0
	s_add_i32 s68, s68, 2
	s_add_u32 s24, s24, 0x100
	s_addc_u32 s25, s25, 0
	s_cmpk_gt_u32 s68, 0x55
	s_mov_b64 s[16:17], s[18:19]
	s_cbranch_scc0 .LBB0_3501
	s_and_b64 vcc, exec, s[10:11]
	s_cbranch_vccz .LBB0_3504
	s_barrier
